# v46 + mainloop loop-edge bookkeeping (next-tile pointer selects, K-step increments) moved behind the fragment reads / staging loads in all four GEMM loops
# speedup vs baseline: 1.0077x; 1.0077x over previous
; #define PG8_LAS __attribute__((address_space(3)))
; #define PG8_STAGE(bufoff, gbase, voff) do { _Pragma("unroll") for (int _i = 0; _i < 2; ++_i) \
;         __builtin_amdgcn_global_load_lds((const unsigned*)((const char*)(gbase) + (voff)[_i]), (PG8_LAS unsigned*)(lds + (bufoff) + ldsw + _i * (8 * USTR)), 16, 0, 0); } while (0)
; #define PG8_LDA(dst, b, h) do { _Pragma("unroll") for (int m = 0; m < 4; ++m) _Pragma("unroll") for (int k = 0; k < 2; ++k) dst[m][k] = *(const PG8_LAS bf16x8*)(lds + PG8_SA(b, h) + aoff + m * (2 * USTR) + k * 64); } while (0)
; #define PG8_LDB(dst, b, h) do { _Pragma("unroll") for (int n = 0; n < 2; ++n) _Pragma("unroll") for (int k = 0; k < 2; ++k) dst[n][k] = *(const PG8_LAS bf16x8*)(lds + PG8_SB(b, h) + boff + n * (2 * USTR) + k * 64); } while (0)
; template <class Epi, class Sched, bool ALIGN_EPI, bool SP2>
; __device__ __forceinline__ void gemm_phase(PG8_LAS unsigned char* lds, const Gemm g, const Sched& S, const Epi& E, int wid) {
;     ...
;             const bool last = (t == nt - 2);
;             const char* a1 = cA + (size_t)(t + 1) * kstep;
;             const char* a2 = last ? nA : cA + (size_t)(t + 2) * kstep; const char* b2 = last ? nB : cB + (size_t)(t + 2) * kstep;
;             const char* a3 = a2 + kstep; const char* b3 = b2 + kstep;
;             if constexpr (Epi::PRE == 1) { if (last) {
;                 const char* rsrc; const char* ssrc; E.pre(cur, rsrc, ssrc);
; #pragma unroll
;                 for (int _i = 0; _i < 2; ++_i) __builtin_amdgcn_global_load_lds((const unsigned*)(rsrc + (wid + 8 * _i) * 1024 + lane * 16), (PG8_LAS unsigned*)(lds + LDS_XOFF + (wid + 8 * _i) * 1024), 16, 0, 0);
;                 if (wid == 0) __builtin_amdgcn_global_load_lds((const unsigned*)(ssrc + lane * 16), (PG8_LAS unsigned*)(lds + LDS_XOFF + 16384), 16, 0, 0);
;             } }
;             if constexpr (SP2) {
;             PG8_LDB(B0, 0, 0); PG8_LDB(B1, 0, 1); PG8_SCHED; PG8_LDA(At, 0, 0); PG8_STAGE(PG8_SA(1, 1), a1 + hstepA, voffA);
;             PG8_WAIT_V(8); PG8_WAIT_L(0); PG8_BAR; PG8_MMA(0, 0, At, B0); PG8_MMA(0, 1, At, B1); PG8_BAR; PG8_SCHED;
;             PG8_LDA(At, 0, 1); PG8_STAGE(PG8_SB(0, 0), b2, voffB); PG8_STAGE(PG8_SB(0, 1), b2 + hstepB, voffB); PG8_STAGE(PG8_SA(0, 0), a2, voffA);
;             PG8_WAIT_V(8); PG8_WAIT_L(0); PG8_BAR; PG8_MMA(1, 0, At, B0); PG8_MMA(1, 1, At, B1); PG8_BAR; PG8_SCHED;
.Lhb_mixout:
	s_add_i32 s95, 0, 0x11000
	s_add_i32 s44, 0, 0x15400
	v_add_u32_e32 v60, s95, v216
	v_add_u32_e32 v156, s44, v216
	ds_read_b128 v[48:51], v60
	ds_read_b128 v[52:55], v60 offset:64
	ds_read_b128 v[56:59], v60 offset:2176
	ds_read_b128 v[60:63], v60 offset:2240
	ds_read_b128 v[144:147], v156
	ds_read_b128 v[148:151], v156 offset:64
	ds_read_b128 v[152:155], v156 offset:2176
	ds_read_b128 v[156:159], v156 offset:2240
	v_lshl_add_u64 v[198:199], s[38:39], 0, v[168:169]
	s_add_i32 m0, s0, 0xcc00
	ds_read_b128 v[172:175], v217
	ds_read_b128 v[176:179], v217 offset:64
	ds_read_b128 v[180:183], v217 offset:2176
	ds_read_b128 v[184:187], v217 offset:2240
	ds_read_b128 v[188:191], v217 offset:4352
	ds_read_b128 v[208:211], v217 offset:4416
	ds_read_b128 v[212:215], v217 offset:6528
	ds_read_b128 v[218:221], v217 offset:6592
	global_load_lds_dwordx4 v[198:199], off
	v_lshl_add_u64 v[198:199], s[38:39], 0, v[170:171]
	s_add_i32 m0, s0, 0xee00
	s_nop 0
	global_load_lds_dwordx4 v[198:199], off
	s_add_u32 s40, s38, 0xfff80080
	s_addc_u32 s41, s39, -1
	s_cmp_eq_u32 s89, 12
	s_cselect_b32 s75, s26, s41
	s_cselect_b32 s74, s27, s40
	s_cselect_b32 s41, s23, s79
	s_cselect_b32 s40, s69, s78
	s_waitcnt vmcnt(8)
	s_waitcnt lgkmcnt(0)
	s_barrier
	s_setprio 1
	s_waitcnt lgkmcnt(0)
	v_mfma_f32_16x16x32_bf16 v[140:143], v[48:51], v[172:175], 0
	v_mfma_f32_16x16x32_bf16 v[136:139], v[56:59], v[172:175], 0
	v_mfma_f32_16x16x32_bf16 v[124:127], v[48:51], v[180:183], 0
	v_mfma_f32_16x16x32_bf16 v[120:123], v[56:59], v[180:183], 0
	v_mfma_f32_16x16x32_bf16 v[108:111], v[48:51], v[188:191], 0
	v_mfma_f32_16x16x32_bf16 v[104:107], v[56:59], v[188:191], 0
	v_mfma_f32_16x16x32_bf16 v[92:95], v[48:51], v[212:215], 0
	v_mfma_f32_16x16x32_bf16 v[88:91], v[56:59], v[212:215], 0
	v_mfma_f32_16x16x32_bf16 v[140:143], v[52:55], v[176:179], v[140:143]
	v_mfma_f32_16x16x32_bf16 v[136:139], v[60:63], v[176:179], v[136:139]
	v_mfma_f32_16x16x32_bf16 v[124:127], v[52:55], v[184:187], v[124:127]
	v_mfma_f32_16x16x32_bf16 v[120:123], v[60:63], v[184:187], v[120:123]
	v_mfma_f32_16x16x32_bf16 v[108:111], v[52:55], v[208:211], v[108:111]
	v_mfma_f32_16x16x32_bf16 v[104:107], v[60:63], v[208:211], v[104:107]
	v_mfma_f32_16x16x32_bf16 v[92:95], v[52:55], v[218:221], v[92:95]
	v_mfma_f32_16x16x32_bf16 v[88:91], v[60:63], v[218:221], v[88:91]
	s_setprio 0
	s_setprio 1
	v_mfma_f32_16x16x32_bf16 v[132:135], v[144:147], v[172:175], 0
	v_mfma_f32_16x16x32_bf16 v[128:131], v[152:155], v[172:175], 0
	v_mfma_f32_16x16x32_bf16 v[116:119], v[144:147], v[180:183], 0
	v_mfma_f32_16x16x32_bf16 v[112:115], v[152:155], v[180:183], 0
	v_mfma_f32_16x16x32_bf16 v[100:103], v[144:147], v[188:191], 0
	v_mfma_f32_16x16x32_bf16 v[96:99], v[152:155], v[188:191], 0
	v_mfma_f32_16x16x32_bf16 v[84:87], v[144:147], v[212:215], 0
	v_mfma_f32_16x16x32_bf16 v[80:83], v[152:155], v[212:215], 0
	v_mfma_f32_16x16x32_bf16 v[132:135], v[148:151], v[176:179], v[132:135]
	v_mfma_f32_16x16x32_bf16 v[128:131], v[156:159], v[176:179], v[128:131]
	v_mfma_f32_16x16x32_bf16 v[116:119], v[148:151], v[184:187], v[116:119]
	v_mfma_f32_16x16x32_bf16 v[112:115], v[156:159], v[184:187], v[112:115]
	v_mfma_f32_16x16x32_bf16 v[100:103], v[148:151], v[208:211], v[100:103]
	v_mfma_f32_16x16x32_bf16 v[96:99], v[156:159], v[208:211], v[96:99]
	v_mfma_f32_16x16x32_bf16 v[84:87], v[148:151], v[218:221], v[84:87]
	v_mfma_f32_16x16x32_bf16 v[80:83], v[156:159], v[218:221], v[80:83]
	s_setprio 0
	s_barrier
	s_add_i32 s45, s95, s33
	v_lshl_add_u64 v[198:199], s[40:41], 0, v[192:193]
	s_mov_b32 m0, s45
	ds_read_b128 v[172:175], v217 offset:17408
	ds_read_b128 v[176:179], v217 offset:17472
	ds_read_b128 v[180:183], v217 offset:19584
	ds_read_b128 v[184:187], v217 offset:19648
	ds_read_b128 v[188:191], v217 offset:21760
	ds_read_b128 v[208:211], v217 offset:21824
	ds_read_b128 v[212:215], v217 offset:23936
	ds_read_b128 v[218:221], v217 offset:24000
	global_load_lds_dwordx4 v[198:199], off
	s_add_i32 m0, s45, 0x2200
	s_add_u32 vcc_lo, s40, 0x40000
	v_lshl_add_u64 v[200:201], s[40:41], 0, v[160:161]
	s_addc_u32 vcc_hi, s41, 0
	s_add_i32 s44, s44, s33
	global_load_lds_dwordx4 v[200:201], off
	v_lshl_add_u64 v[222:223], vcc, 0, v[192:193]
	s_mov_b32 m0, s44
	v_lshl_add_u64 v[224:225], s[74:75], 0, v[162:163]
	global_load_lds_dwordx4 v[222:223], off
	v_lshl_add_u64 v[222:223], vcc, 0, v[160:161]
	s_add_i32 m0, s44, 0x2200
	s_nop 0
	global_load_lds_dwordx4 v[222:223], off
	v_lshl_add_u64 v[222:223], s[74:75], 0, v[164:165]
	s_mov_b32 m0, s0
	s_nop 0
	global_load_lds_dwordx4 v[222:223], off
	s_mov_b32 m0, s5
	s_nop 0
	global_load_lds_dwordx4 v[224:225], off
	s_waitcnt vmcnt(8)
	s_waitcnt lgkmcnt(0)
	s_barrier
; #define PG8_STAGE(bufoff, gbase, voff) do { _Pragma("unroll") for (int _i = 0; _i < 2; ++_i) \
;         __builtin_amdgcn_global_load_lds((const unsigned*)((const char*)(gbase) + (voff)[_i]), (PG8_LAS unsigned*)(lds + (bufoff) + ldsw + _i * (8 * USTR)), 16, 0, 0); } while (0)
; #define PG8_LDA(dst, b, h) do { _Pragma("unroll") for (int m = 0; m < 4; ++m) _Pragma("unroll") for (int k = 0; k < 2; ++k) dst[m][k] = *(const PG8_LAS bf16x8*)(lds + PG8_SA(b, h) + aoff + m * (2 * USTR) + k * 64); } while (0)
; #define PG8_LDB(dst, b, h) do { _Pragma("unroll") for (int n = 0; n < 2; ++n) _Pragma("unroll") for (int k = 0; k < 2; ++k) dst[n][k] = *(const PG8_LAS bf16x8*)(lds + PG8_SB(b, h) + boff + n * (2 * USTR) + k * 64); } while (0)
; #define PG8_MMA(ai, bj, At, Bt) do { __builtin_amdgcn_s_setprio(1); _Pragma("unroll") for (int m = 0; m < 4; ++m) _Pragma("unroll") for (int n = 0; n < 2; ++n) _Pragma("unroll") for (int k = 0; k < 2; ++k) \
;         acc[ai][bj][m][n] = __builtin_amdgcn_mfma_f32_16x16x32_bf16(Bt[n][k], At[m][k], acc[ai][bj][m][n], 0, 0, 0); __builtin_amdgcn_s_setprio(0); } while (0)
; #define PG8_WAIT_V(n) asm volatile("s_waitcnt vmcnt(" #n ")" ::: "memory")
; #define PG8_WAIT_L(n) asm volatile("s_waitcnt lgkmcnt(" #n ")" ::: "memory")
; #define PG8_BAR __builtin_amdgcn_s_barrier()
; #define PG8_SCHED __builtin_amdgcn_sched_barrier(0)
; template <class Epi, class Sched, bool ALIGN_EPI, bool SP2>
; __device__ __forceinline__ void gemm_phase(PG8_LAS unsigned char* lds, const Gemm g, const Sched& S, const Epi& E, int wid) {
;     ...
;             PG8_WAIT_V(8); PG8_WAIT_L(0); PG8_BAR; PG8_MMA(1, 0, At, B0); PG8_MMA(1, 1, At, B1); PG8_BAR; PG8_SCHED;
;             PG8_LDB(B0, 1, 0); PG8_LDB(B1, 1, 1); PG8_SCHED; PG8_LDA(At, 1, 0); PG8_STAGE(PG8_SA(0, 1), a2 + hstepA, voffA);
;             PG8_WAIT_V(8); PG8_WAIT_L(0); PG8_BAR; PG8_MMA(0, 0, At, B0); PG8_MMA(0, 1, At, B1); PG8_BAR; PG8_SCHED;
	s_setprio 1
	s_waitcnt lgkmcnt(0)
	v_mfma_f32_16x16x32_bf16 v[76:79], v[48:51], v[172:175], 0
	v_mfma_f32_16x16x32_bf16 v[72:75], v[56:59], v[172:175], 0
	v_mfma_f32_16x16x32_bf16 v[44:47], v[48:51], v[180:183], 0
	v_mfma_f32_16x16x32_bf16 v[40:43], v[56:59], v[180:183], 0
	v_mfma_f32_16x16x32_bf16 v[24:27], v[48:51], v[188:191], 0
	v_mfma_f32_16x16x32_bf16 v[28:31], v[56:59], v[188:191], 0
	v_mfma_f32_16x16x32_bf16 v[4:7], v[48:51], v[212:215], 0
	v_mfma_f32_16x16x32_bf16 v[12:15], v[56:59], v[212:215], 0
	v_mfma_f32_16x16x32_bf16 v[76:79], v[52:55], v[176:179], v[76:79]
	v_mfma_f32_16x16x32_bf16 v[72:75], v[60:63], v[176:179], v[72:75]
	v_mfma_f32_16x16x32_bf16 v[44:47], v[52:55], v[184:187], v[44:47]
	v_mfma_f32_16x16x32_bf16 v[40:43], v[60:63], v[184:187], v[40:43]
	v_mfma_f32_16x16x32_bf16 v[24:27], v[52:55], v[208:211], v[24:27]
	v_mfma_f32_16x16x32_bf16 v[28:31], v[60:63], v[208:211], v[28:31]
	v_mfma_f32_16x16x32_bf16 v[4:7], v[52:55], v[218:221], v[4:7]
	v_mfma_f32_16x16x32_bf16 v[12:15], v[60:63], v[218:221], v[12:15]
	s_setprio 0
	s_setprio 1
	v_mfma_f32_16x16x32_bf16 v[36:39], v[144:147], v[180:183], 0
	v_mfma_f32_16x16x32_bf16 v[32:35], v[152:155], v[180:183], 0
	v_mfma_f32_16x16x32_bf16 v[20:23], v[144:147], v[188:191], 0
	v_mfma_f32_16x16x32_bf16 v[16:19], v[152:155], v[188:191], 0
	v_mfma_f32_16x16x32_bf16 v[8:11], v[144:147], v[212:215], 0
	v_mfma_f32_16x16x32_bf16 v[0:3], v[152:155], v[212:215], 0
	v_mfma_f32_16x16x32_bf16 v[48:51], v[144:147], v[172:175], 0
	v_mfma_f32_16x16x32_bf16 v[52:55], v[152:155], v[172:175], 0
	v_mfma_f32_16x16x32_bf16 v[36:39], v[148:151], v[184:187], v[36:39]
	v_mfma_f32_16x16x32_bf16 v[32:35], v[156:159], v[184:187], v[32:35]
	v_mfma_f32_16x16x32_bf16 v[20:23], v[148:151], v[208:211], v[20:23]
	v_mfma_f32_16x16x32_bf16 v[16:19], v[156:159], v[208:211], v[16:19]
	v_mfma_f32_16x16x32_bf16 v[8:11], v[148:151], v[218:221], v[8:11]
	v_mfma_f32_16x16x32_bf16 v[0:3], v[156:159], v[218:221], v[0:3]
	v_mfma_f32_16x16x32_bf16 v[48:51], v[148:151], v[176:179], v[48:51]
	v_mfma_f32_16x16x32_bf16 v[52:55], v[156:159], v[176:179], v[52:55]
	s_setprio 0
	s_barrier
	s_add_i32 s44, 0, 0x19800
	s_add_i32 s45, 0, 0x1dc00
	v_add_u32_e32 v68, s44, v216
	v_add_u32_e32 v156, s45, v216
	ds_read_b128 v[56:59], v68
	ds_read_b128 v[60:63], v68 offset:64
	ds_read_b128 v[64:67], v68 offset:2176
	ds_read_b128 v[68:71], v68 offset:2240
	ds_read_b128 v[144:147], v156
	ds_read_b128 v[148:151], v156 offset:64
	ds_read_b128 v[152:155], v156 offset:2176
	ds_read_b128 v[156:159], v156 offset:2240
	s_add_u32 s74, s74, 0x80000
	s_addc_u32 s75, s75, 0
	s_mov_b32 m0, s29
	v_lshl_add_u64 v[226:227], s[74:75], 0, v[164:165]
	ds_read_b128 v[172:175], v217 offset:34816
	ds_read_b128 v[176:179], v217 offset:34880
	ds_read_b128 v[180:183], v217 offset:36992
	ds_read_b128 v[184:187], v217 offset:37056
	ds_read_b128 v[188:191], v217 offset:39168
	ds_read_b128 v[208:211], v217 offset:39232
	ds_read_b128 v[212:215], v217 offset:41344
	ds_read_b128 v[218:221], v217 offset:41408
	global_load_lds_dwordx4 v[226:227], off
	v_lshl_add_u64 v[226:227], s[74:75], 0, v[162:163]
	s_mov_b32 m0, s56
	s_nop 0
	global_load_lds_dwordx4 v[226:227], off
	s_waitcnt vmcnt(8)
	s_waitcnt lgkmcnt(0)
	s_barrier
	s_setprio 1
	s_waitcnt lgkmcnt(0)
	v_mfma_f32_16x16x32_bf16 v[140:143], v[56:59], v[172:175], v[140:143]
	v_mfma_f32_16x16x32_bf16 v[136:139], v[64:67], v[172:175], v[136:139]
	v_mfma_f32_16x16x32_bf16 v[124:127], v[56:59], v[180:183], v[124:127]
	v_mfma_f32_16x16x32_bf16 v[120:123], v[64:67], v[180:183], v[120:123]
	v_mfma_f32_16x16x32_bf16 v[108:111], v[56:59], v[188:191], v[108:111]
	v_mfma_f32_16x16x32_bf16 v[104:107], v[64:67], v[188:191], v[104:107]
	v_mfma_f32_16x16x32_bf16 v[92:95], v[56:59], v[212:215], v[92:95]
	v_mfma_f32_16x16x32_bf16 v[88:91], v[64:67], v[212:215], v[88:91]
	v_mfma_f32_16x16x32_bf16 v[140:143], v[60:63], v[176:179], v[140:143]
	v_mfma_f32_16x16x32_bf16 v[136:139], v[68:71], v[176:179], v[136:139]
	v_mfma_f32_16x16x32_bf16 v[124:127], v[60:63], v[184:187], v[124:127]
	v_mfma_f32_16x16x32_bf16 v[120:123], v[68:71], v[184:187], v[120:123]
	v_mfma_f32_16x16x32_bf16 v[108:111], v[60:63], v[208:211], v[108:111]
	v_mfma_f32_16x16x32_bf16 v[104:107], v[68:71], v[208:211], v[104:107]
	v_mfma_f32_16x16x32_bf16 v[92:95], v[60:63], v[218:221], v[92:95]
	v_mfma_f32_16x16x32_bf16 v[88:91], v[68:71], v[218:221], v[88:91]
	s_setprio 0
	s_setprio 1
	v_mfma_f32_16x16x32_bf16 v[132:135], v[144:147], v[172:175], v[132:135]
	v_mfma_f32_16x16x32_bf16 v[128:131], v[152:155], v[172:175], v[128:131]
	v_mfma_f32_16x16x32_bf16 v[116:119], v[144:147], v[180:183], v[116:119]
	v_mfma_f32_16x16x32_bf16 v[112:115], v[152:155], v[180:183], v[112:115]
	v_mfma_f32_16x16x32_bf16 v[100:103], v[144:147], v[188:191], v[100:103]
	v_mfma_f32_16x16x32_bf16 v[96:99], v[152:155], v[188:191], v[96:99]
	v_mfma_f32_16x16x32_bf16 v[84:87], v[144:147], v[212:215], v[84:87]
	v_mfma_f32_16x16x32_bf16 v[80:83], v[152:155], v[212:215], v[80:83]
	v_mfma_f32_16x16x32_bf16 v[132:135], v[148:151], v[176:179], v[132:135]
	v_mfma_f32_16x16x32_bf16 v[128:131], v[156:159], v[176:179], v[128:131]
	v_mfma_f32_16x16x32_bf16 v[116:119], v[148:151], v[184:187], v[116:119]
	v_mfma_f32_16x16x32_bf16 v[112:115], v[156:159], v[184:187], v[112:115]
	v_mfma_f32_16x16x32_bf16 v[100:103], v[148:151], v[208:211], v[100:103]
	v_mfma_f32_16x16x32_bf16 v[96:99], v[156:159], v[208:211], v[96:99]
	v_mfma_f32_16x16x32_bf16 v[84:87], v[148:151], v[218:221], v[84:87]
	v_mfma_f32_16x16x32_bf16 v[80:83], v[156:159], v[218:221], v[80:83]
	s_setprio 0
	s_barrier
; #define PG8_LAS __attribute__((address_space(3)))
; #define PG8_STAGE(bufoff, gbase, voff) do { _Pragma("unroll") for (int _i = 0; _i < 2; ++_i) \
;         __builtin_amdgcn_global_load_lds((const unsigned*)((const char*)(gbase) + (voff)[_i]), (PG8_LAS unsigned*)(lds + (bufoff) + ldsw + _i * (8 * USTR)), 16, 0, 0); } while (0)
; #define PG8_WAIT_V(n) asm volatile("s_waitcnt vmcnt(" #n ")" ::: "memory")
; #define PG8_WAIT_L(n) asm volatile("s_waitcnt lgkmcnt(" #n ")" ::: "memory")
; template <class Epi, class Sched, bool ALIGN_EPI, bool SP2>
; __device__ __forceinline__ void gemm_phase(PG8_LAS unsigned char* lds, const Gemm g, const Sched& S, const Epi& E, int wid) {
;     ...
;         for (int t = 0; t < nt; t += 2) {
;             const bool last = (t == nt - 2);
;             const char* a1 = cA + (size_t)(t + 1) * kstep;
;             const char* a2 = last ? nA : cA + (size_t)(t + 2) * kstep; const char* b2 = last ? nB : cB + (size_t)(t + 2) * kstep;
;             const char* a3 = a2 + kstep; const char* b3 = b2 + kstep;
;             if constexpr (Epi::PRE == 1) { if (last) {
;                 const char* rsrc; const char* ssrc; E.pre(cur, rsrc, ssrc);
; #pragma unroll
;                 for (int _i = 0; _i < 2; ++_i) __builtin_amdgcn_global_load_lds((const unsigned*)(rsrc + (wid + 8 * _i) * 1024 + lane * 16), (PG8_LAS unsigned*)(lds + LDS_XOFF + (wid + 8 * _i) * 1024), 16, 0, 0);
;                 if (wid == 0) __builtin_amdgcn_global_load_lds((const unsigned*)(ssrc + lane * 16), (PG8_LAS unsigned*)(lds + LDS_XOFF + 16384), 16, 0, 0);
;             } }
;             if constexpr (SP2) {
;             PG8_LDB(B0, 0, 0); PG8_LDB(B1, 0, 1); PG8_SCHED; PG8_LDA(At, 0, 0); PG8_STAGE(PG8_SA(1, 1), a1 + hstepA, voffA);
;             PG8_WAIT_V(8); PG8_WAIT_L(0); PG8_BAR; PG8_MMA(0, 0, At, B0); PG8_MMA(0, 1, At, B1); PG8_BAR; PG8_SCHED;
;             PG8_LDA(At, 0, 1); PG8_STAGE(PG8_SB(0, 0), b2, voffB); PG8_STAGE(PG8_SB(0, 1), b2 + hstepB, voffB); PG8_STAGE(PG8_SA(0, 0), a2, voffA);
;             PG8_WAIT_V(8); PG8_WAIT_L(0); PG8_BAR; PG8_MMA(1, 0, At, B0); PG8_MMA(1, 1, At, B1); PG8_BAR; PG8_SCHED;
;     ...
;             PG8_LDA(At, 1, 1); PG8_STAGE(PG8_SB(1, 0), b3, voffB); PG8_STAGE(PG8_SB(1, 1), b3 + hstepB, voffB); PG8_STAGE(PG8_SA(1, 0), a3, voffA);
;             PG8_WAIT_V(8); PG8_WAIT_L(0); PG8_BAR; PG8_MMA(1, 0, At, B0); PG8_MMA(1, 1, At, B1); PG8_BAR; PG8_SCHED;
	s_add_i32 s44, s44, s33
	v_lshl_add_u64 v[198:199], v[198:199], 0, s[6:7]
	s_mov_b32 m0, s44
	ds_read_b128 v[172:175], v217 offset:52224
	ds_read_b128 v[176:179], v217 offset:52288
	ds_read_b128 v[180:183], v217 offset:54400
	ds_read_b128 v[184:187], v217 offset:54464
	ds_read_b128 v[188:191], v217 offset:56576
	ds_read_b128 v[208:211], v217 offset:56640
	ds_read_b128 v[212:215], v217 offset:58752
	ds_read_b128 v[218:221], v217 offset:58816
	global_load_lds_dwordx4 v[198:199], off
	s_add_i32 m0, s44, 0x2200
	s_add_u32 s40, s40, 0x40080
	v_lshl_add_u64 v[198:199], v[200:201], 0, s[6:7]
	s_addc_u32 s41, s41, 0
	s_add_i32 s44, s45, s33
	global_load_lds_dwordx4 v[198:199], off
	v_lshl_add_u64 v[198:199], s[40:41], 0, v[192:193]
	s_mov_b32 m0, s44
	s_nop 0
	global_load_lds_dwordx4 v[198:199], off
	v_lshl_add_u64 v[198:199], s[40:41], 0, v[160:161]
	s_add_i32 m0, s44, 0x2200
	s_nop 0
	global_load_lds_dwordx4 v[198:199], off
	v_lshl_add_u64 v[198:199], v[222:223], 0, s[6:7]
	s_mov_b32 m0, s57
	s_nop 0
	global_load_lds_dwordx4 v[198:199], off
	v_lshl_add_u64 v[198:199], v[224:225], 0, s[6:7]
	s_mov_b32 m0, s76
	s_nop 0
	global_load_lds_dwordx4 v[198:199], off
	s_add_i32 s89, s89, 2
	s_add_u32 s38, s38, 0x100
	s_addc_u32 s39, s39, 0
	s_add_u32 s78, s78, 0x100
	s_addc_u32 s79, s79, 0
	s_waitcnt vmcnt(8)
	s_waitcnt lgkmcnt(0)
	s_barrier
	s_setprio 1
	s_waitcnt lgkmcnt(0)
	v_mfma_f32_16x16x32_bf16 v[76:79], v[56:59], v[172:175], v[76:79]
	v_mfma_f32_16x16x32_bf16 v[72:75], v[64:67], v[172:175], v[72:75]
	v_mfma_f32_16x16x32_bf16 v[44:47], v[56:59], v[180:183], v[44:47]
	v_mfma_f32_16x16x32_bf16 v[40:43], v[64:67], v[180:183], v[40:43]
	v_mfma_f32_16x16x32_bf16 v[24:27], v[56:59], v[188:191], v[24:27]
	v_mfma_f32_16x16x32_bf16 v[28:31], v[64:67], v[188:191], v[28:31]
	v_mfma_f32_16x16x32_bf16 v[4:7], v[56:59], v[212:215], v[4:7]
	v_mfma_f32_16x16x32_bf16 v[12:15], v[64:67], v[212:215], v[12:15]
	v_mfma_f32_16x16x32_bf16 v[76:79], v[60:63], v[176:179], v[76:79]
	v_mfma_f32_16x16x32_bf16 v[72:75], v[68:71], v[176:179], v[72:75]
	v_mfma_f32_16x16x32_bf16 v[44:47], v[60:63], v[184:187], v[44:47]
	v_mfma_f32_16x16x32_bf16 v[40:43], v[68:71], v[184:187], v[40:43]
	v_mfma_f32_16x16x32_bf16 v[24:27], v[60:63], v[208:211], v[24:27]
	v_mfma_f32_16x16x32_bf16 v[28:31], v[68:71], v[208:211], v[28:31]
	v_mfma_f32_16x16x32_bf16 v[4:7], v[60:63], v[218:221], v[4:7]
	v_mfma_f32_16x16x32_bf16 v[12:15], v[68:71], v[218:221], v[12:15]
	s_setprio 0
	s_setprio 1
	v_mfma_f32_16x16x32_bf16 v[48:51], v[144:147], v[172:175], v[48:51]
	v_mfma_f32_16x16x32_bf16 v[68:71], v[148:151], v[176:179], v[48:51]
	v_mfma_f32_16x16x32_bf16 v[48:51], v[152:155], v[172:175], v[52:55]
	v_mfma_f32_16x16x32_bf16 v[36:39], v[144:147], v[180:183], v[36:39]
	v_mfma_f32_16x16x32_bf16 v[32:35], v[152:155], v[180:183], v[32:35]
	v_mfma_f32_16x16x32_bf16 v[20:23], v[144:147], v[188:191], v[20:23]
	v_mfma_f32_16x16x32_bf16 v[16:19], v[152:155], v[188:191], v[16:19]
	v_mfma_f32_16x16x32_bf16 v[8:11], v[144:147], v[212:215], v[8:11]
	v_mfma_f32_16x16x32_bf16 v[0:3], v[152:155], v[212:215], v[0:3]
	v_mfma_f32_16x16x32_bf16 v[64:67], v[156:159], v[176:179], v[48:51]
	v_mfma_f32_16x16x32_bf16 v[36:39], v[148:151], v[184:187], v[36:39]
	v_mfma_f32_16x16x32_bf16 v[32:35], v[156:159], v[184:187], v[32:35]
	v_mfma_f32_16x16x32_bf16 v[20:23], v[148:151], v[208:211], v[20:23]
	v_mfma_f32_16x16x32_bf16 v[16:19], v[156:159], v[208:211], v[16:19]
	v_mfma_f32_16x16x32_bf16 v[8:11], v[148:151], v[218:221], v[8:11]
	v_mfma_f32_16x16x32_bf16 v[0:3], v[156:159], v[218:221], v[0:3]
	s_setprio 0
	s_barrier
	s_cmp_gt_u32 s89, 13
.LBB0_150:
	s_add_i32 s95, 0, 0x11000
	s_add_i32 s44, 0, 0x15400
	v_add_u32_e32 v60, s95, v216
	v_add_u32_e32 v156, s44, v216
	ds_read_b128 v[48:51], v60
	ds_read_b128 v[52:55], v60 offset:64
	ds_read_b128 v[56:59], v60 offset:2176
	ds_read_b128 v[60:63], v60 offset:2240
	ds_read_b128 v[144:147], v156
	ds_read_b128 v[148:151], v156 offset:64
	ds_read_b128 v[152:155], v156 offset:2176
	ds_read_b128 v[156:159], v156 offset:2240
	v_lshl_add_u64 v[198:199], s[38:39], 0, v[168:169]
	s_add_i32 m0, s0, 0xcc00
	ds_read_b128 v[172:175], v217
	ds_read_b128 v[176:179], v217 offset:64
	ds_read_b128 v[180:183], v217 offset:2176
	ds_read_b128 v[184:187], v217 offset:2240
	ds_read_b128 v[188:191], v217 offset:4352
	ds_read_b128 v[208:211], v217 offset:4416
	ds_read_b128 v[212:215], v217 offset:6528
	ds_read_b128 v[218:221], v217 offset:6592
	global_load_lds_dwordx4 v[198:199], off
	v_lshl_add_u64 v[198:199], s[38:39], 0, v[170:171]
	s_add_i32 m0, s0, 0xee00
	s_nop 0
	global_load_lds_dwordx4 v[198:199], off
	s_add_u32 s40, s38, 0xfff80080
	s_addc_u32 s41, s39, -1
	s_cmp_eq_u32 s89, 12
	s_cselect_b32 s75, s26, s41
	s_cselect_b32 s74, s27, s40
	s_cselect_b32 s41, s23, s79
	s_cselect_b32 s40, s69, s78
	s_waitcnt vmcnt(8)
	s_waitcnt lgkmcnt(0)
	s_barrier
; #define PG8_STAGE(bufoff, gbase, voff) do { _Pragma("unroll") for (int _i = 0; _i < 2; ++_i) \
;         __builtin_amdgcn_global_load_lds((const unsigned*)((const char*)(gbase) + (voff)[_i]), (PG8_LAS unsigned*)(lds + (bufoff) + ldsw + _i * (8 * USTR)), 16, 0, 0); } while (0)
; #define PG8_LDA(dst, b, h) do { _Pragma("unroll") for (int m = 0; m < 4; ++m) _Pragma("unroll") for (int k = 0; k < 2; ++k) dst[m][k] = *(const PG8_LAS bf16x8*)(lds + PG8_SA(b, h) + aoff + m * (2 * USTR) + k * 64); } while (0)
; #define PG8_MMA(ai, bj, At, Bt) do { __builtin_amdgcn_s_setprio(1); _Pragma("unroll") for (int m = 0; m < 4; ++m) _Pragma("unroll") for (int n = 0; n < 2; ++n) _Pragma("unroll") for (int k = 0; k < 2; ++k) \
;         acc[ai][bj][m][n] = __builtin_amdgcn_mfma_f32_16x16x32_bf16(Bt[n][k], At[m][k], acc[ai][bj][m][n], 0, 0, 0); __builtin_amdgcn_s_setprio(0); } while (0)
; #define PG8_WAIT_V(n) asm volatile("s_waitcnt vmcnt(" #n ")" ::: "memory")
; #define PG8_WAIT_L(n) asm volatile("s_waitcnt lgkmcnt(" #n ")" ::: "memory")
; #define PG8_BAR __builtin_amdgcn_s_barrier()
; #define PG8_SCHED __builtin_amdgcn_sched_barrier(0)
; template <class Epi, class Sched, bool ALIGN_EPI, bool SP2>
; __device__ __forceinline__ void gemm_phase(PG8_LAS unsigned char* lds, const Gemm g, const Sched& S, const Epi& E, int wid) {
;     ...
;             PG8_WAIT_V(8); PG8_WAIT_L(0); PG8_BAR; PG8_MMA(0, 0, At, B0); PG8_MMA(0, 1, At, B1); PG8_BAR; PG8_SCHED;
;             PG8_LDA(At, 0, 1); PG8_STAGE(PG8_SB(0, 0), b2, voffB); PG8_STAGE(PG8_SB(0, 1), b2 + hstepB, voffB); PG8_STAGE(PG8_SA(0, 0), a2, voffA);
;             PG8_WAIT_V(8); PG8_WAIT_L(0); PG8_BAR; PG8_MMA(1, 0, At, B0); PG8_MMA(1, 1, At, B1); PG8_BAR; PG8_SCHED;
	s_setprio 1
	s_waitcnt lgkmcnt(0)
	v_mfma_f32_16x16x32_bf16 v[140:143], v[48:51], v[172:175], v[140:143]
	v_mfma_f32_16x16x32_bf16 v[136:139], v[56:59], v[172:175], v[136:139]
	v_mfma_f32_16x16x32_bf16 v[124:127], v[48:51], v[180:183], v[124:127]
	v_mfma_f32_16x16x32_bf16 v[120:123], v[56:59], v[180:183], v[120:123]
	v_mfma_f32_16x16x32_bf16 v[108:111], v[48:51], v[188:191], v[108:111]
	v_mfma_f32_16x16x32_bf16 v[104:107], v[56:59], v[188:191], v[104:107]
	v_mfma_f32_16x16x32_bf16 v[92:95], v[48:51], v[212:215], v[92:95]
	v_mfma_f32_16x16x32_bf16 v[88:91], v[56:59], v[212:215], v[88:91]
	v_mfma_f32_16x16x32_bf16 v[140:143], v[52:55], v[176:179], v[140:143]
	v_mfma_f32_16x16x32_bf16 v[136:139], v[60:63], v[176:179], v[136:139]
	v_mfma_f32_16x16x32_bf16 v[124:127], v[52:55], v[184:187], v[124:127]
	v_mfma_f32_16x16x32_bf16 v[120:123], v[60:63], v[184:187], v[120:123]
	v_mfma_f32_16x16x32_bf16 v[108:111], v[52:55], v[208:211], v[108:111]
	v_mfma_f32_16x16x32_bf16 v[104:107], v[60:63], v[208:211], v[104:107]
	v_mfma_f32_16x16x32_bf16 v[92:95], v[52:55], v[218:221], v[92:95]
	v_mfma_f32_16x16x32_bf16 v[88:91], v[60:63], v[218:221], v[88:91]
	s_setprio 0
	s_setprio 1
	v_mfma_f32_16x16x32_bf16 v[132:135], v[144:147], v[172:175], v[132:135]
	v_mfma_f32_16x16x32_bf16 v[128:131], v[152:155], v[172:175], v[128:131]
	v_mfma_f32_16x16x32_bf16 v[116:119], v[144:147], v[180:183], v[116:119]
	v_mfma_f32_16x16x32_bf16 v[112:115], v[152:155], v[180:183], v[112:115]
	v_mfma_f32_16x16x32_bf16 v[100:103], v[144:147], v[188:191], v[100:103]
	v_mfma_f32_16x16x32_bf16 v[96:99], v[152:155], v[188:191], v[96:99]
	v_mfma_f32_16x16x32_bf16 v[84:87], v[144:147], v[212:215], v[84:87]
	v_mfma_f32_16x16x32_bf16 v[80:83], v[152:155], v[212:215], v[80:83]
	v_mfma_f32_16x16x32_bf16 v[132:135], v[148:151], v[176:179], v[132:135]
	v_mfma_f32_16x16x32_bf16 v[128:131], v[156:159], v[176:179], v[128:131]
	v_mfma_f32_16x16x32_bf16 v[116:119], v[148:151], v[184:187], v[116:119]
	v_mfma_f32_16x16x32_bf16 v[112:115], v[156:159], v[184:187], v[112:115]
	v_mfma_f32_16x16x32_bf16 v[100:103], v[148:151], v[208:211], v[100:103]
	v_mfma_f32_16x16x32_bf16 v[96:99], v[156:159], v[208:211], v[96:99]
	v_mfma_f32_16x16x32_bf16 v[84:87], v[148:151], v[218:221], v[84:87]
	v_mfma_f32_16x16x32_bf16 v[80:83], v[156:159], v[218:221], v[80:83]
	s_setprio 0
	s_barrier
	s_add_i32 s45, s95, s33
	v_lshl_add_u64 v[198:199], s[40:41], 0, v[192:193]
	s_mov_b32 m0, s45
	ds_read_b128 v[172:175], v217 offset:17408
	ds_read_b128 v[176:179], v217 offset:17472
	ds_read_b128 v[180:183], v217 offset:19584
	ds_read_b128 v[184:187], v217 offset:19648
	ds_read_b128 v[188:191], v217 offset:21760
	ds_read_b128 v[208:211], v217 offset:21824
	ds_read_b128 v[212:215], v217 offset:23936
	ds_read_b128 v[218:221], v217 offset:24000
	global_load_lds_dwordx4 v[198:199], off
	s_add_i32 m0, s45, 0x2200
	s_add_u32 vcc_lo, s40, 0x40000
	v_lshl_add_u64 v[200:201], s[40:41], 0, v[160:161]
	s_addc_u32 vcc_hi, s41, 0
	s_add_i32 s44, s44, s33
	global_load_lds_dwordx4 v[200:201], off
	v_lshl_add_u64 v[222:223], vcc, 0, v[192:193]
	s_mov_b32 m0, s44
	v_lshl_add_u64 v[224:225], s[74:75], 0, v[162:163]
	global_load_lds_dwordx4 v[222:223], off
	v_lshl_add_u64 v[222:223], vcc, 0, v[160:161]
	s_add_i32 m0, s44, 0x2200
	s_nop 0
	global_load_lds_dwordx4 v[222:223], off
	v_lshl_add_u64 v[222:223], s[74:75], 0, v[164:165]
	s_mov_b32 m0, s0
	s_nop 0
	global_load_lds_dwordx4 v[222:223], off
	s_mov_b32 m0, s5
	s_nop 0
	global_load_lds_dwordx4 v[224:225], off
	s_waitcnt vmcnt(8)
	s_waitcnt lgkmcnt(0)
	s_barrier
	s_setprio 1
	s_waitcnt lgkmcnt(0)
	v_mfma_f32_16x16x32_bf16 v[76:79], v[48:51], v[172:175], v[76:79]
	v_mfma_f32_16x16x32_bf16 v[72:75], v[56:59], v[172:175], v[72:75]
	v_mfma_f32_16x16x32_bf16 v[44:47], v[48:51], v[180:183], v[44:47]
	v_mfma_f32_16x16x32_bf16 v[40:43], v[56:59], v[180:183], v[40:43]
	v_mfma_f32_16x16x32_bf16 v[24:27], v[48:51], v[188:191], v[24:27]
	v_mfma_f32_16x16x32_bf16 v[28:31], v[56:59], v[188:191], v[28:31]
	v_mfma_f32_16x16x32_bf16 v[4:7], v[48:51], v[212:215], v[4:7]
	v_mfma_f32_16x16x32_bf16 v[12:15], v[56:59], v[212:215], v[12:15]
	v_mfma_f32_16x16x32_bf16 v[76:79], v[52:55], v[176:179], v[76:79]
	v_mfma_f32_16x16x32_bf16 v[72:75], v[60:63], v[176:179], v[72:75]
	v_mfma_f32_16x16x32_bf16 v[44:47], v[52:55], v[184:187], v[44:47]
	v_mfma_f32_16x16x32_bf16 v[40:43], v[60:63], v[184:187], v[40:43]
	v_mfma_f32_16x16x32_bf16 v[24:27], v[52:55], v[208:211], v[24:27]
	v_mfma_f32_16x16x32_bf16 v[28:31], v[60:63], v[208:211], v[28:31]
	v_mfma_f32_16x16x32_bf16 v[4:7], v[52:55], v[218:221], v[4:7]
	v_mfma_f32_16x16x32_bf16 v[12:15], v[60:63], v[218:221], v[12:15]
	s_setprio 0
	s_setprio 1
	v_mfma_f32_16x16x32_bf16 v[36:39], v[144:147], v[180:183], v[36:39]
	v_mfma_f32_16x16x32_bf16 v[32:35], v[152:155], v[180:183], v[32:35]
	v_mfma_f32_16x16x32_bf16 v[20:23], v[144:147], v[188:191], v[20:23]
	v_mfma_f32_16x16x32_bf16 v[16:19], v[152:155], v[188:191], v[16:19]
	v_mfma_f32_16x16x32_bf16 v[8:11], v[144:147], v[212:215], v[8:11]
	v_mfma_f32_16x16x32_bf16 v[0:3], v[152:155], v[212:215], v[0:3]
	v_mfma_f32_16x16x32_bf16 v[48:51], v[144:147], v[172:175], v[68:71]
	v_mfma_f32_16x16x32_bf16 v[52:55], v[152:155], v[172:175], v[64:67]
	v_mfma_f32_16x16x32_bf16 v[36:39], v[148:151], v[184:187], v[36:39]
	v_mfma_f32_16x16x32_bf16 v[32:35], v[156:159], v[184:187], v[32:35]
	v_mfma_f32_16x16x32_bf16 v[20:23], v[148:151], v[208:211], v[20:23]
	v_mfma_f32_16x16x32_bf16 v[16:19], v[156:159], v[208:211], v[16:19]
	v_mfma_f32_16x16x32_bf16 v[8:11], v[148:151], v[218:221], v[8:11]
	v_mfma_f32_16x16x32_bf16 v[0:3], v[156:159], v[218:221], v[0:3]
	v_mfma_f32_16x16x32_bf16 v[48:51], v[148:151], v[176:179], v[48:51]
	v_mfma_f32_16x16x32_bf16 v[52:55], v[156:159], v[176:179], v[52:55]
	s_setprio 0
	s_barrier
; #define PG8_STAGE(bufoff, gbase, voff) do { _Pragma("unroll") for (int _i = 0; _i < 2; ++_i) \
;         __builtin_amdgcn_global_load_lds((const unsigned*)((const char*)(gbase) + (voff)[_i]), (PG8_LAS unsigned*)(lds + (bufoff) + ldsw + _i * (8 * USTR)), 16, 0, 0); } while (0)
; #define PG8_LDA(dst, b, h) do { _Pragma("unroll") for (int m = 0; m < 4; ++m) _Pragma("unroll") for (int k = 0; k < 2; ++k) dst[m][k] = *(const PG8_LAS bf16x8*)(lds + PG8_SA(b, h) + aoff + m * (2 * USTR) + k * 64); } while (0)
; #define PG8_LDB(dst, b, h) do { _Pragma("unroll") for (int n = 0; n < 2; ++n) _Pragma("unroll") for (int k = 0; k < 2; ++k) dst[n][k] = *(const PG8_LAS bf16x8*)(lds + PG8_SB(b, h) + boff + n * (2 * USTR) + k * 64); } while (0)
; #define PG8_MMA(ai, bj, At, Bt) do { __builtin_amdgcn_s_setprio(1); _Pragma("unroll") for (int m = 0; m < 4; ++m) _Pragma("unroll") for (int n = 0; n < 2; ++n) _Pragma("unroll") for (int k = 0; k < 2; ++k) \
;         acc[ai][bj][m][n] = __builtin_amdgcn_mfma_f32_16x16x32_bf16(Bt[n][k], At[m][k], acc[ai][bj][m][n], 0, 0, 0); __builtin_amdgcn_s_setprio(0); } while (0)
; #define PG8_WAIT_V(n) asm volatile("s_waitcnt vmcnt(" #n ")" ::: "memory")
; #define PG8_WAIT_L(n) asm volatile("s_waitcnt lgkmcnt(" #n ")" ::: "memory")
; #define PG8_BAR __builtin_amdgcn_s_barrier()
; #define PG8_SCHED __builtin_amdgcn_sched_barrier(0)
; template <class Epi, class Sched, bool ALIGN_EPI, bool SP2>
; __device__ __forceinline__ void gemm_phase(PG8_LAS unsigned char* lds, const Gemm g, const Sched& S, const Epi& E, int wid) {
;     ...
;             PG8_LDB(B0, 1, 0); PG8_LDB(B1, 1, 1); PG8_SCHED; PG8_LDA(At, 1, 0); PG8_STAGE(PG8_SA(0, 1), a2 + hstepA, voffA);
;             PG8_WAIT_V(8); PG8_WAIT_L(0); PG8_BAR; PG8_MMA(0, 0, At, B0); PG8_MMA(0, 1, At, B1); PG8_BAR; PG8_SCHED;
	s_add_i32 s44, 0, 0x19800
	s_add_i32 s45, 0, 0x1dc00
	v_add_u32_e32 v68, s44, v216
	v_add_u32_e32 v156, s45, v216
	ds_read_b128 v[56:59], v68
	ds_read_b128 v[60:63], v68 offset:64
	ds_read_b128 v[64:67], v68 offset:2176
	ds_read_b128 v[68:71], v68 offset:2240
	ds_read_b128 v[144:147], v156
	ds_read_b128 v[148:151], v156 offset:64
	ds_read_b128 v[152:155], v156 offset:2176
	ds_read_b128 v[156:159], v156 offset:2240
	s_add_u32 s74, s74, 0x80000
	s_addc_u32 s75, s75, 0
	s_mov_b32 m0, s29
	v_lshl_add_u64 v[226:227], s[74:75], 0, v[164:165]
	ds_read_b128 v[172:175], v217 offset:34816
	ds_read_b128 v[176:179], v217 offset:34880
	ds_read_b128 v[180:183], v217 offset:36992
	ds_read_b128 v[184:187], v217 offset:37056
	ds_read_b128 v[188:191], v217 offset:39168
	ds_read_b128 v[208:211], v217 offset:39232
	ds_read_b128 v[212:215], v217 offset:41344
	ds_read_b128 v[218:221], v217 offset:41408
	global_load_lds_dwordx4 v[226:227], off
	v_lshl_add_u64 v[226:227], s[74:75], 0, v[162:163]
	s_mov_b32 m0, s56
	s_nop 0
	global_load_lds_dwordx4 v[226:227], off
	s_waitcnt vmcnt(8)
	s_waitcnt lgkmcnt(0)
	s_barrier
	s_setprio 1
	s_waitcnt lgkmcnt(0)
	v_mfma_f32_16x16x32_bf16 v[140:143], v[56:59], v[172:175], v[140:143]
	v_mfma_f32_16x16x32_bf16 v[136:139], v[64:67], v[172:175], v[136:139]
	v_mfma_f32_16x16x32_bf16 v[124:127], v[56:59], v[180:183], v[124:127]
	v_mfma_f32_16x16x32_bf16 v[120:123], v[64:67], v[180:183], v[120:123]
	v_mfma_f32_16x16x32_bf16 v[108:111], v[56:59], v[188:191], v[108:111]
	v_mfma_f32_16x16x32_bf16 v[104:107], v[64:67], v[188:191], v[104:107]
	v_mfma_f32_16x16x32_bf16 v[92:95], v[56:59], v[212:215], v[92:95]
	v_mfma_f32_16x16x32_bf16 v[88:91], v[64:67], v[212:215], v[88:91]
	v_mfma_f32_16x16x32_bf16 v[140:143], v[60:63], v[176:179], v[140:143]
	v_mfma_f32_16x16x32_bf16 v[136:139], v[68:71], v[176:179], v[136:139]
	v_mfma_f32_16x16x32_bf16 v[124:127], v[60:63], v[184:187], v[124:127]
	v_mfma_f32_16x16x32_bf16 v[120:123], v[68:71], v[184:187], v[120:123]
	v_mfma_f32_16x16x32_bf16 v[108:111], v[60:63], v[208:211], v[108:111]
	v_mfma_f32_16x16x32_bf16 v[104:107], v[68:71], v[208:211], v[104:107]
	v_mfma_f32_16x16x32_bf16 v[92:95], v[60:63], v[218:221], v[92:95]
	v_mfma_f32_16x16x32_bf16 v[88:91], v[68:71], v[218:221], v[88:91]
	s_setprio 0
	s_setprio 1
	v_mfma_f32_16x16x32_bf16 v[132:135], v[144:147], v[172:175], v[132:135]
	v_mfma_f32_16x16x32_bf16 v[128:131], v[152:155], v[172:175], v[128:131]
	v_mfma_f32_16x16x32_bf16 v[116:119], v[144:147], v[180:183], v[116:119]
	v_mfma_f32_16x16x32_bf16 v[112:115], v[152:155], v[180:183], v[112:115]
	v_mfma_f32_16x16x32_bf16 v[100:103], v[144:147], v[188:191], v[100:103]
	v_mfma_f32_16x16x32_bf16 v[96:99], v[152:155], v[188:191], v[96:99]
	v_mfma_f32_16x16x32_bf16 v[84:87], v[144:147], v[212:215], v[84:87]
	v_mfma_f32_16x16x32_bf16 v[80:83], v[152:155], v[212:215], v[80:83]
	v_mfma_f32_16x16x32_bf16 v[132:135], v[148:151], v[176:179], v[132:135]
	v_mfma_f32_16x16x32_bf16 v[128:131], v[156:159], v[176:179], v[128:131]
	v_mfma_f32_16x16x32_bf16 v[116:119], v[148:151], v[184:187], v[116:119]
	v_mfma_f32_16x16x32_bf16 v[112:115], v[156:159], v[184:187], v[112:115]
	v_mfma_f32_16x16x32_bf16 v[100:103], v[148:151], v[208:211], v[100:103]
	v_mfma_f32_16x16x32_bf16 v[96:99], v[156:159], v[208:211], v[96:99]
	v_mfma_f32_16x16x32_bf16 v[84:87], v[148:151], v[218:221], v[84:87]
	v_mfma_f32_16x16x32_bf16 v[80:83], v[156:159], v[218:221], v[80:83]
	s_setprio 0
	s_barrier
; #define PG8_STAGE(bufoff, gbase, voff) do { _Pragma("unroll") for (int _i = 0; _i < 2; ++_i) \
;         __builtin_amdgcn_global_load_lds((const unsigned*)((const char*)(gbase) + (voff)[_i]), (PG8_LAS unsigned*)(lds + (bufoff) + ldsw + _i * (8 * USTR)), 16, 0, 0); } while (0)
; #define PG8_LDA(dst, b, h) do { _Pragma("unroll") for (int m = 0; m < 4; ++m) _Pragma("unroll") for (int k = 0; k < 2; ++k) dst[m][k] = *(const PG8_LAS bf16x8*)(lds + PG8_SA(b, h) + aoff + m * (2 * USTR) + k * 64); } while (0)
; #define PG8_MMA(ai, bj, At, Bt) do { __builtin_amdgcn_s_setprio(1); _Pragma("unroll") for (int m = 0; m < 4; ++m) _Pragma("unroll") for (int n = 0; n < 2; ++n) _Pragma("unroll") for (int k = 0; k < 2; ++k) \
;         acc[ai][bj][m][n] = __builtin_amdgcn_mfma_f32_16x16x32_bf16(Bt[n][k], At[m][k], acc[ai][bj][m][n], 0, 0, 0); __builtin_amdgcn_s_setprio(0); } while (0)
; #define PG8_WAIT_V(n) asm volatile("s_waitcnt vmcnt(" #n ")" ::: "memory")
; #define PG8_WAIT_L(n) asm volatile("s_waitcnt lgkmcnt(" #n ")" ::: "memory")
; #define PG8_BAR __builtin_amdgcn_s_barrier()
; #define PG8_SCHED __builtin_amdgcn_sched_barrier(0)
; template <class Epi, class Sched, bool ALIGN_EPI, bool SP2>
; __device__ __forceinline__ void gemm_phase(PG8_LAS unsigned char* lds, const Gemm g, const Sched& S, const Epi& E, int wid) {
;     ...
;         for (int t = 0; t < nt; t += 2) {
;     ...
;             PG8_LDA(At, 1, 1); PG8_STAGE(PG8_SB(1, 0), b3, voffB); PG8_STAGE(PG8_SB(1, 1), b3 + hstepB, voffB); PG8_STAGE(PG8_SA(1, 0), a3, voffA);
;             PG8_WAIT_V(8); PG8_WAIT_L(0); PG8_BAR; PG8_MMA(1, 0, At, B0); PG8_MMA(1, 1, At, B1); PG8_BAR; PG8_SCHED;
;     ...
;         if constexpr (ALIGN_EPI) { if (wr == 0) PG8_BAR; }
	s_add_i32 s44, s44, s33
	v_lshl_add_u64 v[198:199], v[198:199], 0, s[6:7]
	s_mov_b32 m0, s44
	ds_read_b128 v[172:175], v217 offset:52224
	ds_read_b128 v[176:179], v217 offset:52288
	ds_read_b128 v[180:183], v217 offset:54400
	ds_read_b128 v[184:187], v217 offset:54464
	ds_read_b128 v[188:191], v217 offset:56576
	ds_read_b128 v[208:211], v217 offset:56640
	ds_read_b128 v[212:215], v217 offset:58752
	ds_read_b128 v[218:221], v217 offset:58816
	global_load_lds_dwordx4 v[198:199], off
	s_add_i32 m0, s44, 0x2200
	s_add_u32 s40, s40, 0x40080
	v_lshl_add_u64 v[198:199], v[200:201], 0, s[6:7]
	s_addc_u32 s41, s41, 0
	s_add_i32 s44, s45, s33
	global_load_lds_dwordx4 v[198:199], off
	v_lshl_add_u64 v[198:199], s[40:41], 0, v[192:193]
	s_mov_b32 m0, s44
	s_nop 0
	global_load_lds_dwordx4 v[198:199], off
	v_lshl_add_u64 v[198:199], s[40:41], 0, v[160:161]
	s_add_i32 m0, s44, 0x2200
	s_nop 0
	global_load_lds_dwordx4 v[198:199], off
	v_lshl_add_u64 v[198:199], v[222:223], 0, s[6:7]
	s_mov_b32 m0, s57
	s_nop 0
	global_load_lds_dwordx4 v[198:199], off
	v_lshl_add_u64 v[198:199], v[224:225], 0, s[6:7]
	s_mov_b32 m0, s76
	s_nop 0
	global_load_lds_dwordx4 v[198:199], off
	s_add_i32 s89, s89, 2
	s_add_u32 s38, s38, 0x100
	s_addc_u32 s39, s39, 0
	s_add_u32 s78, s78, 0x100
	s_addc_u32 s79, s79, 0
	s_waitcnt vmcnt(8)
	s_waitcnt lgkmcnt(0)
	s_barrier
	s_setprio 1
	s_waitcnt lgkmcnt(0)
	v_mfma_f32_16x16x32_bf16 v[76:79], v[56:59], v[172:175], v[76:79]
	v_mfma_f32_16x16x32_bf16 v[72:75], v[64:67], v[172:175], v[72:75]
	v_mfma_f32_16x16x32_bf16 v[44:47], v[56:59], v[180:183], v[44:47]
	v_mfma_f32_16x16x32_bf16 v[40:43], v[64:67], v[180:183], v[40:43]
	v_mfma_f32_16x16x32_bf16 v[24:27], v[56:59], v[188:191], v[24:27]
	v_mfma_f32_16x16x32_bf16 v[28:31], v[64:67], v[188:191], v[28:31]
	v_mfma_f32_16x16x32_bf16 v[4:7], v[56:59], v[212:215], v[4:7]
	v_mfma_f32_16x16x32_bf16 v[12:15], v[64:67], v[212:215], v[12:15]
	v_mfma_f32_16x16x32_bf16 v[76:79], v[60:63], v[176:179], v[76:79]
	v_mfma_f32_16x16x32_bf16 v[72:75], v[68:71], v[176:179], v[72:75]
	v_mfma_f32_16x16x32_bf16 v[44:47], v[60:63], v[184:187], v[44:47]
	v_mfma_f32_16x16x32_bf16 v[40:43], v[68:71], v[184:187], v[40:43]
	v_mfma_f32_16x16x32_bf16 v[24:27], v[60:63], v[208:211], v[24:27]
	v_mfma_f32_16x16x32_bf16 v[28:31], v[68:71], v[208:211], v[28:31]
	v_mfma_f32_16x16x32_bf16 v[4:7], v[60:63], v[218:221], v[4:7]
	v_mfma_f32_16x16x32_bf16 v[12:15], v[68:71], v[218:221], v[12:15]
	s_setprio 0
	s_setprio 1
	v_mfma_f32_16x16x32_bf16 v[48:51], v[144:147], v[172:175], v[48:51]
	v_mfma_f32_16x16x32_bf16 v[68:71], v[148:151], v[176:179], v[48:51]
	v_mfma_f32_16x16x32_bf16 v[48:51], v[152:155], v[172:175], v[52:55]
	v_mfma_f32_16x16x32_bf16 v[36:39], v[144:147], v[180:183], v[36:39]
	v_mfma_f32_16x16x32_bf16 v[32:35], v[152:155], v[180:183], v[32:35]
	v_mfma_f32_16x16x32_bf16 v[20:23], v[144:147], v[188:191], v[20:23]
	v_mfma_f32_16x16x32_bf16 v[16:19], v[152:155], v[188:191], v[16:19]
	v_mfma_f32_16x16x32_bf16 v[8:11], v[144:147], v[212:215], v[8:11]
	v_mfma_f32_16x16x32_bf16 v[0:3], v[152:155], v[212:215], v[0:3]
	v_mfma_f32_16x16x32_bf16 v[64:67], v[156:159], v[176:179], v[48:51]
	v_mfma_f32_16x16x32_bf16 v[36:39], v[148:151], v[184:187], v[36:39]
	v_mfma_f32_16x16x32_bf16 v[32:35], v[156:159], v[184:187], v[32:35]
	v_mfma_f32_16x16x32_bf16 v[20:23], v[148:151], v[208:211], v[20:23]
	v_mfma_f32_16x16x32_bf16 v[16:19], v[156:159], v[208:211], v[16:19]
	v_mfma_f32_16x16x32_bf16 v[8:11], v[148:151], v[218:221], v[8:11]
	v_mfma_f32_16x16x32_bf16 v[0:3], v[156:159], v[218:221], v[0:3]
	s_setprio 0
	s_barrier
	s_cmp_gt_u32 s89, 13
	s_cbranch_scc0 .LBB0_150
	s_and_b64 vcc, exec, s[20:21]
	s_cbranch_vccz .LBB0_153
	s_barrier

; #define PG8_LAS __attribute__((address_space(3)))
; #define PG8_STAGE(bufoff, gbase, voff) do { _Pragma("unroll") for (int _i = 0; _i < 2; ++_i) \
;         __builtin_amdgcn_global_load_lds((const unsigned*)((const char*)(gbase) + (voff)[_i]), (PG8_LAS unsigned*)(lds + (bufoff) + ldsw + _i * (8 * USTR)), 16, 0, 0); } while (0)
; #define PG8_LDA(dst, b, h) do { _Pragma("unroll") for (int m = 0; m < 4; ++m) _Pragma("unroll") for (int k = 0; k < 2; ++k) dst[m][k] = *(const PG8_LAS bf16x8*)(lds + PG8_SA(b, h) + aoff + m * (2 * USTR) + k * 64); } while (0)
; #define PG8_LDB(dst, b, h) do { _Pragma("unroll") for (int n = 0; n < 2; ++n) _Pragma("unroll") for (int k = 0; k < 2; ++k) dst[n][k] = *(const PG8_LAS bf16x8*)(lds + PG8_SB(b, h) + boff + n * (2 * USTR) + k * 64); } while (0)
; template <class Epi, class Sched, bool ALIGN_EPI, bool SP2>
; __device__ __forceinline__ void gemm_phase(PG8_LAS unsigned char* lds, const Gemm g, const Sched& S, const Epi& E, int wid) {
;     ...
;             const bool last = (t == nt - 2);
;             const char* a1 = cA + (size_t)(t + 1) * kstep;
;             const char* a2 = last ? nA : cA + (size_t)(t + 2) * kstep; const char* b2 = last ? nB : cB + (size_t)(t + 2) * kstep;
;             const char* a3 = a2 + kstep; const char* b3 = b2 + kstep;
;             if constexpr (Epi::PRE == 1) { if (last) {
;                 const char* rsrc; const char* ssrc; E.pre(cur, rsrc, ssrc);
; #pragma unroll
;                 for (int _i = 0; _i < 2; ++_i) __builtin_amdgcn_global_load_lds((const unsigned*)(rsrc + (wid + 8 * _i) * 1024 + lane * 16), (PG8_LAS unsigned*)(lds + LDS_XOFF + (wid + 8 * _i) * 1024), 16, 0, 0);
;                 if (wid == 0) __builtin_amdgcn_global_load_lds((const unsigned*)(ssrc + lane * 16), (PG8_LAS unsigned*)(lds + LDS_XOFF + 16384), 16, 0, 0);
;             } }
;             if constexpr (SP2) {
;             PG8_LDB(B0, 0, 0); PG8_LDB(B1, 0, 1); PG8_SCHED; PG8_LDA(At, 0, 0); PG8_STAGE(PG8_SA(1, 1), a1 + hstepA, voffA);
;             PG8_WAIT_V(8); PG8_WAIT_L(0); PG8_BAR; PG8_MMA(0, 0, At, B0); PG8_MMA(0, 1, At, B1); PG8_BAR; PG8_SCHED;
;             PG8_LDA(At, 0, 1); PG8_STAGE(PG8_SB(0, 0), b2, voffB); PG8_STAGE(PG8_SB(0, 1), b2 + hstepB, voffB); PG8_STAGE(PG8_SA(0, 0), a2, voffA);
;             PG8_WAIT_V(8); PG8_WAIT_L(0); PG8_BAR; PG8_MMA(1, 0, At, B0); PG8_MMA(1, 1, At, B1); PG8_BAR; PG8_SCHED;
.Lhb_down:
	s_add_i32 s69, 0, 0x11000
	s_add_i32 s76, 0, 0x15400
	v_add_u32_e32 v52, s69, v197
	v_add_u32_e32 v156, s76, v197
	ds_read_b128 v[40:43], v52
	ds_read_b128 v[44:47], v52 offset:64
	ds_read_b128 v[48:51], v52 offset:2176
	ds_read_b128 v[52:55], v52 offset:2240
	ds_read_b128 v[144:147], v156
	ds_read_b128 v[148:151], v156 offset:64
	ds_read_b128 v[152:155], v156 offset:2176
	ds_read_b128 v[156:159], v156 offset:2240
	v_lshl_add_u64 v[198:199], s[38:39], 0, v[212:213]
	s_add_i32 m0, s0, 0xcc00
	ds_read_b128 v[160:163], v241
	ds_read_b128 v[164:167], v241 offset:64
	ds_read_b128 v[168:171], v241 offset:2176
	ds_read_b128 v[172:175], v241 offset:2240
	ds_read_b128 v[176:179], v241 offset:4352
	ds_read_b128 v[180:183], v241 offset:4416
	ds_read_b128 v[184:187], v241 offset:6528
	ds_read_b128 v[188:191], v241 offset:6592
	global_load_lds_dwordx4 v[198:199], off
	v_lshl_add_u64 v[198:199], s[38:39], 0, v[214:215]
	s_add_i32 m0, s0, 0xee00
	s_nop 0
	global_load_lds_dwordx4 v[198:199], off
	s_add_u32 s40, s38, 0xfff50080
	s_addc_u32 s41, s39, -1
	s_cmp_eq_u32 s68, 40
	s_cselect_b32 s43, s23, s41
	s_cselect_b32 s42, s22, s40
	s_cselect_b32 s41, s45, s27
	s_cselect_b32 s40, s44, s26
	s_waitcnt vmcnt(8)
	s_waitcnt lgkmcnt(0)
	s_barrier
	s_setprio 1
	s_waitcnt lgkmcnt(0)
	v_mfma_f32_16x16x32_bf16 v[132:135], v[40:43], v[160:163], 0
	v_mfma_f32_16x16x32_bf16 v[128:131], v[48:51], v[160:163], 0
	v_mfma_f32_16x16x32_bf16 v[124:127], v[40:43], v[168:171], 0
	v_mfma_f32_16x16x32_bf16 v[120:123], v[48:51], v[168:171], 0
	v_mfma_f32_16x16x32_bf16 v[108:111], v[40:43], v[176:179], 0
	v_mfma_f32_16x16x32_bf16 v[104:107], v[48:51], v[176:179], 0
	v_mfma_f32_16x16x32_bf16 v[92:95], v[40:43], v[184:187], 0
	v_mfma_f32_16x16x32_bf16 v[88:91], v[48:51], v[184:187], 0
	v_mfma_f32_16x16x32_bf16 v[132:135], v[44:47], v[164:167], v[132:135]
	v_mfma_f32_16x16x32_bf16 v[128:131], v[52:55], v[164:167], v[128:131]
	v_mfma_f32_16x16x32_bf16 v[124:127], v[44:47], v[172:175], v[124:127]
	v_mfma_f32_16x16x32_bf16 v[120:123], v[52:55], v[172:175], v[120:123]
	v_mfma_f32_16x16x32_bf16 v[108:111], v[44:47], v[180:183], v[108:111]
	v_mfma_f32_16x16x32_bf16 v[104:107], v[52:55], v[180:183], v[104:107]
	v_mfma_f32_16x16x32_bf16 v[92:95], v[44:47], v[188:191], v[92:95]
	v_mfma_f32_16x16x32_bf16 v[88:91], v[52:55], v[188:191], v[88:91]
	s_setprio 0
	s_setprio 1
	v_mfma_f32_16x16x32_bf16 v[140:143], v[144:147], v[160:163], 0
	v_mfma_f32_16x16x32_bf16 v[136:139], v[152:155], v[160:163], 0
	v_mfma_f32_16x16x32_bf16 v[116:119], v[144:147], v[168:171], 0
	v_mfma_f32_16x16x32_bf16 v[112:115], v[152:155], v[168:171], 0
	v_mfma_f32_16x16x32_bf16 v[100:103], v[144:147], v[176:179], 0
	v_mfma_f32_16x16x32_bf16 v[96:99], v[152:155], v[176:179], 0
	v_mfma_f32_16x16x32_bf16 v[84:87], v[144:147], v[184:187], 0
	v_mfma_f32_16x16x32_bf16 v[80:83], v[152:155], v[184:187], 0
	v_mfma_f32_16x16x32_bf16 v[140:143], v[148:151], v[164:167], v[140:143]
	v_mfma_f32_16x16x32_bf16 v[136:139], v[156:159], v[164:167], v[136:139]
	v_mfma_f32_16x16x32_bf16 v[116:119], v[148:151], v[172:175], v[116:119]
	v_mfma_f32_16x16x32_bf16 v[112:115], v[156:159], v[172:175], v[112:115]
	v_mfma_f32_16x16x32_bf16 v[100:103], v[148:151], v[180:183], v[100:103]
	v_mfma_f32_16x16x32_bf16 v[96:99], v[156:159], v[180:183], v[96:99]
	v_mfma_f32_16x16x32_bf16 v[84:87], v[148:151], v[188:191], v[84:87]
	v_mfma_f32_16x16x32_bf16 v[80:83], v[156:159], v[188:191], v[80:83]
	s_setprio 0
	s_barrier
	s_add_i32 s69, s69, s33
	v_lshl_add_u64 v[198:199], s[40:41], 0, v[208:209]
	s_mov_b32 m0, s69
	ds_read_b128 v[160:163], v241 offset:17408
	ds_read_b128 v[164:167], v241 offset:17472
	ds_read_b128 v[168:171], v241 offset:19584
	ds_read_b128 v[172:175], v241 offset:19648
	ds_read_b128 v[176:179], v241 offset:21760
	ds_read_b128 v[180:183], v241 offset:21824
	ds_read_b128 v[184:187], v241 offset:23936
	ds_read_b128 v[188:191], v241 offset:24000
	global_load_lds_dwordx4 v[198:199], off
	s_add_i32 m0, s69, 0x2200
	s_add_u32 s74, s40, 0xb0000
	v_lshl_add_u64 v[200:201], s[40:41], 0, v[210:211]
	s_addc_u32 s75, s41, 0
	s_add_i32 s69, s76, s33
	global_load_lds_dwordx4 v[200:201], off
	v_lshl_add_u64 v[216:217], s[74:75], 0, v[208:209]
	s_mov_b32 m0, s69
	v_lshl_add_u64 v[218:219], s[42:43], 0, v[210:211]
	global_load_lds_dwordx4 v[216:217], off
	v_lshl_add_u64 v[216:217], s[74:75], 0, v[210:211]
	s_add_i32 m0, s69, 0x2200
	s_nop 0
	global_load_lds_dwordx4 v[216:217], off
	v_lshl_add_u64 v[216:217], s[42:43], 0, v[208:209]
	s_mov_b32 m0, s0
	s_nop 0
	global_load_lds_dwordx4 v[216:217], off
	s_mov_b32 m0, s5
	s_nop 0
	global_load_lds_dwordx4 v[218:219], off
	s_waitcnt vmcnt(8)
	s_waitcnt lgkmcnt(0)
	s_barrier
; #define PG8_STAGE(bufoff, gbase, voff) do { _Pragma("unroll") for (int _i = 0; _i < 2; ++_i) \
;         __builtin_amdgcn_global_load_lds((const unsigned*)((const char*)(gbase) + (voff)[_i]), (PG8_LAS unsigned*)(lds + (bufoff) + ldsw + _i * (8 * USTR)), 16, 0, 0); } while (0)
; #define PG8_LDA(dst, b, h) do { _Pragma("unroll") for (int m = 0; m < 4; ++m) _Pragma("unroll") for (int k = 0; k < 2; ++k) dst[m][k] = *(const PG8_LAS bf16x8*)(lds + PG8_SA(b, h) + aoff + m * (2 * USTR) + k * 64); } while (0)
; #define PG8_LDB(dst, b, h) do { _Pragma("unroll") for (int n = 0; n < 2; ++n) _Pragma("unroll") for (int k = 0; k < 2; ++k) dst[n][k] = *(const PG8_LAS bf16x8*)(lds + PG8_SB(b, h) + boff + n * (2 * USTR) + k * 64); } while (0)
; #define PG8_MMA(ai, bj, At, Bt) do { __builtin_amdgcn_s_setprio(1); _Pragma("unroll") for (int m = 0; m < 4; ++m) _Pragma("unroll") for (int n = 0; n < 2; ++n) _Pragma("unroll") for (int k = 0; k < 2; ++k) \
;         acc[ai][bj][m][n] = __builtin_amdgcn_mfma_f32_16x16x32_bf16(Bt[n][k], At[m][k], acc[ai][bj][m][n], 0, 0, 0); __builtin_amdgcn_s_setprio(0); } while (0)
; #define PG8_WAIT_V(n) asm volatile("s_waitcnt vmcnt(" #n ")" ::: "memory")
; #define PG8_WAIT_L(n) asm volatile("s_waitcnt lgkmcnt(" #n ")" ::: "memory")
; #define PG8_BAR __builtin_amdgcn_s_barrier()
; #define PG8_SCHED __builtin_amdgcn_sched_barrier(0)
; template <class Epi, class Sched, bool ALIGN_EPI, bool SP2>
; __device__ __forceinline__ void gemm_phase(PG8_LAS unsigned char* lds, const Gemm g, const Sched& S, const Epi& E, int wid) {
;     ...
;             PG8_WAIT_V(8); PG8_WAIT_L(0); PG8_BAR; PG8_MMA(1, 0, At, B0); PG8_MMA(1, 1, At, B1); PG8_BAR; PG8_SCHED;
;             PG8_LDB(B0, 1, 0); PG8_LDB(B1, 1, 1); PG8_SCHED; PG8_LDA(At, 1, 0); PG8_STAGE(PG8_SA(0, 1), a2 + hstepA, voffA);
;             PG8_WAIT_V(8); PG8_WAIT_L(0); PG8_BAR; PG8_MMA(0, 0, At, B0); PG8_MMA(0, 1, At, B1); PG8_BAR; PG8_SCHED;
	s_setprio 1
	s_waitcnt lgkmcnt(0)
	v_mfma_f32_16x16x32_bf16 v[76:79], v[40:43], v[160:163], 0
	v_mfma_f32_16x16x32_bf16 v[72:75], v[48:51], v[160:163], 0
	v_mfma_f32_16x16x32_bf16 v[60:63], v[40:43], v[168:171], 0
	v_mfma_f32_16x16x32_bf16 v[56:59], v[48:51], v[168:171], 0
	v_mfma_f32_16x16x32_bf16 v[24:27], v[40:43], v[176:179], 0
	v_mfma_f32_16x16x32_bf16 v[28:31], v[48:51], v[176:179], 0
	v_mfma_f32_16x16x32_bf16 v[8:11], v[40:43], v[184:187], 0
	v_mfma_f32_16x16x32_bf16 v[12:15], v[48:51], v[184:187], 0
	v_mfma_f32_16x16x32_bf16 v[76:79], v[44:47], v[164:167], v[76:79]
	v_mfma_f32_16x16x32_bf16 v[72:75], v[52:55], v[164:167], v[72:75]
	v_mfma_f32_16x16x32_bf16 v[60:63], v[44:47], v[172:175], v[60:63]
	v_mfma_f32_16x16x32_bf16 v[56:59], v[52:55], v[172:175], v[56:59]
	v_mfma_f32_16x16x32_bf16 v[24:27], v[44:47], v[180:183], v[24:27]
	v_mfma_f32_16x16x32_bf16 v[28:31], v[52:55], v[180:183], v[28:31]
	v_mfma_f32_16x16x32_bf16 v[8:11], v[44:47], v[188:191], v[8:11]
	v_mfma_f32_16x16x32_bf16 v[12:15], v[52:55], v[188:191], v[12:15]
	s_setprio 0
	s_setprio 1
	v_mfma_f32_16x16x32_bf16 v[36:39], v[144:147], v[168:171], 0
	v_mfma_f32_16x16x32_bf16 v[32:35], v[152:155], v[168:171], 0
	v_mfma_f32_16x16x32_bf16 v[20:23], v[144:147], v[176:179], 0
	v_mfma_f32_16x16x32_bf16 v[16:19], v[152:155], v[176:179], 0
	v_mfma_f32_16x16x32_bf16 v[4:7], v[144:147], v[184:187], 0
	v_mfma_f32_16x16x32_bf16 v[0:3], v[152:155], v[184:187], 0
	v_mfma_f32_16x16x32_bf16 v[40:43], v[144:147], v[160:163], 0
	v_mfma_f32_16x16x32_bf16 v[44:47], v[152:155], v[160:163], 0
	v_mfma_f32_16x16x32_bf16 v[36:39], v[148:151], v[172:175], v[36:39]
	v_mfma_f32_16x16x32_bf16 v[32:35], v[156:159], v[172:175], v[32:35]
	v_mfma_f32_16x16x32_bf16 v[20:23], v[148:151], v[180:183], v[20:23]
	v_mfma_f32_16x16x32_bf16 v[16:19], v[156:159], v[180:183], v[16:19]
	v_mfma_f32_16x16x32_bf16 v[4:7], v[148:151], v[188:191], v[4:7]
	v_mfma_f32_16x16x32_bf16 v[0:3], v[156:159], v[188:191], v[0:3]
	v_mfma_f32_16x16x32_bf16 v[40:43], v[148:151], v[164:167], v[40:43]
	v_mfma_f32_16x16x32_bf16 v[44:47], v[156:159], v[164:167], v[44:47]
	s_setprio 0
	s_barrier
	s_add_i32 s69, 0, 0x19800
	s_add_i32 s74, 0, 0x1dc00
	v_add_u32_e32 v68, s69, v197
	v_add_u32_e32 v156, s74, v197
	ds_read_b128 v[48:51], v68
	ds_read_b128 v[52:55], v68 offset:64
	ds_read_b128 v[64:67], v68 offset:2176
	ds_read_b128 v[68:71], v68 offset:2240
	ds_read_b128 v[144:147], v156
	ds_read_b128 v[148:151], v156 offset:64
	ds_read_b128 v[152:155], v156 offset:2176
	ds_read_b128 v[156:159], v156 offset:2240
	s_add_u32 s42, s42, 0xb0000
	s_addc_u32 s43, s43, 0
	s_mov_b32 m0, s29
	v_lshl_add_u64 v[220:221], s[42:43], 0, v[208:209]
	ds_read_b128 v[160:163], v241 offset:34816
	ds_read_b128 v[164:167], v241 offset:34880
	ds_read_b128 v[168:171], v241 offset:36992
	ds_read_b128 v[172:175], v241 offset:37056
	ds_read_b128 v[176:179], v241 offset:39168
	ds_read_b128 v[180:183], v241 offset:39232
	ds_read_b128 v[184:187], v241 offset:41344
	ds_read_b128 v[188:191], v241 offset:41408
	global_load_lds_dwordx4 v[220:221], off
	v_lshl_add_u64 v[220:221], s[42:43], 0, v[210:211]
	s_mov_b32 m0, s56
	s_nop 0
	global_load_lds_dwordx4 v[220:221], off
	s_waitcnt vmcnt(8)
	s_waitcnt lgkmcnt(0)
	s_barrier
	s_setprio 1
	s_waitcnt lgkmcnt(0)
	v_mfma_f32_16x16x32_bf16 v[132:135], v[48:51], v[160:163], v[132:135]
	v_mfma_f32_16x16x32_bf16 v[128:131], v[64:67], v[160:163], v[128:131]
	v_mfma_f32_16x16x32_bf16 v[124:127], v[48:51], v[168:171], v[124:127]
	v_mfma_f32_16x16x32_bf16 v[120:123], v[64:67], v[168:171], v[120:123]
	v_mfma_f32_16x16x32_bf16 v[108:111], v[48:51], v[176:179], v[108:111]
	v_mfma_f32_16x16x32_bf16 v[104:107], v[64:67], v[176:179], v[104:107]
	v_mfma_f32_16x16x32_bf16 v[92:95], v[48:51], v[184:187], v[92:95]
	v_mfma_f32_16x16x32_bf16 v[88:91], v[64:67], v[184:187], v[88:91]
	v_mfma_f32_16x16x32_bf16 v[132:135], v[52:55], v[164:167], v[132:135]
	v_mfma_f32_16x16x32_bf16 v[128:131], v[68:71], v[164:167], v[128:131]
	v_mfma_f32_16x16x32_bf16 v[124:127], v[52:55], v[172:175], v[124:127]
	v_mfma_f32_16x16x32_bf16 v[120:123], v[68:71], v[172:175], v[120:123]
	v_mfma_f32_16x16x32_bf16 v[108:111], v[52:55], v[180:183], v[108:111]
	v_mfma_f32_16x16x32_bf16 v[104:107], v[68:71], v[180:183], v[104:107]
	v_mfma_f32_16x16x32_bf16 v[92:95], v[52:55], v[188:191], v[92:95]
	v_mfma_f32_16x16x32_bf16 v[88:91], v[68:71], v[188:191], v[88:91]
	s_setprio 0
	s_setprio 1
	v_mfma_f32_16x16x32_bf16 v[140:143], v[144:147], v[160:163], v[140:143]
	v_mfma_f32_16x16x32_bf16 v[136:139], v[152:155], v[160:163], v[136:139]
	v_mfma_f32_16x16x32_bf16 v[116:119], v[144:147], v[168:171], v[116:119]
	v_mfma_f32_16x16x32_bf16 v[112:115], v[152:155], v[168:171], v[112:115]
	v_mfma_f32_16x16x32_bf16 v[100:103], v[144:147], v[176:179], v[100:103]
	v_mfma_f32_16x16x32_bf16 v[96:99], v[152:155], v[176:179], v[96:99]
	v_mfma_f32_16x16x32_bf16 v[84:87], v[144:147], v[184:187], v[84:87]
	v_mfma_f32_16x16x32_bf16 v[80:83], v[152:155], v[184:187], v[80:83]
	v_mfma_f32_16x16x32_bf16 v[140:143], v[148:151], v[164:167], v[140:143]
	v_mfma_f32_16x16x32_bf16 v[136:139], v[156:159], v[164:167], v[136:139]
	v_mfma_f32_16x16x32_bf16 v[116:119], v[148:151], v[172:175], v[116:119]
	v_mfma_f32_16x16x32_bf16 v[112:115], v[156:159], v[172:175], v[112:115]
	v_mfma_f32_16x16x32_bf16 v[100:103], v[148:151], v[180:183], v[100:103]
	v_mfma_f32_16x16x32_bf16 v[96:99], v[156:159], v[180:183], v[96:99]
	v_mfma_f32_16x16x32_bf16 v[84:87], v[148:151], v[188:191], v[84:87]
	v_mfma_f32_16x16x32_bf16 v[80:83], v[156:159], v[188:191], v[80:83]
	s_setprio 0
	s_barrier
; #define PG8_LAS __attribute__((address_space(3)))
; #define PG8_STAGE(bufoff, gbase, voff) do { _Pragma("unroll") for (int _i = 0; _i < 2; ++_i) \
;         __builtin_amdgcn_global_load_lds((const unsigned*)((const char*)(gbase) + (voff)[_i]), (PG8_LAS unsigned*)(lds + (bufoff) + ldsw + _i * (8 * USTR)), 16, 0, 0); } while (0)
; #define PG8_WAIT_V(n) asm volatile("s_waitcnt vmcnt(" #n ")" ::: "memory")
; #define PG8_WAIT_L(n) asm volatile("s_waitcnt lgkmcnt(" #n ")" ::: "memory")
; template <class Epi, class Sched, bool ALIGN_EPI, bool SP2>
; __device__ __forceinline__ void gemm_phase(PG8_LAS unsigned char* lds, const Gemm g, const Sched& S, const Epi& E, int wid) {
;     ...
;         for (int t = 0; t < nt; t += 2) {
;             const bool last = (t == nt - 2);
;             const char* a1 = cA + (size_t)(t + 1) * kstep;
;             const char* a2 = last ? nA : cA + (size_t)(t + 2) * kstep; const char* b2 = last ? nB : cB + (size_t)(t + 2) * kstep;
;             const char* a3 = a2 + kstep; const char* b3 = b2 + kstep;
;             if constexpr (Epi::PRE == 1) { if (last) {
;                 const char* rsrc; const char* ssrc; E.pre(cur, rsrc, ssrc);
; #pragma unroll
;                 for (int _i = 0; _i < 2; ++_i) __builtin_amdgcn_global_load_lds((const unsigned*)(rsrc + (wid + 8 * _i) * 1024 + lane * 16), (PG8_LAS unsigned*)(lds + LDS_XOFF + (wid + 8 * _i) * 1024), 16, 0, 0);
;                 if (wid == 0) __builtin_amdgcn_global_load_lds((const unsigned*)(ssrc + lane * 16), (PG8_LAS unsigned*)(lds + LDS_XOFF + 16384), 16, 0, 0);
;             } }
;             if constexpr (SP2) {
;             PG8_LDB(B0, 0, 0); PG8_LDB(B1, 0, 1); PG8_SCHED; PG8_LDA(At, 0, 0); PG8_STAGE(PG8_SA(1, 1), a1 + hstepA, voffA);
;             PG8_WAIT_V(8); PG8_WAIT_L(0); PG8_BAR; PG8_MMA(0, 0, At, B0); PG8_MMA(0, 1, At, B1); PG8_BAR; PG8_SCHED;
;             PG8_LDA(At, 0, 1); PG8_STAGE(PG8_SB(0, 0), b2, voffB); PG8_STAGE(PG8_SB(0, 1), b2 + hstepB, voffB); PG8_STAGE(PG8_SA(0, 0), a2, voffA);
;             PG8_WAIT_V(8); PG8_WAIT_L(0); PG8_BAR; PG8_MMA(1, 0, At, B0); PG8_MMA(1, 1, At, B1); PG8_BAR; PG8_SCHED;
;     ...
;             PG8_LDA(At, 1, 1); PG8_STAGE(PG8_SB(1, 0), b3, voffB); PG8_STAGE(PG8_SB(1, 1), b3 + hstepB, voffB); PG8_STAGE(PG8_SA(1, 0), a3, voffA);
;             PG8_WAIT_V(8); PG8_WAIT_L(0); PG8_BAR; PG8_MMA(1, 0, At, B0); PG8_MMA(1, 1, At, B1); PG8_BAR; PG8_SCHED;
	s_add_i32 s42, s69, s33
	v_lshl_add_u64 v[198:199], v[198:199], 0, s[6:7]
	s_mov_b32 m0, s42
	ds_read_b128 v[160:163], v241 offset:52224
	ds_read_b128 v[164:167], v241 offset:52288
	ds_read_b128 v[168:171], v241 offset:54400
	ds_read_b128 v[172:175], v241 offset:54464
	ds_read_b128 v[176:179], v241 offset:56576
	ds_read_b128 v[180:183], v241 offset:56640
	ds_read_b128 v[184:187], v241 offset:58752
	ds_read_b128 v[188:191], v241 offset:58816
	global_load_lds_dwordx4 v[198:199], off
	s_add_i32 m0, s42, 0x2200
	s_add_u32 s40, s40, 0xb0080
	v_lshl_add_u64 v[198:199], v[200:201], 0, s[6:7]
	s_addc_u32 s41, s41, 0
	s_add_i32 s42, s74, s33
	global_load_lds_dwordx4 v[198:199], off
	v_lshl_add_u64 v[198:199], s[40:41], 0, v[208:209]
	s_mov_b32 m0, s42
	s_nop 0
	global_load_lds_dwordx4 v[198:199], off
	v_lshl_add_u64 v[198:199], s[40:41], 0, v[210:211]
	s_add_i32 m0, s42, 0x2200
	s_nop 0
	global_load_lds_dwordx4 v[198:199], off
	v_lshl_add_u64 v[198:199], v[216:217], 0, s[6:7]
	s_mov_b32 m0, s57
	s_nop 0
	global_load_lds_dwordx4 v[198:199], off
	v_lshl_add_u64 v[198:199], v[218:219], 0, s[6:7]
	s_mov_b32 m0, s70
	s_nop 0
	global_load_lds_dwordx4 v[198:199], off
	s_add_i32 s68, s68, 2
	s_add_u32 s38, s38, 0x100
	s_addc_u32 s39, s39, 0
	s_add_u32 s26, s26, 0x100
	s_addc_u32 s27, s27, 0
	s_waitcnt vmcnt(8)
	s_waitcnt lgkmcnt(0)
	s_barrier
	s_setprio 1
	s_waitcnt lgkmcnt(0)
	v_mfma_f32_16x16x32_bf16 v[76:79], v[48:51], v[160:163], v[76:79]
	v_mfma_f32_16x16x32_bf16 v[72:75], v[64:67], v[160:163], v[72:75]
	v_mfma_f32_16x16x32_bf16 v[60:63], v[48:51], v[168:171], v[60:63]
	v_mfma_f32_16x16x32_bf16 v[56:59], v[64:67], v[168:171], v[56:59]
	v_mfma_f32_16x16x32_bf16 v[24:27], v[48:51], v[176:179], v[24:27]
	v_mfma_f32_16x16x32_bf16 v[28:31], v[64:67], v[176:179], v[28:31]
	v_mfma_f32_16x16x32_bf16 v[8:11], v[48:51], v[184:187], v[8:11]
	v_mfma_f32_16x16x32_bf16 v[12:15], v[64:67], v[184:187], v[12:15]
	v_mfma_f32_16x16x32_bf16 v[76:79], v[52:55], v[164:167], v[76:79]
	v_mfma_f32_16x16x32_bf16 v[72:75], v[68:71], v[164:167], v[72:75]
	v_mfma_f32_16x16x32_bf16 v[60:63], v[52:55], v[172:175], v[60:63]
	v_mfma_f32_16x16x32_bf16 v[56:59], v[68:71], v[172:175], v[56:59]
	v_mfma_f32_16x16x32_bf16 v[24:27], v[52:55], v[180:183], v[24:27]
	v_mfma_f32_16x16x32_bf16 v[28:31], v[68:71], v[180:183], v[28:31]
	v_mfma_f32_16x16x32_bf16 v[8:11], v[52:55], v[188:191], v[8:11]
	v_mfma_f32_16x16x32_bf16 v[12:15], v[68:71], v[188:191], v[12:15]
	s_setprio 0
	s_setprio 1
	v_mfma_f32_16x16x32_bf16 v[40:43], v[144:147], v[160:163], v[40:43]
	v_mfma_f32_16x16x32_bf16 v[68:71], v[148:151], v[164:167], v[40:43]
	v_mfma_f32_16x16x32_bf16 v[40:43], v[152:155], v[160:163], v[44:47]
	v_mfma_f32_16x16x32_bf16 v[36:39], v[144:147], v[168:171], v[36:39]
	v_mfma_f32_16x16x32_bf16 v[32:35], v[152:155], v[168:171], v[32:35]
	v_mfma_f32_16x16x32_bf16 v[20:23], v[144:147], v[176:179], v[20:23]
	v_mfma_f32_16x16x32_bf16 v[16:19], v[152:155], v[176:179], v[16:19]
	v_mfma_f32_16x16x32_bf16 v[4:7], v[144:147], v[184:187], v[4:7]
	v_mfma_f32_16x16x32_bf16 v[0:3], v[152:155], v[184:187], v[0:3]
	v_mfma_f32_16x16x32_bf16 v[64:67], v[156:159], v[164:167], v[40:43]
	v_mfma_f32_16x16x32_bf16 v[36:39], v[148:151], v[172:175], v[36:39]
	v_mfma_f32_16x16x32_bf16 v[32:35], v[156:159], v[172:175], v[32:35]
	v_mfma_f32_16x16x32_bf16 v[20:23], v[148:151], v[180:183], v[20:23]
	v_mfma_f32_16x16x32_bf16 v[16:19], v[156:159], v[180:183], v[16:19]
	v_mfma_f32_16x16x32_bf16 v[4:7], v[148:151], v[188:191], v[4:7]
	v_mfma_f32_16x16x32_bf16 v[0:3], v[156:159], v[188:191], v[0:3]
	s_setprio 0
	s_barrier
	s_cmp_gt_u32 s68, 41
.LBB0_290:
	s_add_i32 s69, 0, 0x11000
	s_add_i32 s76, 0, 0x15400
	v_add_u32_e32 v52, s69, v197
	v_add_u32_e32 v156, s76, v197
	ds_read_b128 v[40:43], v52
	ds_read_b128 v[44:47], v52 offset:64
	ds_read_b128 v[48:51], v52 offset:2176
	ds_read_b128 v[52:55], v52 offset:2240
	ds_read_b128 v[144:147], v156
	ds_read_b128 v[148:151], v156 offset:64
	ds_read_b128 v[152:155], v156 offset:2176
	ds_read_b128 v[156:159], v156 offset:2240
	v_lshl_add_u64 v[198:199], s[38:39], 0, v[212:213]
	s_add_i32 m0, s0, 0xcc00
	ds_read_b128 v[160:163], v241
	ds_read_b128 v[164:167], v241 offset:64
	ds_read_b128 v[168:171], v241 offset:2176
	ds_read_b128 v[172:175], v241 offset:2240
	ds_read_b128 v[176:179], v241 offset:4352
	ds_read_b128 v[180:183], v241 offset:4416
	ds_read_b128 v[184:187], v241 offset:6528
	ds_read_b128 v[188:191], v241 offset:6592
	global_load_lds_dwordx4 v[198:199], off
	v_lshl_add_u64 v[198:199], s[38:39], 0, v[214:215]
	s_add_i32 m0, s0, 0xee00
	s_nop 0
	global_load_lds_dwordx4 v[198:199], off
	s_add_u32 s40, s38, 0xfff50080
	s_addc_u32 s41, s39, -1
	s_cmp_eq_u32 s68, 40
	s_cselect_b32 s43, s23, s41
	s_cselect_b32 s42, s22, s40
	s_cselect_b32 s41, s45, s27
	s_cselect_b32 s40, s44, s26
	s_waitcnt vmcnt(8)
	s_waitcnt lgkmcnt(0)
	s_barrier
; #define PG8_STAGE(bufoff, gbase, voff) do { _Pragma("unroll") for (int _i = 0; _i < 2; ++_i) \
;         __builtin_amdgcn_global_load_lds((const unsigned*)((const char*)(gbase) + (voff)[_i]), (PG8_LAS unsigned*)(lds + (bufoff) + ldsw + _i * (8 * USTR)), 16, 0, 0); } while (0)
; #define PG8_LDA(dst, b, h) do { _Pragma("unroll") for (int m = 0; m < 4; ++m) _Pragma("unroll") for (int k = 0; k < 2; ++k) dst[m][k] = *(const PG8_LAS bf16x8*)(lds + PG8_SA(b, h) + aoff + m * (2 * USTR) + k * 64); } while (0)
; #define PG8_MMA(ai, bj, At, Bt) do { __builtin_amdgcn_s_setprio(1); _Pragma("unroll") for (int m = 0; m < 4; ++m) _Pragma("unroll") for (int n = 0; n < 2; ++n) _Pragma("unroll") for (int k = 0; k < 2; ++k) \
;         acc[ai][bj][m][n] = __builtin_amdgcn_mfma_f32_16x16x32_bf16(Bt[n][k], At[m][k], acc[ai][bj][m][n], 0, 0, 0); __builtin_amdgcn_s_setprio(0); } while (0)
; #define PG8_WAIT_V(n) asm volatile("s_waitcnt vmcnt(" #n ")" ::: "memory")
; #define PG8_WAIT_L(n) asm volatile("s_waitcnt lgkmcnt(" #n ")" ::: "memory")
; #define PG8_BAR __builtin_amdgcn_s_barrier()
; #define PG8_SCHED __builtin_amdgcn_sched_barrier(0)
; template <class Epi, class Sched, bool ALIGN_EPI, bool SP2>
; __device__ __forceinline__ void gemm_phase(PG8_LAS unsigned char* lds, const Gemm g, const Sched& S, const Epi& E, int wid) {
;     ...
;             PG8_WAIT_V(8); PG8_WAIT_L(0); PG8_BAR; PG8_MMA(0, 0, At, B0); PG8_MMA(0, 1, At, B1); PG8_BAR; PG8_SCHED;
;             PG8_LDA(At, 0, 1); PG8_STAGE(PG8_SB(0, 0), b2, voffB); PG8_STAGE(PG8_SB(0, 1), b2 + hstepB, voffB); PG8_STAGE(PG8_SA(0, 0), a2, voffA);
;             PG8_WAIT_V(8); PG8_WAIT_L(0); PG8_BAR; PG8_MMA(1, 0, At, B0); PG8_MMA(1, 1, At, B1); PG8_BAR; PG8_SCHED;
	s_setprio 1
	s_waitcnt lgkmcnt(0)
	v_mfma_f32_16x16x32_bf16 v[132:135], v[40:43], v[160:163], v[132:135]
	v_mfma_f32_16x16x32_bf16 v[128:131], v[48:51], v[160:163], v[128:131]
	v_mfma_f32_16x16x32_bf16 v[124:127], v[40:43], v[168:171], v[124:127]
	v_mfma_f32_16x16x32_bf16 v[120:123], v[48:51], v[168:171], v[120:123]
	v_mfma_f32_16x16x32_bf16 v[108:111], v[40:43], v[176:179], v[108:111]
	v_mfma_f32_16x16x32_bf16 v[104:107], v[48:51], v[176:179], v[104:107]
	v_mfma_f32_16x16x32_bf16 v[92:95], v[40:43], v[184:187], v[92:95]
	v_mfma_f32_16x16x32_bf16 v[88:91], v[48:51], v[184:187], v[88:91]
	v_mfma_f32_16x16x32_bf16 v[132:135], v[44:47], v[164:167], v[132:135]
	v_mfma_f32_16x16x32_bf16 v[128:131], v[52:55], v[164:167], v[128:131]
	v_mfma_f32_16x16x32_bf16 v[124:127], v[44:47], v[172:175], v[124:127]
	v_mfma_f32_16x16x32_bf16 v[120:123], v[52:55], v[172:175], v[120:123]
	v_mfma_f32_16x16x32_bf16 v[108:111], v[44:47], v[180:183], v[108:111]
	v_mfma_f32_16x16x32_bf16 v[104:107], v[52:55], v[180:183], v[104:107]
	v_mfma_f32_16x16x32_bf16 v[92:95], v[44:47], v[188:191], v[92:95]
	v_mfma_f32_16x16x32_bf16 v[88:91], v[52:55], v[188:191], v[88:91]
	s_setprio 0
	s_setprio 1
	v_mfma_f32_16x16x32_bf16 v[140:143], v[144:147], v[160:163], v[140:143]
	v_mfma_f32_16x16x32_bf16 v[136:139], v[152:155], v[160:163], v[136:139]
	v_mfma_f32_16x16x32_bf16 v[116:119], v[144:147], v[168:171], v[116:119]
	v_mfma_f32_16x16x32_bf16 v[112:115], v[152:155], v[168:171], v[112:115]
	v_mfma_f32_16x16x32_bf16 v[100:103], v[144:147], v[176:179], v[100:103]
	v_mfma_f32_16x16x32_bf16 v[96:99], v[152:155], v[176:179], v[96:99]
	v_mfma_f32_16x16x32_bf16 v[84:87], v[144:147], v[184:187], v[84:87]
	v_mfma_f32_16x16x32_bf16 v[80:83], v[152:155], v[184:187], v[80:83]
	v_mfma_f32_16x16x32_bf16 v[140:143], v[148:151], v[164:167], v[140:143]
	v_mfma_f32_16x16x32_bf16 v[136:139], v[156:159], v[164:167], v[136:139]
	v_mfma_f32_16x16x32_bf16 v[116:119], v[148:151], v[172:175], v[116:119]
	v_mfma_f32_16x16x32_bf16 v[112:115], v[156:159], v[172:175], v[112:115]
	v_mfma_f32_16x16x32_bf16 v[100:103], v[148:151], v[180:183], v[100:103]
	v_mfma_f32_16x16x32_bf16 v[96:99], v[156:159], v[180:183], v[96:99]
	v_mfma_f32_16x16x32_bf16 v[84:87], v[148:151], v[188:191], v[84:87]
	v_mfma_f32_16x16x32_bf16 v[80:83], v[156:159], v[188:191], v[80:83]
	s_setprio 0
	s_barrier
	s_add_i32 s69, s69, s33
	v_lshl_add_u64 v[198:199], s[40:41], 0, v[208:209]
	s_mov_b32 m0, s69
	ds_read_b128 v[160:163], v241 offset:17408
	ds_read_b128 v[164:167], v241 offset:17472
	ds_read_b128 v[168:171], v241 offset:19584
	ds_read_b128 v[172:175], v241 offset:19648
	ds_read_b128 v[176:179], v241 offset:21760
	ds_read_b128 v[180:183], v241 offset:21824
	ds_read_b128 v[184:187], v241 offset:23936
	ds_read_b128 v[188:191], v241 offset:24000
	global_load_lds_dwordx4 v[198:199], off
	s_add_i32 m0, s69, 0x2200
	s_add_u32 s74, s40, 0xb0000
	v_lshl_add_u64 v[200:201], s[40:41], 0, v[210:211]
	s_addc_u32 s75, s41, 0
	s_add_i32 s69, s76, s33
	global_load_lds_dwordx4 v[200:201], off
	v_lshl_add_u64 v[216:217], s[74:75], 0, v[208:209]
	s_mov_b32 m0, s69
	v_lshl_add_u64 v[218:219], s[42:43], 0, v[210:211]
	global_load_lds_dwordx4 v[216:217], off
	v_lshl_add_u64 v[216:217], s[74:75], 0, v[210:211]
	s_add_i32 m0, s69, 0x2200
	s_nop 0
	global_load_lds_dwordx4 v[216:217], off
	v_lshl_add_u64 v[216:217], s[42:43], 0, v[208:209]
	s_mov_b32 m0, s0
	s_nop 0
	global_load_lds_dwordx4 v[216:217], off
	s_mov_b32 m0, s5
	s_nop 0
	global_load_lds_dwordx4 v[218:219], off
	s_waitcnt vmcnt(8)
	s_waitcnt lgkmcnt(0)
	s_barrier
	s_setprio 1
	s_waitcnt lgkmcnt(0)
	v_mfma_f32_16x16x32_bf16 v[76:79], v[40:43], v[160:163], v[76:79]
	v_mfma_f32_16x16x32_bf16 v[72:75], v[48:51], v[160:163], v[72:75]
	v_mfma_f32_16x16x32_bf16 v[60:63], v[40:43], v[168:171], v[60:63]
	v_mfma_f32_16x16x32_bf16 v[56:59], v[48:51], v[168:171], v[56:59]
	v_mfma_f32_16x16x32_bf16 v[24:27], v[40:43], v[176:179], v[24:27]
	v_mfma_f32_16x16x32_bf16 v[28:31], v[48:51], v[176:179], v[28:31]
	v_mfma_f32_16x16x32_bf16 v[8:11], v[40:43], v[184:187], v[8:11]
	v_mfma_f32_16x16x32_bf16 v[12:15], v[48:51], v[184:187], v[12:15]
	v_mfma_f32_16x16x32_bf16 v[76:79], v[44:47], v[164:167], v[76:79]
	v_mfma_f32_16x16x32_bf16 v[72:75], v[52:55], v[164:167], v[72:75]
	v_mfma_f32_16x16x32_bf16 v[60:63], v[44:47], v[172:175], v[60:63]
	v_mfma_f32_16x16x32_bf16 v[56:59], v[52:55], v[172:175], v[56:59]
	v_mfma_f32_16x16x32_bf16 v[24:27], v[44:47], v[180:183], v[24:27]
	v_mfma_f32_16x16x32_bf16 v[28:31], v[52:55], v[180:183], v[28:31]
	v_mfma_f32_16x16x32_bf16 v[8:11], v[44:47], v[188:191], v[8:11]
	v_mfma_f32_16x16x32_bf16 v[12:15], v[52:55], v[188:191], v[12:15]
	s_setprio 0
	s_setprio 1
	v_mfma_f32_16x16x32_bf16 v[36:39], v[144:147], v[168:171], v[36:39]
	v_mfma_f32_16x16x32_bf16 v[32:35], v[152:155], v[168:171], v[32:35]
	v_mfma_f32_16x16x32_bf16 v[20:23], v[144:147], v[176:179], v[20:23]
	v_mfma_f32_16x16x32_bf16 v[16:19], v[152:155], v[176:179], v[16:19]
	v_mfma_f32_16x16x32_bf16 v[4:7], v[144:147], v[184:187], v[4:7]
	v_mfma_f32_16x16x32_bf16 v[0:3], v[152:155], v[184:187], v[0:3]
	v_mfma_f32_16x16x32_bf16 v[40:43], v[144:147], v[160:163], v[68:71]
	v_mfma_f32_16x16x32_bf16 v[44:47], v[152:155], v[160:163], v[64:67]
	v_mfma_f32_16x16x32_bf16 v[36:39], v[148:151], v[172:175], v[36:39]
	v_mfma_f32_16x16x32_bf16 v[32:35], v[156:159], v[172:175], v[32:35]
	v_mfma_f32_16x16x32_bf16 v[20:23], v[148:151], v[180:183], v[20:23]
	v_mfma_f32_16x16x32_bf16 v[16:19], v[156:159], v[180:183], v[16:19]
	v_mfma_f32_16x16x32_bf16 v[4:7], v[148:151], v[188:191], v[4:7]
	v_mfma_f32_16x16x32_bf16 v[0:3], v[156:159], v[188:191], v[0:3]
	v_mfma_f32_16x16x32_bf16 v[40:43], v[148:151], v[164:167], v[40:43]
	v_mfma_f32_16x16x32_bf16 v[44:47], v[156:159], v[164:167], v[44:47]
	s_setprio 0
	s_barrier
; #define PG8_STAGE(bufoff, gbase, voff) do { _Pragma("unroll") for (int _i = 0; _i < 2; ++_i) \
;         __builtin_amdgcn_global_load_lds((const unsigned*)((const char*)(gbase) + (voff)[_i]), (PG8_LAS unsigned*)(lds + (bufoff) + ldsw + _i * (8 * USTR)), 16, 0, 0); } while (0)
; #define PG8_LDA(dst, b, h) do { _Pragma("unroll") for (int m = 0; m < 4; ++m) _Pragma("unroll") for (int k = 0; k < 2; ++k) dst[m][k] = *(const PG8_LAS bf16x8*)(lds + PG8_SA(b, h) + aoff + m * (2 * USTR) + k * 64); } while (0)
; #define PG8_LDB(dst, b, h) do { _Pragma("unroll") for (int n = 0; n < 2; ++n) _Pragma("unroll") for (int k = 0; k < 2; ++k) dst[n][k] = *(const PG8_LAS bf16x8*)(lds + PG8_SB(b, h) + boff + n * (2 * USTR) + k * 64); } while (0)
; #define PG8_MMA(ai, bj, At, Bt) do { __builtin_amdgcn_s_setprio(1); _Pragma("unroll") for (int m = 0; m < 4; ++m) _Pragma("unroll") for (int n = 0; n < 2; ++n) _Pragma("unroll") for (int k = 0; k < 2; ++k) \
;         acc[ai][bj][m][n] = __builtin_amdgcn_mfma_f32_16x16x32_bf16(Bt[n][k], At[m][k], acc[ai][bj][m][n], 0, 0, 0); __builtin_amdgcn_s_setprio(0); } while (0)
; #define PG8_WAIT_V(n) asm volatile("s_waitcnt vmcnt(" #n ")" ::: "memory")
; #define PG8_WAIT_L(n) asm volatile("s_waitcnt lgkmcnt(" #n ")" ::: "memory")
; #define PG8_BAR __builtin_amdgcn_s_barrier()
; #define PG8_SCHED __builtin_amdgcn_sched_barrier(0)
; template <class Epi, class Sched, bool ALIGN_EPI, bool SP2>
; __device__ __forceinline__ void gemm_phase(PG8_LAS unsigned char* lds, const Gemm g, const Sched& S, const Epi& E, int wid) {
;     ...
;             PG8_LDB(B0, 1, 0); PG8_LDB(B1, 1, 1); PG8_SCHED; PG8_LDA(At, 1, 0); PG8_STAGE(PG8_SA(0, 1), a2 + hstepA, voffA);
;             PG8_WAIT_V(8); PG8_WAIT_L(0); PG8_BAR; PG8_MMA(0, 0, At, B0); PG8_MMA(0, 1, At, B1); PG8_BAR; PG8_SCHED;
	s_add_i32 s69, 0, 0x19800
	s_add_i32 s74, 0, 0x1dc00
	v_add_u32_e32 v68, s69, v197
	v_add_u32_e32 v156, s74, v197
	ds_read_b128 v[48:51], v68
	ds_read_b128 v[52:55], v68 offset:64
	ds_read_b128 v[64:67], v68 offset:2176
	ds_read_b128 v[68:71], v68 offset:2240
	ds_read_b128 v[144:147], v156
	ds_read_b128 v[148:151], v156 offset:64
	ds_read_b128 v[152:155], v156 offset:2176
	ds_read_b128 v[156:159], v156 offset:2240
	s_add_u32 s42, s42, 0xb0000
	s_addc_u32 s43, s43, 0
	s_mov_b32 m0, s29
	v_lshl_add_u64 v[220:221], s[42:43], 0, v[208:209]
	ds_read_b128 v[160:163], v241 offset:34816
	ds_read_b128 v[164:167], v241 offset:34880
	ds_read_b128 v[168:171], v241 offset:36992
	ds_read_b128 v[172:175], v241 offset:37056
	ds_read_b128 v[176:179], v241 offset:39168
	ds_read_b128 v[180:183], v241 offset:39232
	ds_read_b128 v[184:187], v241 offset:41344
	ds_read_b128 v[188:191], v241 offset:41408
	global_load_lds_dwordx4 v[220:221], off
	v_lshl_add_u64 v[220:221], s[42:43], 0, v[210:211]
	s_mov_b32 m0, s56
	s_nop 0
	global_load_lds_dwordx4 v[220:221], off
	s_waitcnt vmcnt(8)
	s_waitcnt lgkmcnt(0)
	s_barrier
	s_setprio 1
	s_waitcnt lgkmcnt(0)
	v_mfma_f32_16x16x32_bf16 v[132:135], v[48:51], v[160:163], v[132:135]
	v_mfma_f32_16x16x32_bf16 v[128:131], v[64:67], v[160:163], v[128:131]
	v_mfma_f32_16x16x32_bf16 v[124:127], v[48:51], v[168:171], v[124:127]
	v_mfma_f32_16x16x32_bf16 v[120:123], v[64:67], v[168:171], v[120:123]
	v_mfma_f32_16x16x32_bf16 v[108:111], v[48:51], v[176:179], v[108:111]
	v_mfma_f32_16x16x32_bf16 v[104:107], v[64:67], v[176:179], v[104:107]
	v_mfma_f32_16x16x32_bf16 v[92:95], v[48:51], v[184:187], v[92:95]
	v_mfma_f32_16x16x32_bf16 v[88:91], v[64:67], v[184:187], v[88:91]
	v_mfma_f32_16x16x32_bf16 v[132:135], v[52:55], v[164:167], v[132:135]
	v_mfma_f32_16x16x32_bf16 v[128:131], v[68:71], v[164:167], v[128:131]
	v_mfma_f32_16x16x32_bf16 v[124:127], v[52:55], v[172:175], v[124:127]
	v_mfma_f32_16x16x32_bf16 v[120:123], v[68:71], v[172:175], v[120:123]
	v_mfma_f32_16x16x32_bf16 v[108:111], v[52:55], v[180:183], v[108:111]
	v_mfma_f32_16x16x32_bf16 v[104:107], v[68:71], v[180:183], v[104:107]
	v_mfma_f32_16x16x32_bf16 v[92:95], v[52:55], v[188:191], v[92:95]
	v_mfma_f32_16x16x32_bf16 v[88:91], v[68:71], v[188:191], v[88:91]
	s_setprio 0
	s_setprio 1
	v_mfma_f32_16x16x32_bf16 v[140:143], v[144:147], v[160:163], v[140:143]
	v_mfma_f32_16x16x32_bf16 v[136:139], v[152:155], v[160:163], v[136:139]
	v_mfma_f32_16x16x32_bf16 v[116:119], v[144:147], v[168:171], v[116:119]
	v_mfma_f32_16x16x32_bf16 v[112:115], v[152:155], v[168:171], v[112:115]
	v_mfma_f32_16x16x32_bf16 v[100:103], v[144:147], v[176:179], v[100:103]
	v_mfma_f32_16x16x32_bf16 v[96:99], v[152:155], v[176:179], v[96:99]
	v_mfma_f32_16x16x32_bf16 v[84:87], v[144:147], v[184:187], v[84:87]
	v_mfma_f32_16x16x32_bf16 v[80:83], v[152:155], v[184:187], v[80:83]
	v_mfma_f32_16x16x32_bf16 v[140:143], v[148:151], v[164:167], v[140:143]
	v_mfma_f32_16x16x32_bf16 v[136:139], v[156:159], v[164:167], v[136:139]
	v_mfma_f32_16x16x32_bf16 v[116:119], v[148:151], v[172:175], v[116:119]
	v_mfma_f32_16x16x32_bf16 v[112:115], v[156:159], v[172:175], v[112:115]
	v_mfma_f32_16x16x32_bf16 v[100:103], v[148:151], v[180:183], v[100:103]
	v_mfma_f32_16x16x32_bf16 v[96:99], v[156:159], v[180:183], v[96:99]
	v_mfma_f32_16x16x32_bf16 v[84:87], v[148:151], v[188:191], v[84:87]
	v_mfma_f32_16x16x32_bf16 v[80:83], v[156:159], v[188:191], v[80:83]
	s_setprio 0
	s_barrier
; #define PG8_STAGE(bufoff, gbase, voff) do { _Pragma("unroll") for (int _i = 0; _i < 2; ++_i) \
;         __builtin_amdgcn_global_load_lds((const unsigned*)((const char*)(gbase) + (voff)[_i]), (PG8_LAS unsigned*)(lds + (bufoff) + ldsw + _i * (8 * USTR)), 16, 0, 0); } while (0)
; #define PG8_LDA(dst, b, h) do { _Pragma("unroll") for (int m = 0; m < 4; ++m) _Pragma("unroll") for (int k = 0; k < 2; ++k) dst[m][k] = *(const PG8_LAS bf16x8*)(lds + PG8_SA(b, h) + aoff + m * (2 * USTR) + k * 64); } while (0)
; #define PG8_MMA(ai, bj, At, Bt) do { __builtin_amdgcn_s_setprio(1); _Pragma("unroll") for (int m = 0; m < 4; ++m) _Pragma("unroll") for (int n = 0; n < 2; ++n) _Pragma("unroll") for (int k = 0; k < 2; ++k) \
;         acc[ai][bj][m][n] = __builtin_amdgcn_mfma_f32_16x16x32_bf16(Bt[n][k], At[m][k], acc[ai][bj][m][n], 0, 0, 0); __builtin_amdgcn_s_setprio(0); } while (0)
; #define PG8_WAIT_V(n) asm volatile("s_waitcnt vmcnt(" #n ")" ::: "memory")
; #define PG8_WAIT_L(n) asm volatile("s_waitcnt lgkmcnt(" #n ")" ::: "memory")
; #define PG8_BAR __builtin_amdgcn_s_barrier()
; #define PG8_SCHED __builtin_amdgcn_sched_barrier(0)
; template <class Epi, class Sched, bool ALIGN_EPI, bool SP2>
; __device__ __forceinline__ void gemm_phase(PG8_LAS unsigned char* lds, const Gemm g, const Sched& S, const Epi& E, int wid) {
;     ...
;         for (int t = 0; t < nt; t += 2) {
;             const bool last = (t == nt - 2);
;             const char* a1 = cA + (size_t)(t + 1) * kstep;
;             const char* a2 = last ? nA : cA + (size_t)(t + 2) * kstep; const char* b2 = last ? nB : cB + (size_t)(t + 2) * kstep;
;             const char* a3 = a2 + kstep; const char* b3 = b2 + kstep;
;     ...
;             PG8_LDA(At, 1, 1); PG8_STAGE(PG8_SB(1, 0), b3, voffB); PG8_STAGE(PG8_SB(1, 1), b3 + hstepB, voffB); PG8_STAGE(PG8_SA(1, 0), a3, voffA);
;             PG8_WAIT_V(8); PG8_WAIT_L(0); PG8_BAR; PG8_MMA(1, 0, At, B0); PG8_MMA(1, 1, At, B1); PG8_BAR; PG8_SCHED;
	s_add_i32 s42, s69, s33
	v_lshl_add_u64 v[198:199], v[198:199], 0, s[6:7]
	s_mov_b32 m0, s42
	ds_read_b128 v[160:163], v241 offset:52224
	ds_read_b128 v[164:167], v241 offset:52288
	ds_read_b128 v[168:171], v241 offset:54400
	ds_read_b128 v[172:175], v241 offset:54464
	ds_read_b128 v[176:179], v241 offset:56576
	ds_read_b128 v[180:183], v241 offset:56640
	ds_read_b128 v[184:187], v241 offset:58752
	ds_read_b128 v[188:191], v241 offset:58816
	global_load_lds_dwordx4 v[198:199], off
	s_add_i32 m0, s42, 0x2200
	s_add_u32 s40, s40, 0xb0080
	v_lshl_add_u64 v[198:199], v[200:201], 0, s[6:7]
	s_addc_u32 s41, s41, 0
	s_add_i32 s42, s74, s33
	global_load_lds_dwordx4 v[198:199], off
	v_lshl_add_u64 v[198:199], s[40:41], 0, v[208:209]
	s_mov_b32 m0, s42
	s_nop 0
	global_load_lds_dwordx4 v[198:199], off
	v_lshl_add_u64 v[198:199], s[40:41], 0, v[210:211]
	s_add_i32 m0, s42, 0x2200
	s_nop 0
	global_load_lds_dwordx4 v[198:199], off
	v_lshl_add_u64 v[198:199], v[216:217], 0, s[6:7]
	s_mov_b32 m0, s57
	s_nop 0
	global_load_lds_dwordx4 v[198:199], off
	v_lshl_add_u64 v[198:199], v[218:219], 0, s[6:7]
	s_mov_b32 m0, s70
	s_nop 0
	global_load_lds_dwordx4 v[198:199], off
	s_add_i32 s68, s68, 2
	s_add_u32 s38, s38, 0x100
	s_addc_u32 s39, s39, 0
	s_add_u32 s26, s26, 0x100
	s_addc_u32 s27, s27, 0
	s_waitcnt vmcnt(8)
	s_waitcnt lgkmcnt(0)
	s_barrier
	s_setprio 1
	s_waitcnt lgkmcnt(0)
	v_mfma_f32_16x16x32_bf16 v[76:79], v[48:51], v[160:163], v[76:79]
	v_mfma_f32_16x16x32_bf16 v[72:75], v[64:67], v[160:163], v[72:75]
	v_mfma_f32_16x16x32_bf16 v[60:63], v[48:51], v[168:171], v[60:63]
	v_mfma_f32_16x16x32_bf16 v[56:59], v[64:67], v[168:171], v[56:59]
	v_mfma_f32_16x16x32_bf16 v[24:27], v[48:51], v[176:179], v[24:27]
	v_mfma_f32_16x16x32_bf16 v[28:31], v[64:67], v[176:179], v[28:31]
	v_mfma_f32_16x16x32_bf16 v[8:11], v[48:51], v[184:187], v[8:11]
	v_mfma_f32_16x16x32_bf16 v[12:15], v[64:67], v[184:187], v[12:15]
	v_mfma_f32_16x16x32_bf16 v[76:79], v[52:55], v[164:167], v[76:79]
	v_mfma_f32_16x16x32_bf16 v[72:75], v[68:71], v[164:167], v[72:75]
	v_mfma_f32_16x16x32_bf16 v[60:63], v[52:55], v[172:175], v[60:63]
	v_mfma_f32_16x16x32_bf16 v[56:59], v[68:71], v[172:175], v[56:59]
	v_mfma_f32_16x16x32_bf16 v[24:27], v[52:55], v[180:183], v[24:27]
	v_mfma_f32_16x16x32_bf16 v[28:31], v[68:71], v[180:183], v[28:31]
	v_mfma_f32_16x16x32_bf16 v[8:11], v[52:55], v[188:191], v[8:11]
	v_mfma_f32_16x16x32_bf16 v[12:15], v[68:71], v[188:191], v[12:15]
	s_setprio 0
	s_setprio 1
	v_mfma_f32_16x16x32_bf16 v[40:43], v[144:147], v[160:163], v[40:43]
	v_mfma_f32_16x16x32_bf16 v[68:71], v[148:151], v[164:167], v[40:43]
	v_mfma_f32_16x16x32_bf16 v[40:43], v[152:155], v[160:163], v[44:47]
	v_mfma_f32_16x16x32_bf16 v[36:39], v[144:147], v[168:171], v[36:39]
	v_mfma_f32_16x16x32_bf16 v[32:35], v[152:155], v[168:171], v[32:35]
	v_mfma_f32_16x16x32_bf16 v[20:23], v[144:147], v[176:179], v[20:23]
	v_mfma_f32_16x16x32_bf16 v[16:19], v[152:155], v[176:179], v[16:19]
	v_mfma_f32_16x16x32_bf16 v[4:7], v[144:147], v[184:187], v[4:7]
	v_mfma_f32_16x16x32_bf16 v[0:3], v[152:155], v[184:187], v[0:3]
	v_mfma_f32_16x16x32_bf16 v[64:67], v[156:159], v[164:167], v[40:43]
	v_mfma_f32_16x16x32_bf16 v[36:39], v[148:151], v[172:175], v[36:39]
	v_mfma_f32_16x16x32_bf16 v[32:35], v[156:159], v[172:175], v[32:35]
	v_mfma_f32_16x16x32_bf16 v[20:23], v[148:151], v[180:183], v[20:23]
	v_mfma_f32_16x16x32_bf16 v[16:19], v[156:159], v[180:183], v[16:19]
	v_mfma_f32_16x16x32_bf16 v[4:7], v[148:151], v[188:191], v[4:7]
	v_mfma_f32_16x16x32_bf16 v[0:3], v[156:159], v[188:191], v[0:3]
	s_setprio 0
	s_barrier
	s_cmp_gt_u32 s68, 41
	s_cbranch_scc0 .LBB0_290
	s_and_b64 vcc, exec, s[20:21]
	s_cbranch_vccz .LBB0_293
	s_barrier

; #define PG8_STAGE(bufoff, gbase, voff) do { _Pragma("unroll") for (int _i = 0; _i < 2; ++_i) \
;         __builtin_amdgcn_global_load_lds((const unsigned*)((const char*)(gbase) + (voff)[_i]), (PG8_LAS unsigned*)(lds + (bufoff) + ldsw + _i * (8 * USTR)), 16, 0, 0); } while (0)
; #define PG8_LDA(dst, b, h) do { _Pragma("unroll") for (int m = 0; m < 4; ++m) _Pragma("unroll") for (int k = 0; k < 2; ++k) dst[m][k] = *(const PG8_LAS bf16x8*)(lds + PG8_SA(b, h) + aoff + m * (2 * USTR) + k * 64); } while (0)
; #define PG8_LDB(dst, b, h) do { _Pragma("unroll") for (int n = 0; n < 2; ++n) _Pragma("unroll") for (int k = 0; k < 2; ++k) dst[n][k] = *(const PG8_LAS bf16x8*)(lds + PG8_SB(b, h) + boff + n * (2 * USTR) + k * 64); } while (0)
; #define PG8_MMA(ai, bj, At, Bt) do { __builtin_amdgcn_s_setprio(1); _Pragma("unroll") for (int m = 0; m < 4; ++m) _Pragma("unroll") for (int n = 0; n < 2; ++n) _Pragma("unroll") for (int k = 0; k < 2; ++k) \
;         acc[ai][bj][m][n] = __builtin_amdgcn_mfma_f32_16x16x32_bf16(Bt[n][k], At[m][k], acc[ai][bj][m][n], 0, 0, 0); __builtin_amdgcn_s_setprio(0); } while (0)
; template <class Epi, class Sched, bool ALIGN_EPI, bool SP2>
; __device__ __forceinline__ void gemm_phase(PG8_LAS unsigned char* lds, const Gemm g, const Sched& S, const Epi& E, int wid) {
;     ...
;         const bool has_next = S.next(ui + 1, nxt);
;         const char* nA = has_next ? (const char*)g.A + (size_t)nxt.pm * tstepA : cA; const char* nB = has_next ? (const char*)g.Bt + (size_t)nxt.pn * tstepB : cB;
;         for (int t = 0; t < nt; t += 2) {
;             const bool last = (t == nt - 2);
;             const char* a1 = cA + (size_t)(t + 1) * kstep;
;             const char* a2 = last ? nA : cA + (size_t)(t + 2) * kstep; const char* b2 = last ? nB : cB + (size_t)(t + 2) * kstep;
;             const char* a3 = a2 + kstep; const char* b3 = b2 + kstep;
;     ...
;             PG8_LDB(B0, 0, 0); PG8_LDB(B1, 0, 1); PG8_SCHED; PG8_LDA(At, 0, 0); PG8_STAGE(PG8_SA(1, 1), a1 + hstepA, voffA);
;             PG8_WAIT_V(8); PG8_WAIT_L(0); PG8_BAR; PG8_MMA(0, 0, At, B0); PG8_MMA(0, 1, At, B1); PG8_BAR; PG8_SCHED;
;             PG8_LDA(At, 0, 1); PG8_STAGE(PG8_SB(0, 0), b2, voffB); PG8_STAGE(PG8_SB(0, 1), b2 + hstepB, voffB); PG8_STAGE(PG8_SA(0, 0), a2, voffA);
;             PG8_WAIT_V(8); PG8_WAIT_L(0); PG8_BAR; PG8_MMA(1, 0, At, B0); PG8_MMA(1, 1, At, B1); PG8_BAR; PG8_SCHED;
.Lhb_up:
	s_add_i32 s77, 0, 0x11000
	v_add_u32_e32 v94, s77, v161
	s_add_i32 s89, 0, 0x15400
	ds_read_b128 v[86:89], v94
	ds_read_b128 v[90:93], v94 offset:64
	ds_read_b128 v[164:167], v94 offset:2176
	ds_read_b128 v[168:171], v94 offset:2240
	v_add_u32_e32 v94, s89, v161
	ds_read_b128 v[172:175], v94
	ds_read_b128 v[176:179], v94 offset:64
	ds_read_b128 v[180:183], v94 offset:2176
	ds_read_b128 v[184:187], v94 offset:2240
	v_lshl_add_u64 v[94:95], s[38:39], 0, v[154:155]
	s_add_i32 m0, s0, 0xcc00
	ds_read_b128 v[188:191], v163
	ds_read_b128 v[208:211], v163 offset:64
	ds_read_b128 v[212:215], v163 offset:2176
	ds_read_b128 v[216:219], v163 offset:2240
	ds_read_b128 v[220:223], v163 offset:4352
	ds_read_b128 v[224:227], v163 offset:4416
	ds_read_b128 v[228:231], v163 offset:6528
	ds_read_b128 v[242:245], v163 offset:6592
	global_load_lds_dwordx4 v[94:95], off
	v_lshl_add_u64 v[94:95], s[38:39], 0, v[156:157]
	s_add_i32 m0, s0, 0xee00
	s_nop 0
	global_load_lds_dwordx4 v[94:95], off
	s_cmp_eq_u32 s76, 12
	s_cselect_b64 s[68:69], -1, 0
	s_add_u32 s70, s38, 0xfffc0080
	s_addc_u32 s71, s39, -1
	s_and_b64 s[68:69], s[68:69], exec
	s_cselect_b32 s71, s26, s71
	s_cselect_b32 s70, s27, s70
	s_cselect_b32 s69, s41, s75
	s_cselect_b32 s68, s73, s74
	s_waitcnt vmcnt(8)
	s_waitcnt lgkmcnt(0)
	s_barrier
	s_setprio 1
	s_waitcnt lgkmcnt(0)
	v_mfma_f32_16x16x32_bf16 v[140:143], v[86:89], v[188:191], 0
	v_mfma_f32_16x16x32_bf16 v[136:139], v[164:167], v[188:191], 0
	v_mfma_f32_16x16x32_bf16 v[124:127], v[86:89], v[212:215], 0
	v_mfma_f32_16x16x32_bf16 v[120:123], v[164:167], v[212:215], 0
	v_mfma_f32_16x16x32_bf16 v[108:111], v[86:89], v[220:223], 0
	v_mfma_f32_16x16x32_bf16 v[104:107], v[164:167], v[220:223], 0
	v_mfma_f32_16x16x32_bf16 v[76:79], v[86:89], v[228:231], 0
	v_mfma_f32_16x16x32_bf16 v[72:75], v[164:167], v[228:231], 0
	v_mfma_f32_16x16x32_bf16 v[140:143], v[90:93], v[208:211], v[140:143]
	v_mfma_f32_16x16x32_bf16 v[136:139], v[168:171], v[208:211], v[136:139]
	v_mfma_f32_16x16x32_bf16 v[124:127], v[90:93], v[216:219], v[124:127]
	v_mfma_f32_16x16x32_bf16 v[120:123], v[168:171], v[216:219], v[120:123]
	v_mfma_f32_16x16x32_bf16 v[108:111], v[90:93], v[224:227], v[108:111]
	v_mfma_f32_16x16x32_bf16 v[104:107], v[168:171], v[224:227], v[104:107]
	v_mfma_f32_16x16x32_bf16 v[76:79], v[90:93], v[242:245], v[76:79]
	v_mfma_f32_16x16x32_bf16 v[72:75], v[168:171], v[242:245], v[72:75]
	s_setprio 0
	s_setprio 1
	v_mfma_f32_16x16x32_bf16 v[132:135], v[172:175], v[188:191], 0
	v_mfma_f32_16x16x32_bf16 v[128:131], v[180:183], v[188:191], 0
	v_mfma_f32_16x16x32_bf16 v[116:119], v[172:175], v[212:215], 0
	v_mfma_f32_16x16x32_bf16 v[112:115], v[180:183], v[212:215], 0
	v_mfma_f32_16x16x32_bf16 v[100:103], v[172:175], v[220:223], 0
	v_mfma_f32_16x16x32_bf16 v[94:97], v[180:183], v[220:223], 0
	v_mfma_f32_16x16x32_bf16 v[68:71], v[172:175], v[228:231], 0
	v_mfma_f32_16x16x32_bf16 v[64:67], v[180:183], v[228:231], 0
	v_mfma_f32_16x16x32_bf16 v[132:135], v[176:179], v[208:211], v[132:135]
	v_mfma_f32_16x16x32_bf16 v[128:131], v[184:187], v[208:211], v[128:131]
	v_mfma_f32_16x16x32_bf16 v[116:119], v[176:179], v[216:219], v[116:119]
	v_mfma_f32_16x16x32_bf16 v[112:115], v[184:187], v[216:219], v[112:115]
	v_mfma_f32_16x16x32_bf16 v[100:103], v[176:179], v[224:227], v[100:103]
	v_mfma_f32_16x16x32_bf16 v[94:97], v[184:187], v[224:227], v[94:97]
	v_mfma_f32_16x16x32_bf16 v[68:71], v[176:179], v[242:245], v[68:71]
	v_mfma_f32_16x16x32_bf16 v[64:67], v[184:187], v[242:245], v[64:67]
	s_setprio 0
	s_barrier
	s_add_i32 s77, s77, s33
	v_lshl_add_u64 v[158:159], s[68:69], 0, v[192:193]
	s_mov_b32 m0, s77
	ds_read_b128 v[188:191], v163 offset:17408
	ds_read_b128 v[208:211], v163 offset:17472
	ds_read_b128 v[212:215], v163 offset:19584
	ds_read_b128 v[216:219], v163 offset:19648
	ds_read_b128 v[220:223], v163 offset:21760
	ds_read_b128 v[224:227], v163 offset:21824
	ds_read_b128 v[228:231], v163 offset:23936
	ds_read_b128 v[242:245], v163 offset:24000
	global_load_lds_dwordx4 v[158:159], off
	s_add_i32 m0, s77, 0x2200
	s_add_u32 s78, s68, 0x40000
	v_lshl_add_u64 v[198:199], s[68:69], 0, v[144:145]
	s_addc_u32 s79, s69, 0
	s_add_i32 s77, s89, s33
	global_load_lds_dwordx4 v[198:199], off
	v_lshl_add_u64 v[98:99], s[78:79], 0, v[192:193]
	s_mov_b32 m0, s77
	v_lshl_add_u64 v[200:201], s[70:71], 0, v[148:149]
	global_load_lds_dwordx4 v[98:99], off
	v_lshl_add_u64 v[98:99], s[78:79], 0, v[144:145]
	s_add_i32 m0, s77, 0x2200
	v_lshl_add_u64 v[232:233], s[70:71], 0, v[146:147]
	global_load_lds_dwordx4 v[98:99], off
	s_mov_b32 m0, s0
	s_nop 0
	global_load_lds_dwordx4 v[200:201], off
	s_mov_b32 m0, s5
	s_nop 0
	global_load_lds_dwordx4 v[232:233], off
	s_waitcnt vmcnt(8)
	s_waitcnt lgkmcnt(0)
	s_barrier
; #define PG8_STAGE(bufoff, gbase, voff) do { _Pragma("unroll") for (int _i = 0; _i < 2; ++_i) \
;         __builtin_amdgcn_global_load_lds((const unsigned*)((const char*)(gbase) + (voff)[_i]), (PG8_LAS unsigned*)(lds + (bufoff) + ldsw + _i * (8 * USTR)), 16, 0, 0); } while (0)
; #define PG8_LDA(dst, b, h) do { _Pragma("unroll") for (int m = 0; m < 4; ++m) _Pragma("unroll") for (int k = 0; k < 2; ++k) dst[m][k] = *(const PG8_LAS bf16x8*)(lds + PG8_SA(b, h) + aoff + m * (2 * USTR) + k * 64); } while (0)
; #define PG8_LDB(dst, b, h) do { _Pragma("unroll") for (int n = 0; n < 2; ++n) _Pragma("unroll") for (int k = 0; k < 2; ++k) dst[n][k] = *(const PG8_LAS bf16x8*)(lds + PG8_SB(b, h) + boff + n * (2 * USTR) + k * 64); } while (0)
; #define PG8_MMA(ai, bj, At, Bt) do { __builtin_amdgcn_s_setprio(1); _Pragma("unroll") for (int m = 0; m < 4; ++m) _Pragma("unroll") for (int n = 0; n < 2; ++n) _Pragma("unroll") for (int k = 0; k < 2; ++k) \
;         acc[ai][bj][m][n] = __builtin_amdgcn_mfma_f32_16x16x32_bf16(Bt[n][k], At[m][k], acc[ai][bj][m][n], 0, 0, 0); __builtin_amdgcn_s_setprio(0); } while (0)
; #define PG8_WAIT_V(n) asm volatile("s_waitcnt vmcnt(" #n ")" ::: "memory")
; #define PG8_WAIT_L(n) asm volatile("s_waitcnt lgkmcnt(" #n ")" ::: "memory")
; #define PG8_BAR __builtin_amdgcn_s_barrier()
; #define PG8_SCHED __builtin_amdgcn_sched_barrier(0)
; template <class Epi, class Sched, bool ALIGN_EPI, bool SP2>
; __device__ __forceinline__ void gemm_phase(PG8_LAS unsigned char* lds, const Gemm g, const Sched& S, const Epi& E, int wid) {
;     ...
;             PG8_WAIT_V(8); PG8_WAIT_L(0); PG8_BAR; PG8_MMA(1, 0, At, B0); PG8_MMA(1, 1, At, B1); PG8_BAR; PG8_SCHED;
;             PG8_LDB(B0, 1, 0); PG8_LDB(B1, 1, 1); PG8_SCHED; PG8_LDA(At, 1, 0); PG8_STAGE(PG8_SA(0, 1), a2 + hstepA, voffA);
;             PG8_WAIT_V(8); PG8_WAIT_L(0); PG8_BAR; PG8_MMA(0, 0, At, B0); PG8_MMA(0, 1, At, B1); PG8_BAR; PG8_SCHED;
	s_setprio 1
	s_waitcnt lgkmcnt(0)
	v_mfma_f32_16x16x32_bf16 v[60:63], v[86:89], v[188:191], 0
	v_mfma_f32_16x16x32_bf16 v[56:59], v[164:167], v[188:191], 0
	v_mfma_f32_16x16x32_bf16 v[44:47], v[86:89], v[212:215], 0
	v_mfma_f32_16x16x32_bf16 v[40:43], v[164:167], v[212:215], 0
	v_mfma_f32_16x16x32_bf16 v[28:31], v[86:89], v[220:223], 0
	v_mfma_f32_16x16x32_bf16 v[24:27], v[164:167], v[220:223], 0
	v_mfma_f32_16x16x32_bf16 v[12:15], v[86:89], v[228:231], 0
	v_mfma_f32_16x16x32_bf16 v[8:11], v[164:167], v[228:231], 0
	v_mfma_f32_16x16x32_bf16 v[60:63], v[90:93], v[208:211], v[60:63]
	v_mfma_f32_16x16x32_bf16 v[56:59], v[168:171], v[208:211], v[56:59]
	v_mfma_f32_16x16x32_bf16 v[44:47], v[90:93], v[216:219], v[44:47]
	v_mfma_f32_16x16x32_bf16 v[40:43], v[168:171], v[216:219], v[40:43]
	v_mfma_f32_16x16x32_bf16 v[28:31], v[90:93], v[224:227], v[28:31]
	v_mfma_f32_16x16x32_bf16 v[24:27], v[168:171], v[224:227], v[24:27]
	v_mfma_f32_16x16x32_bf16 v[12:15], v[90:93], v[242:245], v[12:15]
	v_mfma_f32_16x16x32_bf16 v[8:11], v[168:171], v[242:245], v[8:11]
	s_setprio 0
	s_setprio 1
	v_mfma_f32_16x16x32_bf16 v[52:55], v[172:175], v[188:191], 0
	v_mfma_f32_16x16x32_bf16 v[48:51], v[180:183], v[188:191], 0
	v_mfma_f32_16x16x32_bf16 v[36:39], v[172:175], v[212:215], 0
	v_mfma_f32_16x16x32_bf16 v[32:35], v[180:183], v[212:215], 0
	v_mfma_f32_16x16x32_bf16 v[20:23], v[172:175], v[220:223], 0
	v_mfma_f32_16x16x32_bf16 v[16:19], v[180:183], v[220:223], 0
	v_mfma_f32_16x16x32_bf16 v[4:7], v[172:175], v[228:231], 0
	v_mfma_f32_16x16x32_bf16 v[0:3], v[180:183], v[228:231], 0
	v_mfma_f32_16x16x32_bf16 v[52:55], v[176:179], v[208:211], v[52:55]
	v_mfma_f32_16x16x32_bf16 v[48:51], v[184:187], v[208:211], v[48:51]
	v_mfma_f32_16x16x32_bf16 v[36:39], v[176:179], v[216:219], v[36:39]
	v_mfma_f32_16x16x32_bf16 v[32:35], v[184:187], v[216:219], v[32:35]
	v_mfma_f32_16x16x32_bf16 v[20:23], v[176:179], v[224:227], v[20:23]
	v_mfma_f32_16x16x32_bf16 v[16:19], v[184:187], v[224:227], v[16:19]
	v_mfma_f32_16x16x32_bf16 v[4:7], v[176:179], v[242:245], v[4:7]
	v_mfma_f32_16x16x32_bf16 v[0:3], v[184:187], v[242:245], v[0:3]
	s_setprio 0
	s_barrier
	s_add_i32 s77, 0, 0x19800
	v_add_u32_e32 v98, s77, v161
	s_add_i32 s78, 0, 0x1dc00
	ds_read_b128 v[86:89], v98
	ds_read_b128 v[90:93], v98 offset:64
	ds_read_b128 v[164:167], v98 offset:2176
	ds_read_b128 v[168:171], v98 offset:2240
	v_add_u32_e32 v98, s78, v161
	ds_read_b128 v[172:175], v98
	ds_read_b128 v[176:179], v98 offset:64
	ds_read_b128 v[180:183], v98 offset:2176
	ds_read_b128 v[184:187], v98 offset:2240
	s_add_u32 s70, s70, 0x40000
	s_addc_u32 s71, s71, 0
	s_mov_b32 m0, s10
	v_lshl_add_u64 v[98:99], s[70:71], 0, v[148:149]
	ds_read_b128 v[188:191], v163 offset:34816
	ds_read_b128 v[208:211], v163 offset:34880
	ds_read_b128 v[212:215], v163 offset:36992
	ds_read_b128 v[216:219], v163 offset:37056
	ds_read_b128 v[220:223], v163 offset:39168
	ds_read_b128 v[224:227], v163 offset:39232
	ds_read_b128 v[228:231], v163 offset:41344
	ds_read_b128 v[242:245], v163 offset:41408
	global_load_lds_dwordx4 v[98:99], off
	v_lshl_add_u64 v[98:99], s[70:71], 0, v[146:147]
	s_mov_b32 m0, s29
	s_nop 0
	global_load_lds_dwordx4 v[98:99], off
	s_waitcnt vmcnt(8)
	s_waitcnt lgkmcnt(0)
	s_barrier
	s_setprio 1
	s_waitcnt lgkmcnt(0)
	v_mfma_f32_16x16x32_bf16 v[140:143], v[86:89], v[188:191], v[140:143]
	v_mfma_f32_16x16x32_bf16 v[136:139], v[164:167], v[188:191], v[136:139]
	v_mfma_f32_16x16x32_bf16 v[124:127], v[86:89], v[212:215], v[124:127]
	v_mfma_f32_16x16x32_bf16 v[120:123], v[164:167], v[212:215], v[120:123]
	v_mfma_f32_16x16x32_bf16 v[108:111], v[86:89], v[220:223], v[108:111]
	v_mfma_f32_16x16x32_bf16 v[104:107], v[164:167], v[220:223], v[104:107]
	v_mfma_f32_16x16x32_bf16 v[76:79], v[86:89], v[228:231], v[76:79]
	v_mfma_f32_16x16x32_bf16 v[72:75], v[164:167], v[228:231], v[72:75]
	v_mfma_f32_16x16x32_bf16 v[140:143], v[90:93], v[208:211], v[140:143]
	v_mfma_f32_16x16x32_bf16 v[136:139], v[168:171], v[208:211], v[136:139]
	v_mfma_f32_16x16x32_bf16 v[124:127], v[90:93], v[216:219], v[124:127]
	v_mfma_f32_16x16x32_bf16 v[120:123], v[168:171], v[216:219], v[120:123]
	v_mfma_f32_16x16x32_bf16 v[108:111], v[90:93], v[224:227], v[108:111]
	v_mfma_f32_16x16x32_bf16 v[104:107], v[168:171], v[224:227], v[104:107]
	v_mfma_f32_16x16x32_bf16 v[76:79], v[90:93], v[242:245], v[76:79]
	v_mfma_f32_16x16x32_bf16 v[72:75], v[168:171], v[242:245], v[72:75]
	s_setprio 0
	s_setprio 1
	v_mfma_f32_16x16x32_bf16 v[132:135], v[172:175], v[188:191], v[132:135]
	v_mfma_f32_16x16x32_bf16 v[128:131], v[180:183], v[188:191], v[128:131]
	v_mfma_f32_16x16x32_bf16 v[116:119], v[172:175], v[212:215], v[116:119]
	v_mfma_f32_16x16x32_bf16 v[112:115], v[180:183], v[212:215], v[112:115]
	v_mfma_f32_16x16x32_bf16 v[98:101], v[172:175], v[220:223], v[100:103]
	v_mfma_f32_16x16x32_bf16 v[94:97], v[180:183], v[220:223], v[94:97]
	v_mfma_f32_16x16x32_bf16 v[68:71], v[172:175], v[228:231], v[68:71]
	v_mfma_f32_16x16x32_bf16 v[64:67], v[180:183], v[228:231], v[64:67]
	v_mfma_f32_16x16x32_bf16 v[132:135], v[176:179], v[208:211], v[132:135]
	v_mfma_f32_16x16x32_bf16 v[128:131], v[184:187], v[208:211], v[128:131]
	v_mfma_f32_16x16x32_bf16 v[116:119], v[176:179], v[216:219], v[116:119]
	v_mfma_f32_16x16x32_bf16 v[112:115], v[184:187], v[216:219], v[112:115]
	v_mfma_f32_16x16x32_bf16 v[100:103], v[176:179], v[224:227], v[98:101]
	v_mfma_f32_16x16x32_bf16 v[96:99], v[184:187], v[224:227], v[94:97]
	v_mfma_f32_16x16x32_bf16 v[68:71], v[176:179], v[242:245], v[68:71]
	v_mfma_f32_16x16x32_bf16 v[64:67], v[184:187], v[242:245], v[64:67]
	s_setprio 0
	s_barrier
; #define PG8_STAGE(bufoff, gbase, voff) do { _Pragma("unroll") for (int _i = 0; _i < 2; ++_i) \
;         __builtin_amdgcn_global_load_lds((const unsigned*)((const char*)(gbase) + (voff)[_i]), (PG8_LAS unsigned*)(lds + (bufoff) + ldsw + _i * (8 * USTR)), 16, 0, 0); } while (0)
; #define PG8_LDA(dst, b, h) do { _Pragma("unroll") for (int m = 0; m < 4; ++m) _Pragma("unroll") for (int k = 0; k < 2; ++k) dst[m][k] = *(const PG8_LAS bf16x8*)(lds + PG8_SA(b, h) + aoff + m * (2 * USTR) + k * 64); } while (0)
; #define PG8_LDB(dst, b, h) do { _Pragma("unroll") for (int n = 0; n < 2; ++n) _Pragma("unroll") for (int k = 0; k < 2; ++k) dst[n][k] = *(const PG8_LAS bf16x8*)(lds + PG8_SB(b, h) + boff + n * (2 * USTR) + k * 64); } while (0)
; #define PG8_MMA(ai, bj, At, Bt) do { __builtin_amdgcn_s_setprio(1); _Pragma("unroll") for (int m = 0; m < 4; ++m) _Pragma("unroll") for (int n = 0; n < 2; ++n) _Pragma("unroll") for (int k = 0; k < 2; ++k) \
;         acc[ai][bj][m][n] = __builtin_amdgcn_mfma_f32_16x16x32_bf16(Bt[n][k], At[m][k], acc[ai][bj][m][n], 0, 0, 0); __builtin_amdgcn_s_setprio(0); } while (0)
; #define PG8_BAR __builtin_amdgcn_s_barrier()
; template <class Epi, class Sched, bool ALIGN_EPI, bool SP2>
; __device__ __forceinline__ void gemm_phase(PG8_LAS unsigned char* lds, const Gemm g, const Sched& S, const Epi& E, int wid) {
;     ...
;             PG8_LDB(B0, 0, 0); PG8_LDB(B1, 0, 1); PG8_SCHED; PG8_LDA(At, 0, 0); PG8_STAGE(PG8_SA(1, 1), a1 + hstepA, voffA);
;             PG8_WAIT_V(8); PG8_WAIT_L(0); PG8_BAR; PG8_MMA(0, 0, At, B0); PG8_MMA(0, 1, At, B1); PG8_BAR; PG8_SCHED;
;             PG8_LDA(At, 0, 1); PG8_STAGE(PG8_SB(0, 0), b2, voffB); PG8_STAGE(PG8_SB(0, 1), b2 + hstepB, voffB); PG8_STAGE(PG8_SA(0, 0), a2, voffA);
;             PG8_WAIT_V(8); PG8_WAIT_L(0); PG8_BAR; PG8_MMA(1, 0, At, B0); PG8_MMA(1, 1, At, B1); PG8_BAR; PG8_SCHED;
;             PG8_LDB(B0, 1, 0); PG8_LDB(B1, 1, 1); PG8_SCHED; PG8_LDA(At, 1, 0); PG8_STAGE(PG8_SA(0, 1), a2 + hstepA, voffA);
;             PG8_WAIT_V(8); PG8_WAIT_L(0); PG8_BAR; PG8_MMA(0, 0, At, B0); PG8_MMA(0, 1, At, B1); PG8_BAR; PG8_SCHED;
;             PG8_LDA(At, 1, 1); PG8_STAGE(PG8_SB(1, 0), b3, voffB); PG8_STAGE(PG8_SB(1, 1), b3 + hstepB, voffB); PG8_STAGE(PG8_SA(1, 0), a3, voffA);
;             PG8_WAIT_V(8); PG8_WAIT_L(0); PG8_BAR; PG8_MMA(1, 0, At, B0); PG8_MMA(1, 1, At, B1); PG8_BAR; PG8_SCHED;
	s_add_i32 s70, s77, s33
	v_lshl_add_u64 v[94:95], v[158:159], 0, s[6:7]
	s_mov_b32 m0, s70
	ds_read_b128 v[188:191], v163 offset:52224
	ds_read_b128 v[208:211], v163 offset:52288
	ds_read_b128 v[212:215], v163 offset:54400
	ds_read_b128 v[216:219], v163 offset:54464
	ds_read_b128 v[220:223], v163 offset:56576
	ds_read_b128 v[224:227], v163 offset:56640
	ds_read_b128 v[228:231], v163 offset:58752
	ds_read_b128 v[242:245], v163 offset:58816
	global_load_lds_dwordx4 v[94:95], off
	s_add_i32 m0, s70, 0x2200
	s_add_u32 s68, s68, 0x40080
	v_lshl_add_u64 v[94:95], v[198:199], 0, s[6:7]
	s_addc_u32 s69, s69, 0
	s_add_i32 s70, s78, s33
	global_load_lds_dwordx4 v[94:95], off
	v_lshl_add_u64 v[94:95], s[68:69], 0, v[192:193]
	s_mov_b32 m0, s70
	s_nop 0
	global_load_lds_dwordx4 v[94:95], off
	v_lshl_add_u64 v[94:95], s[68:69], 0, v[144:145]
	s_add_i32 m0, s70, 0x2200
	s_nop 0
	global_load_lds_dwordx4 v[94:95], off
	v_lshl_add_u64 v[94:95], v[200:201], 0, s[6:7]
	s_mov_b32 m0, s56
	s_nop 0
	global_load_lds_dwordx4 v[94:95], off
	v_lshl_add_u64 v[94:95], v[232:233], 0, s[6:7]
	s_mov_b32 m0, s57
	s_nop 0
	global_load_lds_dwordx4 v[94:95], off
	s_add_i32 s76, s76, 2
	s_add_u32 s38, s38, 0x100
	s_addc_u32 s39, s39, 0
	s_add_u32 s74, s74, 0x100
	s_addc_u32 s75, s75, 0
	s_waitcnt vmcnt(8)
	s_waitcnt lgkmcnt(0)
	s_barrier
	s_setprio 1
	s_waitcnt lgkmcnt(0)
	v_mfma_f32_16x16x32_bf16 v[60:63], v[86:89], v[188:191], v[60:63]
	v_mfma_f32_16x16x32_bf16 v[56:59], v[164:167], v[188:191], v[56:59]
	v_mfma_f32_16x16x32_bf16 v[44:47], v[86:89], v[212:215], v[44:47]
	v_mfma_f32_16x16x32_bf16 v[40:43], v[164:167], v[212:215], v[40:43]
	v_mfma_f32_16x16x32_bf16 v[28:31], v[86:89], v[220:223], v[28:31]
	v_mfma_f32_16x16x32_bf16 v[24:27], v[164:167], v[220:223], v[24:27]
	v_mfma_f32_16x16x32_bf16 v[12:15], v[86:89], v[228:231], v[12:15]
	v_mfma_f32_16x16x32_bf16 v[8:11], v[164:167], v[228:231], v[8:11]
	v_mfma_f32_16x16x32_bf16 v[60:63], v[90:93], v[208:211], v[60:63]
	v_mfma_f32_16x16x32_bf16 v[56:59], v[168:171], v[208:211], v[56:59]
	v_mfma_f32_16x16x32_bf16 v[44:47], v[90:93], v[216:219], v[44:47]
	v_mfma_f32_16x16x32_bf16 v[40:43], v[168:171], v[216:219], v[40:43]
	v_mfma_f32_16x16x32_bf16 v[28:31], v[90:93], v[224:227], v[28:31]
	v_mfma_f32_16x16x32_bf16 v[24:27], v[168:171], v[224:227], v[24:27]
	v_mfma_f32_16x16x32_bf16 v[12:15], v[90:93], v[242:245], v[12:15]
	v_mfma_f32_16x16x32_bf16 v[8:11], v[168:171], v[242:245], v[8:11]
	s_setprio 0
	s_setprio 1
	v_mfma_f32_16x16x32_bf16 v[52:55], v[172:175], v[188:191], v[52:55]
	v_mfma_f32_16x16x32_bf16 v[48:51], v[180:183], v[188:191], v[48:51]
	v_mfma_f32_16x16x32_bf16 v[36:39], v[172:175], v[212:215], v[36:39]
	v_mfma_f32_16x16x32_bf16 v[32:35], v[180:183], v[212:215], v[32:35]
	v_mfma_f32_16x16x32_bf16 v[20:23], v[172:175], v[220:223], v[20:23]
	v_mfma_f32_16x16x32_bf16 v[16:19], v[180:183], v[220:223], v[16:19]
	v_mfma_f32_16x16x32_bf16 v[4:7], v[172:175], v[228:231], v[4:7]
	v_mfma_f32_16x16x32_bf16 v[0:3], v[180:183], v[228:231], v[0:3]
	v_mfma_f32_16x16x32_bf16 v[52:55], v[176:179], v[208:211], v[52:55]
	v_mfma_f32_16x16x32_bf16 v[48:51], v[184:187], v[208:211], v[48:51]
	v_mfma_f32_16x16x32_bf16 v[36:39], v[176:179], v[216:219], v[36:39]
	v_mfma_f32_16x16x32_bf16 v[32:35], v[184:187], v[216:219], v[32:35]
	v_mfma_f32_16x16x32_bf16 v[20:23], v[176:179], v[224:227], v[20:23]
	v_mfma_f32_16x16x32_bf16 v[16:19], v[184:187], v[224:227], v[16:19]
	v_mfma_f32_16x16x32_bf16 v[4:7], v[176:179], v[242:245], v[4:7]
	v_mfma_f32_16x16x32_bf16 v[0:3], v[184:187], v[242:245], v[0:3]
	s_setprio 0
	s_barrier
	s_cmp_gt_u32 s76, 13
	s_branch .LBB0_374
.LBB0_373:
	s_add_i32 s77, 0, 0x11000
	v_add_u32_e32 v94, s77, v161
	s_add_i32 s89, 0, 0x15400
	ds_read_b128 v[86:89], v94
	ds_read_b128 v[90:93], v94 offset:64
	ds_read_b128 v[164:167], v94 offset:2176
	ds_read_b128 v[168:171], v94 offset:2240
	v_add_u32_e32 v94, s89, v161
	ds_read_b128 v[172:175], v94
	ds_read_b128 v[176:179], v94 offset:64
	ds_read_b128 v[180:183], v94 offset:2176
	ds_read_b128 v[184:187], v94 offset:2240
	v_lshl_add_u64 v[94:95], s[38:39], 0, v[154:155]
	s_add_i32 m0, s0, 0xcc00
	ds_read_b128 v[188:191], v163
	ds_read_b128 v[208:211], v163 offset:64
	ds_read_b128 v[212:215], v163 offset:2176
	ds_read_b128 v[216:219], v163 offset:2240
	ds_read_b128 v[220:223], v163 offset:4352
	ds_read_b128 v[224:227], v163 offset:4416
	ds_read_b128 v[228:231], v163 offset:6528
	ds_read_b128 v[242:245], v163 offset:6592
	global_load_lds_dwordx4 v[94:95], off
	v_lshl_add_u64 v[94:95], s[38:39], 0, v[156:157]
	s_add_i32 m0, s0, 0xee00
	s_nop 0
	global_load_lds_dwordx4 v[94:95], off
	s_add_u32 s70, s38, 0xfffc0080
	s_addc_u32 s71, s39, -1
	s_and_b64 s[68:69], s[68:69], exec
	s_cselect_b32 s71, s26, s71
	s_cselect_b32 s70, s27, s70
	s_cselect_b32 s69, s41, s75
	s_cselect_b32 s68, s73, s74
	s_waitcnt vmcnt(8)
	s_waitcnt lgkmcnt(0)
	s_barrier
; #define PG8_STAGE(bufoff, gbase, voff) do { _Pragma("unroll") for (int _i = 0; _i < 2; ++_i) \
;         __builtin_amdgcn_global_load_lds((const unsigned*)((const char*)(gbase) + (voff)[_i]), (PG8_LAS unsigned*)(lds + (bufoff) + ldsw + _i * (8 * USTR)), 16, 0, 0); } while (0)
; #define PG8_LDA(dst, b, h) do { _Pragma("unroll") for (int m = 0; m < 4; ++m) _Pragma("unroll") for (int k = 0; k < 2; ++k) dst[m][k] = *(const PG8_LAS bf16x8*)(lds + PG8_SA(b, h) + aoff + m * (2 * USTR) + k * 64); } while (0)
; #define PG8_MMA(ai, bj, At, Bt) do { __builtin_amdgcn_s_setprio(1); _Pragma("unroll") for (int m = 0; m < 4; ++m) _Pragma("unroll") for (int n = 0; n < 2; ++n) _Pragma("unroll") for (int k = 0; k < 2; ++k) \
;         acc[ai][bj][m][n] = __builtin_amdgcn_mfma_f32_16x16x32_bf16(Bt[n][k], At[m][k], acc[ai][bj][m][n], 0, 0, 0); __builtin_amdgcn_s_setprio(0); } while (0)
; #define PG8_WAIT_V(n) asm volatile("s_waitcnt vmcnt(" #n ")" ::: "memory")
; #define PG8_WAIT_L(n) asm volatile("s_waitcnt lgkmcnt(" #n ")" ::: "memory")
; #define PG8_BAR __builtin_amdgcn_s_barrier()
; #define PG8_SCHED __builtin_amdgcn_sched_barrier(0)
; template <class Epi, class Sched, bool ALIGN_EPI, bool SP2>
; __device__ __forceinline__ void gemm_phase(PG8_LAS unsigned char* lds, const Gemm g, const Sched& S, const Epi& E, int wid) {
;     ...
;             PG8_WAIT_V(8); PG8_WAIT_L(0); PG8_BAR; PG8_MMA(0, 0, At, B0); PG8_MMA(0, 1, At, B1); PG8_BAR; PG8_SCHED;
;             PG8_LDA(At, 0, 1); PG8_STAGE(PG8_SB(0, 0), b2, voffB); PG8_STAGE(PG8_SB(0, 1), b2 + hstepB, voffB); PG8_STAGE(PG8_SA(0, 0), a2, voffA);
;             PG8_WAIT_V(8); PG8_WAIT_L(0); PG8_BAR; PG8_MMA(1, 0, At, B0); PG8_MMA(1, 1, At, B1); PG8_BAR; PG8_SCHED;
	s_setprio 1
	s_waitcnt lgkmcnt(0)
	v_mfma_f32_16x16x32_bf16 v[140:143], v[86:89], v[188:191], v[140:143]
	v_mfma_f32_16x16x32_bf16 v[136:139], v[164:167], v[188:191], v[136:139]
	v_mfma_f32_16x16x32_bf16 v[124:127], v[86:89], v[212:215], v[124:127]
	v_mfma_f32_16x16x32_bf16 v[120:123], v[164:167], v[212:215], v[120:123]
	v_mfma_f32_16x16x32_bf16 v[108:111], v[86:89], v[220:223], v[108:111]
	v_mfma_f32_16x16x32_bf16 v[104:107], v[164:167], v[220:223], v[104:107]
	v_mfma_f32_16x16x32_bf16 v[76:79], v[86:89], v[228:231], v[76:79]
	v_mfma_f32_16x16x32_bf16 v[72:75], v[164:167], v[228:231], v[72:75]
	v_mfma_f32_16x16x32_bf16 v[140:143], v[90:93], v[208:211], v[140:143]
	v_mfma_f32_16x16x32_bf16 v[136:139], v[168:171], v[208:211], v[136:139]
	v_mfma_f32_16x16x32_bf16 v[124:127], v[90:93], v[216:219], v[124:127]
	v_mfma_f32_16x16x32_bf16 v[120:123], v[168:171], v[216:219], v[120:123]
	v_mfma_f32_16x16x32_bf16 v[108:111], v[90:93], v[224:227], v[108:111]
	v_mfma_f32_16x16x32_bf16 v[104:107], v[168:171], v[224:227], v[104:107]
	v_mfma_f32_16x16x32_bf16 v[76:79], v[90:93], v[242:245], v[76:79]
	v_mfma_f32_16x16x32_bf16 v[72:75], v[168:171], v[242:245], v[72:75]
	s_setprio 0
	s_setprio 1
	v_mfma_f32_16x16x32_bf16 v[132:135], v[172:175], v[188:191], v[132:135]
	v_mfma_f32_16x16x32_bf16 v[128:131], v[180:183], v[188:191], v[128:131]
	v_mfma_f32_16x16x32_bf16 v[116:119], v[172:175], v[212:215], v[116:119]
	v_mfma_f32_16x16x32_bf16 v[112:115], v[180:183], v[212:215], v[112:115]
	v_mfma_f32_16x16x32_bf16 v[100:103], v[172:175], v[220:223], v[100:103]
	v_mfma_f32_16x16x32_bf16 v[94:97], v[180:183], v[220:223], v[96:99]
	v_mfma_f32_16x16x32_bf16 v[68:71], v[172:175], v[228:231], v[68:71]
	v_mfma_f32_16x16x32_bf16 v[64:67], v[180:183], v[228:231], v[64:67]
	v_mfma_f32_16x16x32_bf16 v[132:135], v[176:179], v[208:211], v[132:135]
	v_mfma_f32_16x16x32_bf16 v[128:131], v[184:187], v[208:211], v[128:131]
	v_mfma_f32_16x16x32_bf16 v[116:119], v[176:179], v[216:219], v[116:119]
	v_mfma_f32_16x16x32_bf16 v[112:115], v[184:187], v[216:219], v[112:115]
	v_mfma_f32_16x16x32_bf16 v[100:103], v[176:179], v[224:227], v[100:103]
	v_mfma_f32_16x16x32_bf16 v[94:97], v[184:187], v[224:227], v[94:97]
	v_mfma_f32_16x16x32_bf16 v[68:71], v[176:179], v[242:245], v[68:71]
	v_mfma_f32_16x16x32_bf16 v[64:67], v[184:187], v[242:245], v[64:67]
	s_setprio 0
	s_barrier
	s_add_i32 s77, s77, s33
	v_lshl_add_u64 v[158:159], s[68:69], 0, v[192:193]
	s_mov_b32 m0, s77
	ds_read_b128 v[188:191], v163 offset:17408
	ds_read_b128 v[208:211], v163 offset:17472
	ds_read_b128 v[212:215], v163 offset:19584
	ds_read_b128 v[216:219], v163 offset:19648
	ds_read_b128 v[220:223], v163 offset:21760
	ds_read_b128 v[224:227], v163 offset:21824
	ds_read_b128 v[228:231], v163 offset:23936
	ds_read_b128 v[242:245], v163 offset:24000
	global_load_lds_dwordx4 v[158:159], off
	s_add_i32 m0, s77, 0x2200
	s_add_u32 s78, s68, 0x40000
	v_lshl_add_u64 v[198:199], s[68:69], 0, v[144:145]
	s_addc_u32 s79, s69, 0
	s_add_i32 s77, s89, s33
	global_load_lds_dwordx4 v[198:199], off
	v_lshl_add_u64 v[98:99], s[78:79], 0, v[192:193]
	s_mov_b32 m0, s77
	v_lshl_add_u64 v[200:201], s[70:71], 0, v[148:149]
	global_load_lds_dwordx4 v[98:99], off
	v_lshl_add_u64 v[98:99], s[78:79], 0, v[144:145]
	s_add_i32 m0, s77, 0x2200
	v_lshl_add_u64 v[232:233], s[70:71], 0, v[146:147]
	global_load_lds_dwordx4 v[98:99], off
	s_mov_b32 m0, s0
	s_nop 0
	global_load_lds_dwordx4 v[200:201], off
	s_mov_b32 m0, s5
	s_nop 0
	global_load_lds_dwordx4 v[232:233], off
	s_waitcnt vmcnt(8)
	s_waitcnt lgkmcnt(0)
	s_barrier
	s_setprio 1
	s_waitcnt lgkmcnt(0)
	v_mfma_f32_16x16x32_bf16 v[60:63], v[86:89], v[188:191], v[60:63]
	v_mfma_f32_16x16x32_bf16 v[56:59], v[164:167], v[188:191], v[56:59]
	v_mfma_f32_16x16x32_bf16 v[44:47], v[86:89], v[212:215], v[44:47]
	v_mfma_f32_16x16x32_bf16 v[40:43], v[164:167], v[212:215], v[40:43]
	v_mfma_f32_16x16x32_bf16 v[28:31], v[86:89], v[220:223], v[28:31]
	v_mfma_f32_16x16x32_bf16 v[24:27], v[164:167], v[220:223], v[24:27]
	v_mfma_f32_16x16x32_bf16 v[12:15], v[86:89], v[228:231], v[12:15]
	v_mfma_f32_16x16x32_bf16 v[8:11], v[164:167], v[228:231], v[8:11]
	v_mfma_f32_16x16x32_bf16 v[60:63], v[90:93], v[208:211], v[60:63]
	v_mfma_f32_16x16x32_bf16 v[56:59], v[168:171], v[208:211], v[56:59]
	v_mfma_f32_16x16x32_bf16 v[44:47], v[90:93], v[216:219], v[44:47]
	v_mfma_f32_16x16x32_bf16 v[40:43], v[168:171], v[216:219], v[40:43]
	v_mfma_f32_16x16x32_bf16 v[28:31], v[90:93], v[224:227], v[28:31]
	v_mfma_f32_16x16x32_bf16 v[24:27], v[168:171], v[224:227], v[24:27]
	v_mfma_f32_16x16x32_bf16 v[12:15], v[90:93], v[242:245], v[12:15]
	v_mfma_f32_16x16x32_bf16 v[8:11], v[168:171], v[242:245], v[8:11]
	s_setprio 0
	s_setprio 1
	v_mfma_f32_16x16x32_bf16 v[52:55], v[172:175], v[188:191], v[52:55]
	v_mfma_f32_16x16x32_bf16 v[48:51], v[180:183], v[188:191], v[48:51]
	v_mfma_f32_16x16x32_bf16 v[36:39], v[172:175], v[212:215], v[36:39]
	v_mfma_f32_16x16x32_bf16 v[32:35], v[180:183], v[212:215], v[32:35]
	v_mfma_f32_16x16x32_bf16 v[20:23], v[172:175], v[220:223], v[20:23]
	v_mfma_f32_16x16x32_bf16 v[16:19], v[180:183], v[220:223], v[16:19]
	v_mfma_f32_16x16x32_bf16 v[4:7], v[172:175], v[228:231], v[4:7]
	v_mfma_f32_16x16x32_bf16 v[0:3], v[180:183], v[228:231], v[0:3]
	v_mfma_f32_16x16x32_bf16 v[52:55], v[176:179], v[208:211], v[52:55]
	v_mfma_f32_16x16x32_bf16 v[48:51], v[184:187], v[208:211], v[48:51]
	v_mfma_f32_16x16x32_bf16 v[36:39], v[176:179], v[216:219], v[36:39]
	v_mfma_f32_16x16x32_bf16 v[32:35], v[184:187], v[216:219], v[32:35]
	v_mfma_f32_16x16x32_bf16 v[20:23], v[176:179], v[224:227], v[20:23]
	v_mfma_f32_16x16x32_bf16 v[16:19], v[184:187], v[224:227], v[16:19]
	v_mfma_f32_16x16x32_bf16 v[4:7], v[176:179], v[242:245], v[4:7]
	v_mfma_f32_16x16x32_bf16 v[0:3], v[184:187], v[242:245], v[0:3]
	s_setprio 0
	s_barrier
; #define PG8_STAGE(bufoff, gbase, voff) do { _Pragma("unroll") for (int _i = 0; _i < 2; ++_i) \
;         __builtin_amdgcn_global_load_lds((const unsigned*)((const char*)(gbase) + (voff)[_i]), (PG8_LAS unsigned*)(lds + (bufoff) + ldsw + _i * (8 * USTR)), 16, 0, 0); } while (0)
; #define PG8_LDA(dst, b, h) do { _Pragma("unroll") for (int m = 0; m < 4; ++m) _Pragma("unroll") for (int k = 0; k < 2; ++k) dst[m][k] = *(const PG8_LAS bf16x8*)(lds + PG8_SA(b, h) + aoff + m * (2 * USTR) + k * 64); } while (0)
; #define PG8_LDB(dst, b, h) do { _Pragma("unroll") for (int n = 0; n < 2; ++n) _Pragma("unroll") for (int k = 0; k < 2; ++k) dst[n][k] = *(const PG8_LAS bf16x8*)(lds + PG8_SB(b, h) + boff + n * (2 * USTR) + k * 64); } while (0)
; #define PG8_MMA(ai, bj, At, Bt) do { __builtin_amdgcn_s_setprio(1); _Pragma("unroll") for (int m = 0; m < 4; ++m) _Pragma("unroll") for (int n = 0; n < 2; ++n) _Pragma("unroll") for (int k = 0; k < 2; ++k) \
;         acc[ai][bj][m][n] = __builtin_amdgcn_mfma_f32_16x16x32_bf16(Bt[n][k], At[m][k], acc[ai][bj][m][n], 0, 0, 0); __builtin_amdgcn_s_setprio(0); } while (0)
; #define PG8_WAIT_V(n) asm volatile("s_waitcnt vmcnt(" #n ")" ::: "memory")
; #define PG8_WAIT_L(n) asm volatile("s_waitcnt lgkmcnt(" #n ")" ::: "memory")
; #define PG8_BAR __builtin_amdgcn_s_barrier()
; #define PG8_SCHED __builtin_amdgcn_sched_barrier(0)
; template <class Epi, class Sched, bool ALIGN_EPI, bool SP2>
; __device__ __forceinline__ void gemm_phase(PG8_LAS unsigned char* lds, const Gemm g, const Sched& S, const Epi& E, int wid) {
;     ...
;             PG8_LDB(B0, 1, 0); PG8_LDB(B1, 1, 1); PG8_SCHED; PG8_LDA(At, 1, 0); PG8_STAGE(PG8_SA(0, 1), a2 + hstepA, voffA);
;             PG8_WAIT_V(8); PG8_WAIT_L(0); PG8_BAR; PG8_MMA(0, 0, At, B0); PG8_MMA(0, 1, At, B1); PG8_BAR; PG8_SCHED;
	s_add_i32 s77, 0, 0x19800
	v_add_u32_e32 v98, s77, v161
	s_add_i32 s78, 0, 0x1dc00
	ds_read_b128 v[86:89], v98
	ds_read_b128 v[90:93], v98 offset:64
	ds_read_b128 v[164:167], v98 offset:2176
	ds_read_b128 v[168:171], v98 offset:2240
	v_add_u32_e32 v98, s78, v161
	ds_read_b128 v[172:175], v98
	ds_read_b128 v[176:179], v98 offset:64
	ds_read_b128 v[180:183], v98 offset:2176
	ds_read_b128 v[184:187], v98 offset:2240
	s_add_u32 s70, s70, 0x40000
	s_addc_u32 s71, s71, 0
	s_mov_b32 m0, s10
	v_lshl_add_u64 v[98:99], s[70:71], 0, v[148:149]
	ds_read_b128 v[188:191], v163 offset:34816
	ds_read_b128 v[208:211], v163 offset:34880
	ds_read_b128 v[212:215], v163 offset:36992
	ds_read_b128 v[216:219], v163 offset:37056
	ds_read_b128 v[220:223], v163 offset:39168
	ds_read_b128 v[224:227], v163 offset:39232
	ds_read_b128 v[228:231], v163 offset:41344
	ds_read_b128 v[242:245], v163 offset:41408
	global_load_lds_dwordx4 v[98:99], off
	v_lshl_add_u64 v[98:99], s[70:71], 0, v[146:147]
	s_mov_b32 m0, s29
	s_nop 0
	global_load_lds_dwordx4 v[98:99], off
	s_waitcnt vmcnt(8)
	s_waitcnt lgkmcnt(0)
	s_barrier
	s_setprio 1
	s_waitcnt lgkmcnt(0)
	v_mfma_f32_16x16x32_bf16 v[140:143], v[86:89], v[188:191], v[140:143]
	v_mfma_f32_16x16x32_bf16 v[136:139], v[164:167], v[188:191], v[136:139]
	v_mfma_f32_16x16x32_bf16 v[124:127], v[86:89], v[212:215], v[124:127]
	v_mfma_f32_16x16x32_bf16 v[120:123], v[164:167], v[212:215], v[120:123]
	v_mfma_f32_16x16x32_bf16 v[108:111], v[86:89], v[220:223], v[108:111]
	v_mfma_f32_16x16x32_bf16 v[104:107], v[164:167], v[220:223], v[104:107]
	v_mfma_f32_16x16x32_bf16 v[76:79], v[86:89], v[228:231], v[76:79]
	v_mfma_f32_16x16x32_bf16 v[72:75], v[164:167], v[228:231], v[72:75]
	v_mfma_f32_16x16x32_bf16 v[140:143], v[90:93], v[208:211], v[140:143]
	v_mfma_f32_16x16x32_bf16 v[136:139], v[168:171], v[208:211], v[136:139]
	v_mfma_f32_16x16x32_bf16 v[124:127], v[90:93], v[216:219], v[124:127]
	v_mfma_f32_16x16x32_bf16 v[120:123], v[168:171], v[216:219], v[120:123]
	v_mfma_f32_16x16x32_bf16 v[108:111], v[90:93], v[224:227], v[108:111]
	v_mfma_f32_16x16x32_bf16 v[104:107], v[168:171], v[224:227], v[104:107]
	v_mfma_f32_16x16x32_bf16 v[76:79], v[90:93], v[242:245], v[76:79]
	v_mfma_f32_16x16x32_bf16 v[72:75], v[168:171], v[242:245], v[72:75]
	s_setprio 0
	s_setprio 1
	v_mfma_f32_16x16x32_bf16 v[132:135], v[172:175], v[188:191], v[132:135]
	v_mfma_f32_16x16x32_bf16 v[128:131], v[180:183], v[188:191], v[128:131]
	v_mfma_f32_16x16x32_bf16 v[116:119], v[172:175], v[212:215], v[116:119]
	v_mfma_f32_16x16x32_bf16 v[112:115], v[180:183], v[212:215], v[112:115]
	v_mfma_f32_16x16x32_bf16 v[98:101], v[172:175], v[220:223], v[100:103]
	v_mfma_f32_16x16x32_bf16 v[94:97], v[180:183], v[220:223], v[94:97]
	v_mfma_f32_16x16x32_bf16 v[68:71], v[172:175], v[228:231], v[68:71]
	v_mfma_f32_16x16x32_bf16 v[64:67], v[180:183], v[228:231], v[64:67]
	v_mfma_f32_16x16x32_bf16 v[132:135], v[176:179], v[208:211], v[132:135]
	v_mfma_f32_16x16x32_bf16 v[128:131], v[184:187], v[208:211], v[128:131]
	v_mfma_f32_16x16x32_bf16 v[116:119], v[176:179], v[216:219], v[116:119]
	v_mfma_f32_16x16x32_bf16 v[112:115], v[184:187], v[216:219], v[112:115]
	v_mfma_f32_16x16x32_bf16 v[100:103], v[176:179], v[224:227], v[98:101]
	v_mfma_f32_16x16x32_bf16 v[96:99], v[184:187], v[224:227], v[94:97]
	v_mfma_f32_16x16x32_bf16 v[68:71], v[176:179], v[242:245], v[68:71]
	v_mfma_f32_16x16x32_bf16 v[64:67], v[184:187], v[242:245], v[64:67]
	s_setprio 0
	s_barrier
; #define PG8_STAGE(bufoff, gbase, voff) do { _Pragma("unroll") for (int _i = 0; _i < 2; ++_i) \
;         __builtin_amdgcn_global_load_lds((const unsigned*)((const char*)(gbase) + (voff)[_i]), (PG8_LAS unsigned*)(lds + (bufoff) + ldsw + _i * (8 * USTR)), 16, 0, 0); } while (0)
; #define PG8_LDA(dst, b, h) do { _Pragma("unroll") for (int m = 0; m < 4; ++m) _Pragma("unroll") for (int k = 0; k < 2; ++k) dst[m][k] = *(const PG8_LAS bf16x8*)(lds + PG8_SA(b, h) + aoff + m * (2 * USTR) + k * 64); } while (0)
; #define PG8_MMA(ai, bj, At, Bt) do { __builtin_amdgcn_s_setprio(1); _Pragma("unroll") for (int m = 0; m < 4; ++m) _Pragma("unroll") for (int n = 0; n < 2; ++n) _Pragma("unroll") for (int k = 0; k < 2; ++k) \
;         acc[ai][bj][m][n] = __builtin_amdgcn_mfma_f32_16x16x32_bf16(Bt[n][k], At[m][k], acc[ai][bj][m][n], 0, 0, 0); __builtin_amdgcn_s_setprio(0); } while (0)
; #define PG8_WAIT_V(n) asm volatile("s_waitcnt vmcnt(" #n ")" ::: "memory")
; #define PG8_WAIT_L(n) asm volatile("s_waitcnt lgkmcnt(" #n ")" ::: "memory")
; #define PG8_BAR __builtin_amdgcn_s_barrier()
; #define PG8_SCHED __builtin_amdgcn_sched_barrier(0)
; template <class Epi, class Sched, bool ALIGN_EPI, bool SP2>
; __device__ __forceinline__ void gemm_phase(PG8_LAS unsigned char* lds, const Gemm g, const Sched& S, const Epi& E, int wid) {
;     ...
;         for (int t = 0; t < nt; t += 2) {
;             const bool last = (t == nt - 2);
;             const char* a1 = cA + (size_t)(t + 1) * kstep;
;             const char* a2 = last ? nA : cA + (size_t)(t + 2) * kstep; const char* b2 = last ? nB : cB + (size_t)(t + 2) * kstep;
;             const char* a3 = a2 + kstep; const char* b3 = b2 + kstep;
;     ...
;             PG8_LDA(At, 1, 1); PG8_STAGE(PG8_SB(1, 0), b3, voffB); PG8_STAGE(PG8_SB(1, 1), b3 + hstepB, voffB); PG8_STAGE(PG8_SA(1, 0), a3, voffA);
;             PG8_WAIT_V(8); PG8_WAIT_L(0); PG8_BAR; PG8_MMA(1, 0, At, B0); PG8_MMA(1, 1, At, B1); PG8_BAR; PG8_SCHED;
	s_add_i32 s70, s77, s33
	v_lshl_add_u64 v[94:95], v[158:159], 0, s[6:7]
	s_mov_b32 m0, s70
	ds_read_b128 v[188:191], v163 offset:52224
	ds_read_b128 v[208:211], v163 offset:52288
	ds_read_b128 v[212:215], v163 offset:54400
	ds_read_b128 v[216:219], v163 offset:54464
	ds_read_b128 v[220:223], v163 offset:56576
	ds_read_b128 v[224:227], v163 offset:56640
	ds_read_b128 v[228:231], v163 offset:58752
	ds_read_b128 v[242:245], v163 offset:58816
	global_load_lds_dwordx4 v[94:95], off
	s_add_i32 m0, s70, 0x2200
	s_add_u32 s68, s68, 0x40080
	v_lshl_add_u64 v[94:95], v[198:199], 0, s[6:7]
	s_addc_u32 s69, s69, 0
	s_add_i32 s70, s78, s33
	global_load_lds_dwordx4 v[94:95], off
	v_lshl_add_u64 v[94:95], s[68:69], 0, v[192:193]
	s_mov_b32 m0, s70
	s_nop 0
	global_load_lds_dwordx4 v[94:95], off
	v_lshl_add_u64 v[94:95], s[68:69], 0, v[144:145]
	s_add_i32 m0, s70, 0x2200
	s_nop 0
	global_load_lds_dwordx4 v[94:95], off
	v_lshl_add_u64 v[94:95], v[200:201], 0, s[6:7]
	s_mov_b32 m0, s56
	s_nop 0
	global_load_lds_dwordx4 v[94:95], off
	v_lshl_add_u64 v[94:95], v[232:233], 0, s[6:7]
	s_mov_b32 m0, s57
	s_nop 0
	global_load_lds_dwordx4 v[94:95], off
	s_add_i32 s76, s76, 2
	s_add_u32 s38, s38, 0x100
	s_addc_u32 s39, s39, 0
	s_add_u32 s74, s74, 0x100
	s_addc_u32 s75, s75, 0
	s_waitcnt vmcnt(8)
	s_waitcnt lgkmcnt(0)
	s_barrier
	s_setprio 1
	s_waitcnt lgkmcnt(0)
	v_mfma_f32_16x16x32_bf16 v[60:63], v[86:89], v[188:191], v[60:63]
	v_mfma_f32_16x16x32_bf16 v[56:59], v[164:167], v[188:191], v[56:59]
	v_mfma_f32_16x16x32_bf16 v[44:47], v[86:89], v[212:215], v[44:47]
	v_mfma_f32_16x16x32_bf16 v[40:43], v[164:167], v[212:215], v[40:43]
	v_mfma_f32_16x16x32_bf16 v[28:31], v[86:89], v[220:223], v[28:31]
	v_mfma_f32_16x16x32_bf16 v[24:27], v[164:167], v[220:223], v[24:27]
	v_mfma_f32_16x16x32_bf16 v[12:15], v[86:89], v[228:231], v[12:15]
	v_mfma_f32_16x16x32_bf16 v[8:11], v[164:167], v[228:231], v[8:11]
	v_mfma_f32_16x16x32_bf16 v[60:63], v[90:93], v[208:211], v[60:63]
	v_mfma_f32_16x16x32_bf16 v[56:59], v[168:171], v[208:211], v[56:59]
	v_mfma_f32_16x16x32_bf16 v[44:47], v[90:93], v[216:219], v[44:47]
	v_mfma_f32_16x16x32_bf16 v[40:43], v[168:171], v[216:219], v[40:43]
	v_mfma_f32_16x16x32_bf16 v[28:31], v[90:93], v[224:227], v[28:31]
	v_mfma_f32_16x16x32_bf16 v[24:27], v[168:171], v[224:227], v[24:27]
	v_mfma_f32_16x16x32_bf16 v[12:15], v[90:93], v[242:245], v[12:15]
	v_mfma_f32_16x16x32_bf16 v[8:11], v[168:171], v[242:245], v[8:11]
	s_setprio 0
	s_setprio 1
	v_mfma_f32_16x16x32_bf16 v[52:55], v[172:175], v[188:191], v[52:55]
	v_mfma_f32_16x16x32_bf16 v[48:51], v[180:183], v[188:191], v[48:51]
	v_mfma_f32_16x16x32_bf16 v[36:39], v[172:175], v[212:215], v[36:39]
	v_mfma_f32_16x16x32_bf16 v[32:35], v[180:183], v[212:215], v[32:35]
	v_mfma_f32_16x16x32_bf16 v[20:23], v[172:175], v[220:223], v[20:23]
	v_mfma_f32_16x16x32_bf16 v[16:19], v[180:183], v[220:223], v[16:19]
	v_mfma_f32_16x16x32_bf16 v[4:7], v[172:175], v[228:231], v[4:7]
	v_mfma_f32_16x16x32_bf16 v[0:3], v[180:183], v[228:231], v[0:3]
	v_mfma_f32_16x16x32_bf16 v[52:55], v[176:179], v[208:211], v[52:55]
	v_mfma_f32_16x16x32_bf16 v[48:51], v[184:187], v[208:211], v[48:51]
	v_mfma_f32_16x16x32_bf16 v[36:39], v[176:179], v[216:219], v[36:39]
	v_mfma_f32_16x16x32_bf16 v[32:35], v[184:187], v[216:219], v[32:35]
	v_mfma_f32_16x16x32_bf16 v[20:23], v[176:179], v[224:227], v[20:23]
	v_mfma_f32_16x16x32_bf16 v[16:19], v[184:187], v[224:227], v[16:19]
	v_mfma_f32_16x16x32_bf16 v[4:7], v[176:179], v[242:245], v[4:7]
	v_mfma_f32_16x16x32_bf16 v[0:3], v[184:187], v[242:245], v[0:3]
	s_setprio 0
	s_barrier
	s_cmp_gt_u32 s76, 13
	s_cbranch_scc1 .LBB0_377

; #define PG8_STAGE(bufoff, gbase, voff) do { _Pragma("unroll") for (int _i = 0; _i < 2; ++_i) \
;         __builtin_amdgcn_global_load_lds((const unsigned*)((const char*)(gbase) + (voff)[_i]), (PG8_LAS unsigned*)(lds + (bufoff) + ldsw + _i * (8 * USTR)), 16, 0, 0); } while (0)
; #define PG8_LDA(dst, b, h) do { _Pragma("unroll") for (int m = 0; m < 4; ++m) _Pragma("unroll") for (int k = 0; k < 2; ++k) dst[m][k] = *(const PG8_LAS bf16x8*)(lds + PG8_SA(b, h) + aoff + m * (2 * USTR) + k * 64); } while (0)
; #define PG8_LDB(dst, b, h) do { _Pragma("unroll") for (int n = 0; n < 2; ++n) _Pragma("unroll") for (int k = 0; k < 2; ++k) dst[n][k] = *(const PG8_LAS bf16x8*)(lds + PG8_SB(b, h) + boff + n * (2 * USTR) + k * 64); } while (0)
; #define PG8_MMA(ai, bj, At, Bt) do { __builtin_amdgcn_s_setprio(1); _Pragma("unroll") for (int m = 0; m < 4; ++m) _Pragma("unroll") for (int n = 0; n < 2; ++n) _Pragma("unroll") for (int k = 0; k < 2; ++k) \
;         acc[ai][bj][m][n] = __builtin_amdgcn_mfma_f32_16x16x32_bf16(Bt[n][k], At[m][k], acc[ai][bj][m][n], 0, 0, 0); __builtin_amdgcn_s_setprio(0); } while (0)
; template <class Epi, class Sched, bool ALIGN_EPI, bool SP2>
; __device__ __forceinline__ void gemm_phase(PG8_LAS unsigned char* lds, const Gemm g, const Sched& S, const Epi& E, int wid) {
;     ...
;         const bool has_next = S.next(ui + 1, nxt);
;         const char* nA = has_next ? (const char*)g.A + (size_t)nxt.pm * tstepA : cA; const char* nB = has_next ? (const char*)g.Bt + (size_t)nxt.pn * tstepB : cB;
;         for (int t = 0; t < nt; t += 2) {
;             const bool last = (t == nt - 2);
;             const char* a1 = cA + (size_t)(t + 1) * kstep;
;             const char* a2 = last ? nA : cA + (size_t)(t + 2) * kstep; const char* b2 = last ? nB : cB + (size_t)(t + 2) * kstep;
;             const char* a3 = a2 + kstep; const char* b3 = b2 + kstep;
;     ...
;             PG8_LDB(B0, 0, 0); PG8_LDB(B1, 0, 1); PG8_SCHED; PG8_LDA(At, 0, 0); PG8_STAGE(PG8_SA(1, 1), a1 + hstepA, voffA);
;             PG8_WAIT_V(8); PG8_WAIT_L(0); PG8_BAR; PG8_MMA(0, 0, At, B0); PG8_MMA(0, 1, At, B1); PG8_BAR; PG8_SCHED;
;             PG8_LDA(At, 0, 1); PG8_STAGE(PG8_SB(0, 0), b2, voffB); PG8_STAGE(PG8_SB(0, 1), b2 + hstepB, voffB); PG8_STAGE(PG8_SA(0, 0), a2, voffA);
;             PG8_WAIT_V(8); PG8_WAIT_L(0); PG8_BAR; PG8_MMA(1, 0, At, B0); PG8_MMA(1, 1, At, B1); PG8_BAR; PG8_SCHED;
.Lhb_mixin:
	s_add_i32 s73, 0, 0x11000
	v_add_u32_e32 v30, s73, v197
	s_add_i32 vcc_lo, 0, 0x15400
	ds_read_b128 v[22:25], v30
	ds_read_b128 v[26:29], v30 offset:64
	ds_read_b128 v[158:161], v30 offset:2176
	ds_read_b128 v[162:165], v30 offset:2240
	v_add_u32_e32 v30, vcc_lo, v197
	ds_read_b128 v[166:169], v30
	ds_read_b128 v[170:173], v30 offset:64
	ds_read_b128 v[174:177], v30 offset:2176
	ds_read_b128 v[178:181], v30 offset:2240
	v_lshl_add_u64 v[30:31], s[38:39], 0, v[154:155]
	s_add_i32 m0, s95, 0xcc00
	ds_read_b128 v[182:185], v210
	ds_read_b128 v[186:189], v210 offset:64
	ds_read_b128 v[212:215], v210 offset:2176
	ds_read_b128 v[216:219], v210 offset:2240
	ds_read_b128 v[220:223], v210 offset:4352
	ds_read_b128 v[224:227], v210 offset:4416
	ds_read_b128 v[228:231], v210 offset:6528
	ds_read_b128 v[242:245], v210 offset:6592
	global_load_lds_dwordx4 v[30:31], off
	v_lshl_add_u64 v[30:31], s[38:39], 0, v[156:157]
	s_add_i32 m0, s95, 0xee00
	s_nop 0
	global_load_lds_dwordx4 v[30:31], off
	s_cmp_eq_u32 s71, 12
	s_cselect_b64 s[40:41], -1, 0
	s_add_u32 s42, s38, 0xfffc0080
	s_addc_u32 s43, s39, -1
	s_and_b64 s[40:41], s[40:41], exec
	s_cselect_b32 s43, s10, s43
	s_cselect_b32 s42, s44, s42
	s_cselect_b32 s41, s45, s70
	s_cselect_b32 s40, s69, s23
	s_waitcnt vmcnt(8)
	s_waitcnt lgkmcnt(0)
	s_barrier
	s_setprio 1
	s_waitcnt lgkmcnt(0)
	v_mfma_f32_16x16x32_bf16 v[140:143], v[22:25], v[182:185], 0
	v_mfma_f32_16x16x32_bf16 v[136:139], v[158:161], v[182:185], 0
	v_mfma_f32_16x16x32_bf16 v[124:127], v[22:25], v[212:215], 0
	v_mfma_f32_16x16x32_bf16 v[120:123], v[158:161], v[212:215], 0
	v_mfma_f32_16x16x32_bf16 v[108:111], v[22:25], v[220:223], 0
	v_mfma_f32_16x16x32_bf16 v[104:107], v[158:161], v[220:223], 0
	v_mfma_f32_16x16x32_bf16 v[92:95], v[22:25], v[228:231], 0
	v_mfma_f32_16x16x32_bf16 v[88:91], v[158:161], v[228:231], 0
	v_mfma_f32_16x16x32_bf16 v[140:143], v[26:29], v[186:189], v[140:143]
	v_mfma_f32_16x16x32_bf16 v[136:139], v[162:165], v[186:189], v[136:139]
	v_mfma_f32_16x16x32_bf16 v[124:127], v[26:29], v[216:219], v[124:127]
	v_mfma_f32_16x16x32_bf16 v[120:123], v[162:165], v[216:219], v[120:123]
	v_mfma_f32_16x16x32_bf16 v[108:111], v[26:29], v[224:227], v[108:111]
	v_mfma_f32_16x16x32_bf16 v[104:107], v[162:165], v[224:227], v[104:107]
	v_mfma_f32_16x16x32_bf16 v[92:95], v[26:29], v[242:245], v[92:95]
	v_mfma_f32_16x16x32_bf16 v[88:91], v[162:165], v[242:245], v[88:91]
	s_setprio 0
	s_setprio 1
	v_mfma_f32_16x16x32_bf16 v[132:135], v[166:169], v[182:185], 0
	v_mfma_f32_16x16x32_bf16 v[128:131], v[174:177], v[182:185], 0
	v_mfma_f32_16x16x32_bf16 v[116:119], v[166:169], v[212:215], 0
	v_mfma_f32_16x16x32_bf16 v[112:115], v[174:177], v[212:215], 0
	v_mfma_f32_16x16x32_bf16 v[100:103], v[166:169], v[220:223], 0
	v_mfma_f32_16x16x32_bf16 v[96:99], v[174:177], v[220:223], 0
	v_mfma_f32_16x16x32_bf16 v[84:87], v[166:169], v[228:231], 0
	v_mfma_f32_16x16x32_bf16 v[80:83], v[174:177], v[228:231], 0
	v_mfma_f32_16x16x32_bf16 v[132:135], v[170:173], v[186:189], v[132:135]
	v_mfma_f32_16x16x32_bf16 v[128:131], v[178:181], v[186:189], v[128:131]
	v_mfma_f32_16x16x32_bf16 v[116:119], v[170:173], v[216:219], v[116:119]
	v_mfma_f32_16x16x32_bf16 v[112:115], v[178:181], v[216:219], v[112:115]
	v_mfma_f32_16x16x32_bf16 v[100:103], v[170:173], v[224:227], v[100:103]
	v_mfma_f32_16x16x32_bf16 v[96:99], v[178:181], v[224:227], v[96:99]
	v_mfma_f32_16x16x32_bf16 v[84:87], v[170:173], v[242:245], v[84:87]
	v_mfma_f32_16x16x32_bf16 v[80:83], v[178:181], v[242:245], v[80:83]
	s_setprio 0
	s_barrier
	s_add_i32 s73, s73, s33
	v_lshl_add_u64 v[190:191], s[40:41], 0, v[192:193]
	s_mov_b32 m0, s73
	ds_read_b128 v[182:185], v210 offset:17408
	ds_read_b128 v[186:189], v210 offset:17472
	ds_read_b128 v[212:215], v210 offset:19584
	ds_read_b128 v[216:219], v210 offset:19648
	ds_read_b128 v[220:223], v210 offset:21760
	ds_read_b128 v[224:227], v210 offset:21824
	ds_read_b128 v[228:231], v210 offset:23936
	ds_read_b128 v[242:245], v210 offset:24000
	global_load_lds_dwordx4 v[190:191], off
	s_add_i32 m0, s73, 0x2200
	s_add_u32 s76, s40, 0x40000
	v_lshl_add_u64 v[198:199], s[40:41], 0, v[146:147]
	s_addc_u32 s77, s41, 0
	s_add_i32 s73, vcc_lo, s33
	global_load_lds_dwordx4 v[198:199], off
	v_lshl_add_u64 v[30:31], s[76:77], 0, v[192:193]
	s_mov_b32 m0, s73
	v_lshl_add_u64 v[200:201], s[42:43], 0, v[150:151]
	global_load_lds_dwordx4 v[30:31], off
	v_lshl_add_u64 v[30:31], s[76:77], 0, v[146:147]
	s_add_i32 m0, s73, 0x2200
	v_lshl_add_u64 v[208:209], s[42:43], 0, v[148:149]
	global_load_lds_dwordx4 v[30:31], off
	s_mov_b32 m0, s95
	s_nop 0
	global_load_lds_dwordx4 v[200:201], off
	s_mov_b32 m0, s5
	s_nop 0
	global_load_lds_dwordx4 v[208:209], off
	s_waitcnt vmcnt(8)
	s_waitcnt lgkmcnt(0)
	s_barrier
; #define PG8_STAGE(bufoff, gbase, voff) do { _Pragma("unroll") for (int _i = 0; _i < 2; ++_i) \
;         __builtin_amdgcn_global_load_lds((const unsigned*)((const char*)(gbase) + (voff)[_i]), (PG8_LAS unsigned*)(lds + (bufoff) + ldsw + _i * (8 * USTR)), 16, 0, 0); } while (0)
; #define PG8_LDA(dst, b, h) do { _Pragma("unroll") for (int m = 0; m < 4; ++m) _Pragma("unroll") for (int k = 0; k < 2; ++k) dst[m][k] = *(const PG8_LAS bf16x8*)(lds + PG8_SA(b, h) + aoff + m * (2 * USTR) + k * 64); } while (0)
; #define PG8_LDB(dst, b, h) do { _Pragma("unroll") for (int n = 0; n < 2; ++n) _Pragma("unroll") for (int k = 0; k < 2; ++k) dst[n][k] = *(const PG8_LAS bf16x8*)(lds + PG8_SB(b, h) + boff + n * (2 * USTR) + k * 64); } while (0)
; #define PG8_MMA(ai, bj, At, Bt) do { __builtin_amdgcn_s_setprio(1); _Pragma("unroll") for (int m = 0; m < 4; ++m) _Pragma("unroll") for (int n = 0; n < 2; ++n) _Pragma("unroll") for (int k = 0; k < 2; ++k) \
;         acc[ai][bj][m][n] = __builtin_amdgcn_mfma_f32_16x16x32_bf16(Bt[n][k], At[m][k], acc[ai][bj][m][n], 0, 0, 0); __builtin_amdgcn_s_setprio(0); } while (0)
; #define PG8_WAIT_V(n) asm volatile("s_waitcnt vmcnt(" #n ")" ::: "memory")
; #define PG8_WAIT_L(n) asm volatile("s_waitcnt lgkmcnt(" #n ")" ::: "memory")
; #define PG8_BAR __builtin_amdgcn_s_barrier()
; #define PG8_SCHED __builtin_amdgcn_sched_barrier(0)
; template <class Epi, class Sched, bool ALIGN_EPI, bool SP2>
; __device__ __forceinline__ void gemm_phase(PG8_LAS unsigned char* lds, const Gemm g, const Sched& S, const Epi& E, int wid) {
;     ...
;             PG8_WAIT_V(8); PG8_WAIT_L(0); PG8_BAR; PG8_MMA(1, 0, At, B0); PG8_MMA(1, 1, At, B1); PG8_BAR; PG8_SCHED;
;             PG8_LDB(B0, 1, 0); PG8_LDB(B1, 1, 1); PG8_SCHED; PG8_LDA(At, 1, 0); PG8_STAGE(PG8_SA(0, 1), a2 + hstepA, voffA);
;             PG8_WAIT_V(8); PG8_WAIT_L(0); PG8_BAR; PG8_MMA(0, 0, At, B0); PG8_MMA(0, 1, At, B1); PG8_BAR; PG8_SCHED;
	s_setprio 1
	s_waitcnt lgkmcnt(0)
	v_mfma_f32_16x16x32_bf16 v[76:79], v[22:25], v[182:185], 0
	v_mfma_f32_16x16x32_bf16 v[72:75], v[158:161], v[182:185], 0
	v_mfma_f32_16x16x32_bf16 v[60:63], v[22:25], v[212:215], 0
	v_mfma_f32_16x16x32_bf16 v[56:59], v[158:161], v[212:215], 0
	v_mfma_f32_16x16x32_bf16 v[44:47], v[22:25], v[220:223], 0
	v_mfma_f32_16x16x32_bf16 v[40:43], v[158:161], v[220:223], 0
	v_mfma_f32_16x16x32_bf16 v[12:15], v[22:25], v[228:231], 0
	v_mfma_f32_16x16x32_bf16 v[8:11], v[158:161], v[228:231], 0
	v_mfma_f32_16x16x32_bf16 v[76:79], v[26:29], v[186:189], v[76:79]
	v_mfma_f32_16x16x32_bf16 v[72:75], v[162:165], v[186:189], v[72:75]
	v_mfma_f32_16x16x32_bf16 v[60:63], v[26:29], v[216:219], v[60:63]
	v_mfma_f32_16x16x32_bf16 v[56:59], v[162:165], v[216:219], v[56:59]
	v_mfma_f32_16x16x32_bf16 v[44:47], v[26:29], v[224:227], v[44:47]
	v_mfma_f32_16x16x32_bf16 v[40:43], v[162:165], v[224:227], v[40:43]
	v_mfma_f32_16x16x32_bf16 v[12:15], v[26:29], v[242:245], v[12:15]
	v_mfma_f32_16x16x32_bf16 v[8:11], v[162:165], v[242:245], v[8:11]
	s_setprio 0
	s_setprio 1
	v_mfma_f32_16x16x32_bf16 v[52:55], v[166:169], v[212:215], 0
	v_mfma_f32_16x16x32_bf16 v[48:51], v[174:177], v[212:215], 0
	v_mfma_f32_16x16x32_bf16 v[36:39], v[166:169], v[220:223], 0
	v_mfma_f32_16x16x32_bf16 v[30:33], v[174:177], v[220:223], 0
	v_mfma_f32_16x16x32_bf16 v[4:7], v[166:169], v[228:231], 0
	v_mfma_f32_16x16x32_bf16 v[0:3], v[174:177], v[228:231], 0
	v_mfma_f32_16x16x32_bf16 v[22:25], v[166:169], v[182:185], 0
	v_mfma_f32_16x16x32_bf16 v[26:29], v[174:177], v[182:185], 0
	v_mfma_f32_16x16x32_bf16 v[52:55], v[170:173], v[216:219], v[52:55]
	v_mfma_f32_16x16x32_bf16 v[48:51], v[178:181], v[216:219], v[48:51]
	v_mfma_f32_16x16x32_bf16 v[36:39], v[170:173], v[224:227], v[36:39]
	v_mfma_f32_16x16x32_bf16 v[30:33], v[178:181], v[224:227], v[30:33]
	v_mfma_f32_16x16x32_bf16 v[4:7], v[170:173], v[242:245], v[4:7]
	v_mfma_f32_16x16x32_bf16 v[0:3], v[178:181], v[242:245], v[0:3]
	v_mfma_f32_16x16x32_bf16 v[22:25], v[170:173], v[186:189], v[22:25]
	v_mfma_f32_16x16x32_bf16 v[26:29], v[178:181], v[186:189], v[26:29]
	s_setprio 0
	s_barrier
	s_add_i32 s73, 0, 0x19800
	v_add_u32_e32 v34, s73, v197
	s_add_i32 s76, 0, 0x1dc00
	ds_read_b128 v[64:67], v34
	ds_read_b128 v[68:71], v34 offset:64
	ds_read_b128 v[158:161], v34 offset:2176
	ds_read_b128 v[162:165], v34 offset:2240
	v_add_u32_e32 v34, s76, v197
	ds_read_b128 v[166:169], v34
	ds_read_b128 v[170:173], v34 offset:64
	ds_read_b128 v[174:177], v34 offset:2176
	ds_read_b128 v[178:181], v34 offset:2240
	s_add_u32 s42, s42, 0x40000
	s_addc_u32 s43, s43, 0
	s_mov_b32 m0, s56
	v_lshl_add_u64 v[34:35], s[42:43], 0, v[150:151]
	ds_read_b128 v[182:185], v210 offset:34816
	ds_read_b128 v[186:189], v210 offset:34880
	ds_read_b128 v[212:215], v210 offset:36992
	ds_read_b128 v[216:219], v210 offset:37056
	ds_read_b128 v[220:223], v210 offset:39168
	ds_read_b128 v[224:227], v210 offset:39232
	ds_read_b128 v[228:231], v210 offset:41344
	ds_read_b128 v[242:245], v210 offset:41408
	global_load_lds_dwordx4 v[34:35], off
	v_lshl_add_u64 v[34:35], s[42:43], 0, v[148:149]
	s_mov_b32 m0, s57
	s_nop 0
	global_load_lds_dwordx4 v[34:35], off
	s_waitcnt vmcnt(8)
	s_waitcnt lgkmcnt(0)
	s_barrier
	s_setprio 1
	s_waitcnt lgkmcnt(0)
	v_mfma_f32_16x16x32_bf16 v[140:143], v[64:67], v[182:185], v[140:143]
	v_mfma_f32_16x16x32_bf16 v[136:139], v[158:161], v[182:185], v[136:139]
	v_mfma_f32_16x16x32_bf16 v[124:127], v[64:67], v[212:215], v[124:127]
	v_mfma_f32_16x16x32_bf16 v[120:123], v[158:161], v[212:215], v[120:123]
	v_mfma_f32_16x16x32_bf16 v[108:111], v[64:67], v[220:223], v[108:111]
	v_mfma_f32_16x16x32_bf16 v[104:107], v[158:161], v[220:223], v[104:107]
	v_mfma_f32_16x16x32_bf16 v[92:95], v[64:67], v[228:231], v[92:95]
	v_mfma_f32_16x16x32_bf16 v[88:91], v[158:161], v[228:231], v[88:91]
	v_mfma_f32_16x16x32_bf16 v[140:143], v[68:71], v[186:189], v[140:143]
	v_mfma_f32_16x16x32_bf16 v[136:139], v[162:165], v[186:189], v[136:139]
	v_mfma_f32_16x16x32_bf16 v[124:127], v[68:71], v[216:219], v[124:127]
	v_mfma_f32_16x16x32_bf16 v[120:123], v[162:165], v[216:219], v[120:123]
	v_mfma_f32_16x16x32_bf16 v[108:111], v[68:71], v[224:227], v[108:111]
	v_mfma_f32_16x16x32_bf16 v[104:107], v[162:165], v[224:227], v[104:107]
	v_mfma_f32_16x16x32_bf16 v[92:95], v[68:71], v[242:245], v[92:95]
	v_mfma_f32_16x16x32_bf16 v[88:91], v[162:165], v[242:245], v[88:91]
	s_setprio 0
	s_setprio 1
	v_mfma_f32_16x16x32_bf16 v[132:135], v[166:169], v[182:185], v[132:135]
	v_mfma_f32_16x16x32_bf16 v[128:131], v[174:177], v[182:185], v[128:131]
	v_mfma_f32_16x16x32_bf16 v[116:119], v[166:169], v[212:215], v[116:119]
	v_mfma_f32_16x16x32_bf16 v[112:115], v[174:177], v[212:215], v[112:115]
	v_mfma_f32_16x16x32_bf16 v[100:103], v[166:169], v[220:223], v[100:103]
	v_mfma_f32_16x16x32_bf16 v[96:99], v[174:177], v[220:223], v[96:99]
	v_mfma_f32_16x16x32_bf16 v[84:87], v[166:169], v[228:231], v[84:87]
	v_mfma_f32_16x16x32_bf16 v[80:83], v[174:177], v[228:231], v[80:83]
	v_mfma_f32_16x16x32_bf16 v[132:135], v[170:173], v[186:189], v[132:135]
	v_mfma_f32_16x16x32_bf16 v[128:131], v[178:181], v[186:189], v[128:131]
	v_mfma_f32_16x16x32_bf16 v[116:119], v[170:173], v[216:219], v[116:119]
	v_mfma_f32_16x16x32_bf16 v[112:115], v[178:181], v[216:219], v[112:115]
	v_mfma_f32_16x16x32_bf16 v[100:103], v[170:173], v[224:227], v[100:103]
	v_mfma_f32_16x16x32_bf16 v[96:99], v[178:181], v[224:227], v[96:99]
	v_mfma_f32_16x16x32_bf16 v[84:87], v[170:173], v[242:245], v[84:87]
	v_mfma_f32_16x16x32_bf16 v[80:83], v[178:181], v[242:245], v[80:83]
	s_setprio 0
	s_barrier
; #define PG8_STAGE(bufoff, gbase, voff) do { _Pragma("unroll") for (int _i = 0; _i < 2; ++_i) \
;         __builtin_amdgcn_global_load_lds((const unsigned*)((const char*)(gbase) + (voff)[_i]), (PG8_LAS unsigned*)(lds + (bufoff) + ldsw + _i * (8 * USTR)), 16, 0, 0); } while (0)
; #define PG8_LDA(dst, b, h) do { _Pragma("unroll") for (int m = 0; m < 4; ++m) _Pragma("unroll") for (int k = 0; k < 2; ++k) dst[m][k] = *(const PG8_LAS bf16x8*)(lds + PG8_SA(b, h) + aoff + m * (2 * USTR) + k * 64); } while (0)
; #define PG8_LDB(dst, b, h) do { _Pragma("unroll") for (int n = 0; n < 2; ++n) _Pragma("unroll") for (int k = 0; k < 2; ++k) dst[n][k] = *(const PG8_LAS bf16x8*)(lds + PG8_SB(b, h) + boff + n * (2 * USTR) + k * 64); } while (0)
; #define PG8_MMA(ai, bj, At, Bt) do { __builtin_amdgcn_s_setprio(1); _Pragma("unroll") for (int m = 0; m < 4; ++m) _Pragma("unroll") for (int n = 0; n < 2; ++n) _Pragma("unroll") for (int k = 0; k < 2; ++k) \
;         acc[ai][bj][m][n] = __builtin_amdgcn_mfma_f32_16x16x32_bf16(Bt[n][k], At[m][k], acc[ai][bj][m][n], 0, 0, 0); __builtin_amdgcn_s_setprio(0); } while (0)
; #define PG8_BAR __builtin_amdgcn_s_barrier()
; template <class Epi, class Sched, bool ALIGN_EPI, bool SP2>
; __device__ __forceinline__ void gemm_phase(PG8_LAS unsigned char* lds, const Gemm g, const Sched& S, const Epi& E, int wid) {
;     ...
;             PG8_LDB(B0, 0, 0); PG8_LDB(B1, 0, 1); PG8_SCHED; PG8_LDA(At, 0, 0); PG8_STAGE(PG8_SA(1, 1), a1 + hstepA, voffA);
;             PG8_WAIT_V(8); PG8_WAIT_L(0); PG8_BAR; PG8_MMA(0, 0, At, B0); PG8_MMA(0, 1, At, B1); PG8_BAR; PG8_SCHED;
;             PG8_LDA(At, 0, 1); PG8_STAGE(PG8_SB(0, 0), b2, voffB); PG8_STAGE(PG8_SB(0, 1), b2 + hstepB, voffB); PG8_STAGE(PG8_SA(0, 0), a2, voffA);
;             PG8_WAIT_V(8); PG8_WAIT_L(0); PG8_BAR; PG8_MMA(1, 0, At, B0); PG8_MMA(1, 1, At, B1); PG8_BAR; PG8_SCHED;
;             PG8_LDB(B0, 1, 0); PG8_LDB(B1, 1, 1); PG8_SCHED; PG8_LDA(At, 1, 0); PG8_STAGE(PG8_SA(0, 1), a2 + hstepA, voffA);
;             PG8_WAIT_V(8); PG8_WAIT_L(0); PG8_BAR; PG8_MMA(0, 0, At, B0); PG8_MMA(0, 1, At, B1); PG8_BAR; PG8_SCHED;
;             PG8_LDA(At, 1, 1); PG8_STAGE(PG8_SB(1, 0), b3, voffB); PG8_STAGE(PG8_SB(1, 1), b3 + hstepB, voffB); PG8_STAGE(PG8_SA(1, 0), a3, voffA);
;             PG8_WAIT_V(8); PG8_WAIT_L(0); PG8_BAR; PG8_MMA(1, 0, At, B0); PG8_MMA(1, 1, At, B1); PG8_BAR; PG8_SCHED;
	s_add_i32 s42, s73, s33
	v_lshl_add_u64 v[34:35], v[190:191], 0, s[6:7]
	s_mov_b32 m0, s42
	ds_read_b128 v[182:185], v210 offset:52224
	ds_read_b128 v[186:189], v210 offset:52288
	ds_read_b128 v[212:215], v210 offset:54400
	ds_read_b128 v[216:219], v210 offset:54464
	ds_read_b128 v[220:223], v210 offset:56576
	ds_read_b128 v[224:227], v210 offset:56640
	ds_read_b128 v[228:231], v210 offset:58752
	ds_read_b128 v[242:245], v210 offset:58816
	global_load_lds_dwordx4 v[34:35], off
	s_add_i32 m0, s42, 0x2200
	s_add_u32 s40, s40, 0x40080
	v_lshl_add_u64 v[34:35], v[198:199], 0, s[6:7]
	s_addc_u32 s41, s41, 0
	s_add_i32 s42, s76, s33
	global_load_lds_dwordx4 v[34:35], off
	v_lshl_add_u64 v[34:35], s[40:41], 0, v[192:193]
	s_mov_b32 m0, s42
	s_nop 0
	global_load_lds_dwordx4 v[34:35], off
	v_lshl_add_u64 v[34:35], s[40:41], 0, v[146:147]
	s_add_i32 m0, s42, 0x2200
	s_nop 0
	global_load_lds_dwordx4 v[34:35], off
	v_lshl_add_u64 v[34:35], v[200:201], 0, s[6:7]
	s_mov_b32 m0, s29
	s_nop 0
	global_load_lds_dwordx4 v[34:35], off
	v_lshl_add_u64 v[34:35], v[208:209], 0, s[6:7]
	s_mov_b32 m0, s0
	s_nop 0
	global_load_lds_dwordx4 v[34:35], off
	s_add_i32 s71, s71, 2
	s_add_u32 s38, s38, 0x100
	s_addc_u32 s39, s39, 0
	s_add_u32 s23, s23, 0x100
	s_addc_u32 s70, s70, 0
	s_waitcnt vmcnt(8)
	s_waitcnt lgkmcnt(0)
	s_barrier
	s_setprio 1
	s_waitcnt lgkmcnt(0)
	v_mfma_f32_16x16x32_bf16 v[76:79], v[64:67], v[182:185], v[76:79]
	v_mfma_f32_16x16x32_bf16 v[72:75], v[158:161], v[182:185], v[72:75]
	v_mfma_f32_16x16x32_bf16 v[60:63], v[64:67], v[212:215], v[60:63]
	v_mfma_f32_16x16x32_bf16 v[56:59], v[158:161], v[212:215], v[56:59]
	v_mfma_f32_16x16x32_bf16 v[44:47], v[64:67], v[220:223], v[44:47]
	v_mfma_f32_16x16x32_bf16 v[40:43], v[158:161], v[220:223], v[40:43]
	v_mfma_f32_16x16x32_bf16 v[12:15], v[64:67], v[228:231], v[12:15]
	v_mfma_f32_16x16x32_bf16 v[8:11], v[158:161], v[228:231], v[8:11]
	v_mfma_f32_16x16x32_bf16 v[76:79], v[68:71], v[186:189], v[76:79]
	v_mfma_f32_16x16x32_bf16 v[72:75], v[162:165], v[186:189], v[72:75]
	v_mfma_f32_16x16x32_bf16 v[60:63], v[68:71], v[216:219], v[60:63]
	v_mfma_f32_16x16x32_bf16 v[56:59], v[162:165], v[216:219], v[56:59]
	v_mfma_f32_16x16x32_bf16 v[44:47], v[68:71], v[224:227], v[44:47]
	v_mfma_f32_16x16x32_bf16 v[40:43], v[162:165], v[224:227], v[40:43]
	v_mfma_f32_16x16x32_bf16 v[12:15], v[68:71], v[242:245], v[12:15]
	v_mfma_f32_16x16x32_bf16 v[8:11], v[162:165], v[242:245], v[8:11]
	s_setprio 0
	s_setprio 1
	v_mfma_f32_16x16x32_bf16 v[22:25], v[166:169], v[182:185], v[22:25]
	v_mfma_f32_16x16x32_bf16 v[68:71], v[170:173], v[186:189], v[22:25]
	v_mfma_f32_16x16x32_bf16 v[22:25], v[174:177], v[182:185], v[26:29]
	v_mfma_f32_16x16x32_bf16 v[64:67], v[178:181], v[186:189], v[22:25]
	v_mfma_f32_16x16x32_bf16 v[22:25], v[166:169], v[212:215], v[52:55]
	v_mfma_f32_16x16x32_bf16 v[52:55], v[170:173], v[216:219], v[22:25]
	v_mfma_f32_16x16x32_bf16 v[22:25], v[174:177], v[212:215], v[48:51]
	v_mfma_f32_16x16x32_bf16 v[48:51], v[178:181], v[216:219], v[22:25]
	v_mfma_f32_16x16x32_bf16 v[22:25], v[166:169], v[220:223], v[36:39]
	v_mfma_f32_16x16x32_bf16 v[36:39], v[170:173], v[224:227], v[22:25]
	v_mfma_f32_16x16x32_bf16 v[22:25], v[174:177], v[220:223], v[30:33]
	v_mfma_f32_16x16x32_bf16 v[4:7], v[166:169], v[228:231], v[4:7]
	v_mfma_f32_16x16x32_bf16 v[0:3], v[174:177], v[228:231], v[0:3]
	v_mfma_f32_16x16x32_bf16 v[32:35], v[178:181], v[224:227], v[22:25]
	v_mfma_f32_16x16x32_bf16 v[4:7], v[170:173], v[242:245], v[4:7]
	v_mfma_f32_16x16x32_bf16 v[0:3], v[178:181], v[242:245], v[0:3]
	s_setprio 0
	s_barrier
	s_cmp_gt_u32 s71, 13
	s_branch .LBB0_394
.LBB0_393:
	s_add_i32 s73, 0, 0x11000
	v_add_u32_e32 v30, s73, v197
	s_add_i32 vcc_lo, 0, 0x15400
	ds_read_b128 v[22:25], v30
	ds_read_b128 v[26:29], v30 offset:64
	ds_read_b128 v[158:161], v30 offset:2176
	ds_read_b128 v[162:165], v30 offset:2240
	v_add_u32_e32 v30, vcc_lo, v197
	ds_read_b128 v[166:169], v30
	ds_read_b128 v[170:173], v30 offset:64
	ds_read_b128 v[174:177], v30 offset:2176
	ds_read_b128 v[178:181], v30 offset:2240
	v_lshl_add_u64 v[30:31], s[38:39], 0, v[154:155]
	s_add_i32 m0, s95, 0xcc00
	ds_read_b128 v[182:185], v210
	ds_read_b128 v[186:189], v210 offset:64
	ds_read_b128 v[212:215], v210 offset:2176
	ds_read_b128 v[216:219], v210 offset:2240
	ds_read_b128 v[220:223], v210 offset:4352
	ds_read_b128 v[224:227], v210 offset:4416
	ds_read_b128 v[228:231], v210 offset:6528
	ds_read_b128 v[242:245], v210 offset:6592
	global_load_lds_dwordx4 v[30:31], off
	v_lshl_add_u64 v[30:31], s[38:39], 0, v[156:157]
	s_add_i32 m0, s95, 0xee00
	s_nop 0
	global_load_lds_dwordx4 v[30:31], off
	s_add_u32 s42, s38, 0xfffc0080
	s_addc_u32 s43, s39, -1
	s_and_b64 s[40:41], s[40:41], exec
	s_cselect_b32 s43, s10, s43
	s_cselect_b32 s42, s44, s42
	s_cselect_b32 s41, s45, s70
	s_cselect_b32 s40, s69, s23
	s_waitcnt vmcnt(8)
	s_waitcnt lgkmcnt(0)
	s_barrier
; #define PG8_STAGE(bufoff, gbase, voff) do { _Pragma("unroll") for (int _i = 0; _i < 2; ++_i) \
;         __builtin_amdgcn_global_load_lds((const unsigned*)((const char*)(gbase) + (voff)[_i]), (PG8_LAS unsigned*)(lds + (bufoff) + ldsw + _i * (8 * USTR)), 16, 0, 0); } while (0)
; #define PG8_LDA(dst, b, h) do { _Pragma("unroll") for (int m = 0; m < 4; ++m) _Pragma("unroll") for (int k = 0; k < 2; ++k) dst[m][k] = *(const PG8_LAS bf16x8*)(lds + PG8_SA(b, h) + aoff + m * (2 * USTR) + k * 64); } while (0)
; #define PG8_MMA(ai, bj, At, Bt) do { __builtin_amdgcn_s_setprio(1); _Pragma("unroll") for (int m = 0; m < 4; ++m) _Pragma("unroll") for (int n = 0; n < 2; ++n) _Pragma("unroll") for (int k = 0; k < 2; ++k) \
;         acc[ai][bj][m][n] = __builtin_amdgcn_mfma_f32_16x16x32_bf16(Bt[n][k], At[m][k], acc[ai][bj][m][n], 0, 0, 0); __builtin_amdgcn_s_setprio(0); } while (0)
; #define PG8_WAIT_V(n) asm volatile("s_waitcnt vmcnt(" #n ")" ::: "memory")
; #define PG8_WAIT_L(n) asm volatile("s_waitcnt lgkmcnt(" #n ")" ::: "memory")
; #define PG8_BAR __builtin_amdgcn_s_barrier()
; #define PG8_SCHED __builtin_amdgcn_sched_barrier(0)
; template <class Epi, class Sched, bool ALIGN_EPI, bool SP2>
; __device__ __forceinline__ void gemm_phase(PG8_LAS unsigned char* lds, const Gemm g, const Sched& S, const Epi& E, int wid) {
;     ...
;             PG8_WAIT_V(8); PG8_WAIT_L(0); PG8_BAR; PG8_MMA(0, 0, At, B0); PG8_MMA(0, 1, At, B1); PG8_BAR; PG8_SCHED;
;             PG8_LDA(At, 0, 1); PG8_STAGE(PG8_SB(0, 0), b2, voffB); PG8_STAGE(PG8_SB(0, 1), b2 + hstepB, voffB); PG8_STAGE(PG8_SA(0, 0), a2, voffA);
;             PG8_WAIT_V(8); PG8_WAIT_L(0); PG8_BAR; PG8_MMA(1, 0, At, B0); PG8_MMA(1, 1, At, B1); PG8_BAR; PG8_SCHED;
	s_setprio 1
	s_waitcnt lgkmcnt(0)
	v_mfma_f32_16x16x32_bf16 v[140:143], v[22:25], v[182:185], v[140:143]
	v_mfma_f32_16x16x32_bf16 v[136:139], v[158:161], v[182:185], v[136:139]
	v_mfma_f32_16x16x32_bf16 v[124:127], v[22:25], v[212:215], v[124:127]
	v_mfma_f32_16x16x32_bf16 v[120:123], v[158:161], v[212:215], v[120:123]
	v_mfma_f32_16x16x32_bf16 v[108:111], v[22:25], v[220:223], v[108:111]
	v_mfma_f32_16x16x32_bf16 v[104:107], v[158:161], v[220:223], v[104:107]
	v_mfma_f32_16x16x32_bf16 v[92:95], v[22:25], v[228:231], v[92:95]
	v_mfma_f32_16x16x32_bf16 v[88:91], v[158:161], v[228:231], v[88:91]
	v_mfma_f32_16x16x32_bf16 v[140:143], v[26:29], v[186:189], v[140:143]
	v_mfma_f32_16x16x32_bf16 v[136:139], v[162:165], v[186:189], v[136:139]
	v_mfma_f32_16x16x32_bf16 v[124:127], v[26:29], v[216:219], v[124:127]
	v_mfma_f32_16x16x32_bf16 v[120:123], v[162:165], v[216:219], v[120:123]
	v_mfma_f32_16x16x32_bf16 v[108:111], v[26:29], v[224:227], v[108:111]
	v_mfma_f32_16x16x32_bf16 v[104:107], v[162:165], v[224:227], v[104:107]
	v_mfma_f32_16x16x32_bf16 v[92:95], v[26:29], v[242:245], v[92:95]
	v_mfma_f32_16x16x32_bf16 v[88:91], v[162:165], v[242:245], v[88:91]
	s_setprio 0
	s_setprio 1
	v_mfma_f32_16x16x32_bf16 v[132:135], v[166:169], v[182:185], v[132:135]
	v_mfma_f32_16x16x32_bf16 v[128:131], v[174:177], v[182:185], v[128:131]
	v_mfma_f32_16x16x32_bf16 v[116:119], v[166:169], v[212:215], v[116:119]
	v_mfma_f32_16x16x32_bf16 v[112:115], v[174:177], v[212:215], v[112:115]
	v_mfma_f32_16x16x32_bf16 v[100:103], v[166:169], v[220:223], v[100:103]
	v_mfma_f32_16x16x32_bf16 v[96:99], v[174:177], v[220:223], v[96:99]
	v_mfma_f32_16x16x32_bf16 v[84:87], v[166:169], v[228:231], v[84:87]
	v_mfma_f32_16x16x32_bf16 v[80:83], v[174:177], v[228:231], v[80:83]
	v_mfma_f32_16x16x32_bf16 v[132:135], v[170:173], v[186:189], v[132:135]
	v_mfma_f32_16x16x32_bf16 v[128:131], v[178:181], v[186:189], v[128:131]
	v_mfma_f32_16x16x32_bf16 v[116:119], v[170:173], v[216:219], v[116:119]
	v_mfma_f32_16x16x32_bf16 v[112:115], v[178:181], v[216:219], v[112:115]
	v_mfma_f32_16x16x32_bf16 v[100:103], v[170:173], v[224:227], v[100:103]
	v_mfma_f32_16x16x32_bf16 v[96:99], v[178:181], v[224:227], v[96:99]
	v_mfma_f32_16x16x32_bf16 v[84:87], v[170:173], v[242:245], v[84:87]
	v_mfma_f32_16x16x32_bf16 v[80:83], v[178:181], v[242:245], v[80:83]
	s_setprio 0
	s_barrier
	s_add_i32 s73, s73, s33
	v_lshl_add_u64 v[190:191], s[40:41], 0, v[192:193]
	s_mov_b32 m0, s73
	ds_read_b128 v[182:185], v210 offset:17408
	ds_read_b128 v[186:189], v210 offset:17472
	ds_read_b128 v[212:215], v210 offset:19584
	ds_read_b128 v[216:219], v210 offset:19648
	ds_read_b128 v[220:223], v210 offset:21760
	ds_read_b128 v[224:227], v210 offset:21824
	ds_read_b128 v[228:231], v210 offset:23936
	ds_read_b128 v[242:245], v210 offset:24000
	global_load_lds_dwordx4 v[190:191], off
	s_add_i32 m0, s73, 0x2200
	s_add_u32 s76, s40, 0x40000
	v_lshl_add_u64 v[198:199], s[40:41], 0, v[146:147]
	s_addc_u32 s77, s41, 0
	s_add_i32 s73, vcc_lo, s33
	global_load_lds_dwordx4 v[198:199], off
	v_lshl_add_u64 v[30:31], s[76:77], 0, v[192:193]
	s_mov_b32 m0, s73
	v_lshl_add_u64 v[200:201], s[42:43], 0, v[150:151]
	global_load_lds_dwordx4 v[30:31], off
	v_lshl_add_u64 v[30:31], s[76:77], 0, v[146:147]
	s_add_i32 m0, s73, 0x2200
	v_lshl_add_u64 v[208:209], s[42:43], 0, v[148:149]
	global_load_lds_dwordx4 v[30:31], off
	s_mov_b32 m0, s95
	s_nop 0
	global_load_lds_dwordx4 v[200:201], off
	s_mov_b32 m0, s5
	s_nop 0
	global_load_lds_dwordx4 v[208:209], off
	s_waitcnt vmcnt(8)
	s_waitcnt lgkmcnt(0)
	s_barrier
	s_setprio 1
	s_waitcnt lgkmcnt(0)
	v_mfma_f32_16x16x32_bf16 v[76:79], v[22:25], v[182:185], v[76:79]
	v_mfma_f32_16x16x32_bf16 v[72:75], v[158:161], v[182:185], v[72:75]
	v_mfma_f32_16x16x32_bf16 v[60:63], v[22:25], v[212:215], v[60:63]
	v_mfma_f32_16x16x32_bf16 v[56:59], v[158:161], v[212:215], v[56:59]
	v_mfma_f32_16x16x32_bf16 v[44:47], v[22:25], v[220:223], v[44:47]
	v_mfma_f32_16x16x32_bf16 v[40:43], v[158:161], v[220:223], v[40:43]
	v_mfma_f32_16x16x32_bf16 v[12:15], v[22:25], v[228:231], v[12:15]
	v_mfma_f32_16x16x32_bf16 v[8:11], v[158:161], v[228:231], v[8:11]
	v_mfma_f32_16x16x32_bf16 v[76:79], v[26:29], v[186:189], v[76:79]
	v_mfma_f32_16x16x32_bf16 v[72:75], v[162:165], v[186:189], v[72:75]
	v_mfma_f32_16x16x32_bf16 v[60:63], v[26:29], v[216:219], v[60:63]
	v_mfma_f32_16x16x32_bf16 v[56:59], v[162:165], v[216:219], v[56:59]
	v_mfma_f32_16x16x32_bf16 v[44:47], v[26:29], v[224:227], v[44:47]
	v_mfma_f32_16x16x32_bf16 v[40:43], v[162:165], v[224:227], v[40:43]
	v_mfma_f32_16x16x32_bf16 v[12:15], v[26:29], v[242:245], v[12:15]
	v_mfma_f32_16x16x32_bf16 v[8:11], v[162:165], v[242:245], v[8:11]
	s_setprio 0
	s_setprio 1
	v_mfma_f32_16x16x32_bf16 v[52:55], v[166:169], v[212:215], v[52:55]
	v_mfma_f32_16x16x32_bf16 v[48:51], v[174:177], v[212:215], v[48:51]
	v_mfma_f32_16x16x32_bf16 v[36:39], v[166:169], v[220:223], v[36:39]
	v_mfma_f32_16x16x32_bf16 v[30:33], v[174:177], v[220:223], v[32:35]
	v_mfma_f32_16x16x32_bf16 v[4:7], v[166:169], v[228:231], v[4:7]
	v_mfma_f32_16x16x32_bf16 v[0:3], v[174:177], v[228:231], v[0:3]
	v_mfma_f32_16x16x32_bf16 v[22:25], v[166:169], v[182:185], v[68:71]
	v_mfma_f32_16x16x32_bf16 v[26:29], v[174:177], v[182:185], v[64:67]
	v_mfma_f32_16x16x32_bf16 v[52:55], v[170:173], v[216:219], v[52:55]
	v_mfma_f32_16x16x32_bf16 v[48:51], v[178:181], v[216:219], v[48:51]
	v_mfma_f32_16x16x32_bf16 v[36:39], v[170:173], v[224:227], v[36:39]
	v_mfma_f32_16x16x32_bf16 v[30:33], v[178:181], v[224:227], v[30:33]
	v_mfma_f32_16x16x32_bf16 v[4:7], v[170:173], v[242:245], v[4:7]
	v_mfma_f32_16x16x32_bf16 v[0:3], v[178:181], v[242:245], v[0:3]
	v_mfma_f32_16x16x32_bf16 v[22:25], v[170:173], v[186:189], v[22:25]
	v_mfma_f32_16x16x32_bf16 v[26:29], v[178:181], v[186:189], v[26:29]
	s_setprio 0
	s_barrier
; #define PG8_STAGE(bufoff, gbase, voff) do { _Pragma("unroll") for (int _i = 0; _i < 2; ++_i) \
;         __builtin_amdgcn_global_load_lds((const unsigned*)((const char*)(gbase) + (voff)[_i]), (PG8_LAS unsigned*)(lds + (bufoff) + ldsw + _i * (8 * USTR)), 16, 0, 0); } while (0)
; #define PG8_LDA(dst, b, h) do { _Pragma("unroll") for (int m = 0; m < 4; ++m) _Pragma("unroll") for (int k = 0; k < 2; ++k) dst[m][k] = *(const PG8_LAS bf16x8*)(lds + PG8_SA(b, h) + aoff + m * (2 * USTR) + k * 64); } while (0)
; #define PG8_LDB(dst, b, h) do { _Pragma("unroll") for (int n = 0; n < 2; ++n) _Pragma("unroll") for (int k = 0; k < 2; ++k) dst[n][k] = *(const PG8_LAS bf16x8*)(lds + PG8_SB(b, h) + boff + n * (2 * USTR) + k * 64); } while (0)
; #define PG8_MMA(ai, bj, At, Bt) do { __builtin_amdgcn_s_setprio(1); _Pragma("unroll") for (int m = 0; m < 4; ++m) _Pragma("unroll") for (int n = 0; n < 2; ++n) _Pragma("unroll") for (int k = 0; k < 2; ++k) \
;         acc[ai][bj][m][n] = __builtin_amdgcn_mfma_f32_16x16x32_bf16(Bt[n][k], At[m][k], acc[ai][bj][m][n], 0, 0, 0); __builtin_amdgcn_s_setprio(0); } while (0)
; #define PG8_WAIT_V(n) asm volatile("s_waitcnt vmcnt(" #n ")" ::: "memory")
; #define PG8_WAIT_L(n) asm volatile("s_waitcnt lgkmcnt(" #n ")" ::: "memory")
; #define PG8_BAR __builtin_amdgcn_s_barrier()
; #define PG8_SCHED __builtin_amdgcn_sched_barrier(0)
; template <class Epi, class Sched, bool ALIGN_EPI, bool SP2>
; __device__ __forceinline__ void gemm_phase(PG8_LAS unsigned char* lds, const Gemm g, const Sched& S, const Epi& E, int wid) {
;     ...
;             PG8_LDB(B0, 1, 0); PG8_LDB(B1, 1, 1); PG8_SCHED; PG8_LDA(At, 1, 0); PG8_STAGE(PG8_SA(0, 1), a2 + hstepA, voffA);
;             PG8_WAIT_V(8); PG8_WAIT_L(0); PG8_BAR; PG8_MMA(0, 0, At, B0); PG8_MMA(0, 1, At, B1); PG8_BAR; PG8_SCHED;
	s_add_i32 s73, 0, 0x19800
	v_add_u32_e32 v34, s73, v197
	s_add_i32 s76, 0, 0x1dc00
	ds_read_b128 v[64:67], v34
	ds_read_b128 v[68:71], v34 offset:64
	ds_read_b128 v[158:161], v34 offset:2176
	ds_read_b128 v[162:165], v34 offset:2240
	v_add_u32_e32 v34, s76, v197
	ds_read_b128 v[166:169], v34
	ds_read_b128 v[170:173], v34 offset:64
	ds_read_b128 v[174:177], v34 offset:2176
	ds_read_b128 v[178:181], v34 offset:2240
	s_add_u32 s42, s42, 0x40000
	s_addc_u32 s43, s43, 0
	s_mov_b32 m0, s56
	v_lshl_add_u64 v[34:35], s[42:43], 0, v[150:151]
	ds_read_b128 v[182:185], v210 offset:34816
	ds_read_b128 v[186:189], v210 offset:34880
	ds_read_b128 v[212:215], v210 offset:36992
	ds_read_b128 v[216:219], v210 offset:37056
	ds_read_b128 v[220:223], v210 offset:39168
	ds_read_b128 v[224:227], v210 offset:39232
	ds_read_b128 v[228:231], v210 offset:41344
	ds_read_b128 v[242:245], v210 offset:41408
	global_load_lds_dwordx4 v[34:35], off
	v_lshl_add_u64 v[34:35], s[42:43], 0, v[148:149]
	s_mov_b32 m0, s57
	s_nop 0
	global_load_lds_dwordx4 v[34:35], off
	s_waitcnt vmcnt(8)
	s_waitcnt lgkmcnt(0)
	s_barrier
	s_setprio 1
	s_waitcnt lgkmcnt(0)
	v_mfma_f32_16x16x32_bf16 v[140:143], v[64:67], v[182:185], v[140:143]
	v_mfma_f32_16x16x32_bf16 v[136:139], v[158:161], v[182:185], v[136:139]
	v_mfma_f32_16x16x32_bf16 v[124:127], v[64:67], v[212:215], v[124:127]
	v_mfma_f32_16x16x32_bf16 v[120:123], v[158:161], v[212:215], v[120:123]
	v_mfma_f32_16x16x32_bf16 v[108:111], v[64:67], v[220:223], v[108:111]
	v_mfma_f32_16x16x32_bf16 v[104:107], v[158:161], v[220:223], v[104:107]
	v_mfma_f32_16x16x32_bf16 v[92:95], v[64:67], v[228:231], v[92:95]
	v_mfma_f32_16x16x32_bf16 v[88:91], v[158:161], v[228:231], v[88:91]
	v_mfma_f32_16x16x32_bf16 v[140:143], v[68:71], v[186:189], v[140:143]
	v_mfma_f32_16x16x32_bf16 v[136:139], v[162:165], v[186:189], v[136:139]
	v_mfma_f32_16x16x32_bf16 v[124:127], v[68:71], v[216:219], v[124:127]
	v_mfma_f32_16x16x32_bf16 v[120:123], v[162:165], v[216:219], v[120:123]
	v_mfma_f32_16x16x32_bf16 v[108:111], v[68:71], v[224:227], v[108:111]
	v_mfma_f32_16x16x32_bf16 v[104:107], v[162:165], v[224:227], v[104:107]
	v_mfma_f32_16x16x32_bf16 v[92:95], v[68:71], v[242:245], v[92:95]
	v_mfma_f32_16x16x32_bf16 v[88:91], v[162:165], v[242:245], v[88:91]
	s_setprio 0
	s_setprio 1
	v_mfma_f32_16x16x32_bf16 v[132:135], v[166:169], v[182:185], v[132:135]
	v_mfma_f32_16x16x32_bf16 v[128:131], v[174:177], v[182:185], v[128:131]
	v_mfma_f32_16x16x32_bf16 v[116:119], v[166:169], v[212:215], v[116:119]
	v_mfma_f32_16x16x32_bf16 v[112:115], v[174:177], v[212:215], v[112:115]
	v_mfma_f32_16x16x32_bf16 v[100:103], v[166:169], v[220:223], v[100:103]
	v_mfma_f32_16x16x32_bf16 v[96:99], v[174:177], v[220:223], v[96:99]
	v_mfma_f32_16x16x32_bf16 v[84:87], v[166:169], v[228:231], v[84:87]
	v_mfma_f32_16x16x32_bf16 v[80:83], v[174:177], v[228:231], v[80:83]
	v_mfma_f32_16x16x32_bf16 v[132:135], v[170:173], v[186:189], v[132:135]
	v_mfma_f32_16x16x32_bf16 v[128:131], v[178:181], v[186:189], v[128:131]
	v_mfma_f32_16x16x32_bf16 v[116:119], v[170:173], v[216:219], v[116:119]
	v_mfma_f32_16x16x32_bf16 v[112:115], v[178:181], v[216:219], v[112:115]
	v_mfma_f32_16x16x32_bf16 v[100:103], v[170:173], v[224:227], v[100:103]
	v_mfma_f32_16x16x32_bf16 v[96:99], v[178:181], v[224:227], v[96:99]
	v_mfma_f32_16x16x32_bf16 v[84:87], v[170:173], v[242:245], v[84:87]
	v_mfma_f32_16x16x32_bf16 v[80:83], v[178:181], v[242:245], v[80:83]
	s_setprio 0
	s_barrier
; #define PG8_STAGE(bufoff, gbase, voff) do { _Pragma("unroll") for (int _i = 0; _i < 2; ++_i) \
;         __builtin_amdgcn_global_load_lds((const unsigned*)((const char*)(gbase) + (voff)[_i]), (PG8_LAS unsigned*)(lds + (bufoff) + ldsw + _i * (8 * USTR)), 16, 0, 0); } while (0)
; #define PG8_LDA(dst, b, h) do { _Pragma("unroll") for (int m = 0; m < 4; ++m) _Pragma("unroll") for (int k = 0; k < 2; ++k) dst[m][k] = *(const PG8_LAS bf16x8*)(lds + PG8_SA(b, h) + aoff + m * (2 * USTR) + k * 64); } while (0)
; #define PG8_MMA(ai, bj, At, Bt) do { __builtin_amdgcn_s_setprio(1); _Pragma("unroll") for (int m = 0; m < 4; ++m) _Pragma("unroll") for (int n = 0; n < 2; ++n) _Pragma("unroll") for (int k = 0; k < 2; ++k) \
;         acc[ai][bj][m][n] = __builtin_amdgcn_mfma_f32_16x16x32_bf16(Bt[n][k], At[m][k], acc[ai][bj][m][n], 0, 0, 0); __builtin_amdgcn_s_setprio(0); } while (0)
; #define PG8_WAIT_V(n) asm volatile("s_waitcnt vmcnt(" #n ")" ::: "memory")
; #define PG8_WAIT_L(n) asm volatile("s_waitcnt lgkmcnt(" #n ")" ::: "memory")
; #define PG8_BAR __builtin_amdgcn_s_barrier()
; #define PG8_SCHED __builtin_amdgcn_sched_barrier(0)
; template <class Epi, class Sched, bool ALIGN_EPI, bool SP2>
; __device__ __forceinline__ void gemm_phase(PG8_LAS unsigned char* lds, const Gemm g, const Sched& S, const Epi& E, int wid) {
;     ...
;         for (int t = 0; t < nt; t += 2) {
;             const bool last = (t == nt - 2);
;             const char* a1 = cA + (size_t)(t + 1) * kstep;
;             const char* a2 = last ? nA : cA + (size_t)(t + 2) * kstep; const char* b2 = last ? nB : cB + (size_t)(t + 2) * kstep;
;             const char* a3 = a2 + kstep; const char* b3 = b2 + kstep;
;     ...
;             PG8_LDA(At, 1, 1); PG8_STAGE(PG8_SB(1, 0), b3, voffB); PG8_STAGE(PG8_SB(1, 1), b3 + hstepB, voffB); PG8_STAGE(PG8_SA(1, 0), a3, voffA);
;             PG8_WAIT_V(8); PG8_WAIT_L(0); PG8_BAR; PG8_MMA(1, 0, At, B0); PG8_MMA(1, 1, At, B1); PG8_BAR; PG8_SCHED;
	s_add_i32 s42, s73, s33
	v_lshl_add_u64 v[34:35], v[190:191], 0, s[6:7]
	s_mov_b32 m0, s42
	ds_read_b128 v[182:185], v210 offset:52224
	ds_read_b128 v[186:189], v210 offset:52288
	ds_read_b128 v[212:215], v210 offset:54400
	ds_read_b128 v[216:219], v210 offset:54464
	ds_read_b128 v[220:223], v210 offset:56576
	ds_read_b128 v[224:227], v210 offset:56640
	ds_read_b128 v[228:231], v210 offset:58752
	ds_read_b128 v[242:245], v210 offset:58816
	global_load_lds_dwordx4 v[34:35], off
	s_add_i32 m0, s42, 0x2200
	s_add_u32 s40, s40, 0x40080
	v_lshl_add_u64 v[34:35], v[198:199], 0, s[6:7]
	s_addc_u32 s41, s41, 0
	s_add_i32 s42, s76, s33
	global_load_lds_dwordx4 v[34:35], off
	v_lshl_add_u64 v[34:35], s[40:41], 0, v[192:193]
	s_mov_b32 m0, s42
	s_nop 0
	global_load_lds_dwordx4 v[34:35], off
	v_lshl_add_u64 v[34:35], s[40:41], 0, v[146:147]
	s_add_i32 m0, s42, 0x2200
	s_nop 0
	global_load_lds_dwordx4 v[34:35], off
	v_lshl_add_u64 v[34:35], v[200:201], 0, s[6:7]
	s_mov_b32 m0, s29
	s_nop 0
	global_load_lds_dwordx4 v[34:35], off
	v_lshl_add_u64 v[34:35], v[208:209], 0, s[6:7]
	s_mov_b32 m0, s0
	s_nop 0
	global_load_lds_dwordx4 v[34:35], off
	s_add_i32 s71, s71, 2
	s_add_u32 s38, s38, 0x100
	s_addc_u32 s39, s39, 0
	s_add_u32 s23, s23, 0x100
	s_addc_u32 s70, s70, 0
	s_waitcnt vmcnt(8)
	s_waitcnt lgkmcnt(0)
	s_barrier
	s_setprio 1
	s_waitcnt lgkmcnt(0)
	v_mfma_f32_16x16x32_bf16 v[76:79], v[64:67], v[182:185], v[76:79]
	v_mfma_f32_16x16x32_bf16 v[72:75], v[158:161], v[182:185], v[72:75]
	v_mfma_f32_16x16x32_bf16 v[60:63], v[64:67], v[212:215], v[60:63]
	v_mfma_f32_16x16x32_bf16 v[56:59], v[158:161], v[212:215], v[56:59]
	v_mfma_f32_16x16x32_bf16 v[44:47], v[64:67], v[220:223], v[44:47]
	v_mfma_f32_16x16x32_bf16 v[40:43], v[158:161], v[220:223], v[40:43]
	v_mfma_f32_16x16x32_bf16 v[12:15], v[64:67], v[228:231], v[12:15]
	v_mfma_f32_16x16x32_bf16 v[8:11], v[158:161], v[228:231], v[8:11]
	v_mfma_f32_16x16x32_bf16 v[76:79], v[68:71], v[186:189], v[76:79]
	v_mfma_f32_16x16x32_bf16 v[72:75], v[162:165], v[186:189], v[72:75]
	v_mfma_f32_16x16x32_bf16 v[60:63], v[68:71], v[216:219], v[60:63]
	v_mfma_f32_16x16x32_bf16 v[56:59], v[162:165], v[216:219], v[56:59]
	v_mfma_f32_16x16x32_bf16 v[44:47], v[68:71], v[224:227], v[44:47]
	v_mfma_f32_16x16x32_bf16 v[40:43], v[162:165], v[224:227], v[40:43]
	v_mfma_f32_16x16x32_bf16 v[12:15], v[68:71], v[242:245], v[12:15]
	v_mfma_f32_16x16x32_bf16 v[8:11], v[162:165], v[242:245], v[8:11]
	s_setprio 0
	s_setprio 1
	v_mfma_f32_16x16x32_bf16 v[22:25], v[166:169], v[182:185], v[22:25]
	v_mfma_f32_16x16x32_bf16 v[68:71], v[170:173], v[186:189], v[22:25]
	v_mfma_f32_16x16x32_bf16 v[22:25], v[174:177], v[182:185], v[26:29]
	v_mfma_f32_16x16x32_bf16 v[64:67], v[178:181], v[186:189], v[22:25]
	v_mfma_f32_16x16x32_bf16 v[22:25], v[166:169], v[212:215], v[52:55]
	v_mfma_f32_16x16x32_bf16 v[52:55], v[170:173], v[216:219], v[22:25]
	v_mfma_f32_16x16x32_bf16 v[22:25], v[174:177], v[212:215], v[48:51]
	v_mfma_f32_16x16x32_bf16 v[48:51], v[178:181], v[216:219], v[22:25]
	v_mfma_f32_16x16x32_bf16 v[22:25], v[166:169], v[220:223], v[36:39]
	v_mfma_f32_16x16x32_bf16 v[36:39], v[170:173], v[224:227], v[22:25]
	v_mfma_f32_16x16x32_bf16 v[22:25], v[174:177], v[220:223], v[30:33]
	v_mfma_f32_16x16x32_bf16 v[4:7], v[166:169], v[228:231], v[4:7]
	v_mfma_f32_16x16x32_bf16 v[0:3], v[174:177], v[228:231], v[0:3]
	v_mfma_f32_16x16x32_bf16 v[32:35], v[178:181], v[224:227], v[22:25]
	v_mfma_f32_16x16x32_bf16 v[4:7], v[170:173], v[242:245], v[4:7]
	v_mfma_f32_16x16x32_bf16 v[0:3], v[178:181], v[242:245], v[0:3]
	s_setprio 0
	s_barrier
	s_cmp_gt_u32 s71, 13
	s_cbranch_scc1 .LBB0_397
